# store widening (permlane16_swap dwordx4) extended to wout/ffn2 bf16 resid stores and branch epilogue
# speedup vs baseline: 1.0321x; 1.0051x over previous
; DI u32 pack2(float a, float b) { f2_t v = {a, b}; bf2_t r = __builtin_convertvector(v, bf2_t); return __builtin_bit_cast(u32, r); }
; DI float bflo(u32 v) { return __uint_as_float(v << 16); }
; DI float bfhi(u32 v) { return __uint_as_float(v & 0xffff0000u); }
; DI float sigmoidf_(float x) { return __builtin_amdgcn_rcpf(1.f + __builtin_amdgcn_exp2f(-LOG2E * x)); }
; DI void branch_tile8(const Params& P, const WsPtrs& W, int layer, int mt, int nt, unsigned char* smem) {
;     ...
;         const int row = m0 + bj * 128 + wc * 32 + n * 16 + fr;
;         const u16* gp = W.Y + (size_t)row * LDY + O_GT + jb * 1024;
;         u16* mp = W.MERGED + (size_t)row * 1024;
; #pragma unroll
;         for (int ai = 0; ai < 2; ++ai)
; #pragma unroll
;           for (int m = 0; m < 4; ++m) {
;             const int f = n0 + ai * 128 + wr * 64 + m * 16 + fq * 4;
;             const u32x2 gv = *(const u32x2*)(gp + f);
;             const f32x4 b4 = *(const f32x4*)(gbp + f);
;             f32x4v a = acc[ai][bj][m][n];
;             float v0 = sigmoidf_(bflo(gv.x) + b4.x) * a.x, v1 = sigmoidf_(bfhi(gv.x) + b4.y) * a.y;
;             float v2 = sigmoidf_(bflo(gv.y) + b4.z) * a.z, v3 = sigmoidf_(bfhi(gv.y) + b4.w) * a.w;
;             if (jb > 0) { const u32x2 pv = *(const u32x2*)(mp + f); v0 += bflo(pv.x); v1 += bfhi(pv.x); v2 += bflo(pv.y); v3 += bfhi(pv.y); }
;             u32x2 o2; o2.x = pack2(v0, v1); o2.y = pack2(v2, v3);
;             *(u32x2*)(mp + f) = o2;
;           }
.LBB0_710:
	s_or_b64 exec, exec, s[6:7]
	v_mbcnt_lo_u32_b32 v164, -1, 0
	v_mbcnt_hi_u32_b32 v164, -1, v164
	v_bfe_u32 v164, v164, 4, 1
	v_mul_u32_u24_e32 v164, 24, v164
	v_mov_b32_e32 v165, 0
	v_mov_b32_e32 v0, v250
	s_lshl_b64 s[6:7], s[2:3], 2
	v_lshrrev_b32_e32 v131, 1, v0
	v_and_b32_e32 v130, 15, v0
	v_and_b32_e32 v131, 0x60, v131
	v_or3_b32 v134, v130, v131, s12
	v_ashrrev_i32_e32 v130, 2, v0
	s_add_u32 s6, s26, s6
	v_and_b32_e32 v130, 0xffffffc0, v130
	s_addc_u32 s7, s27, s7
	v_add_u32_e32 v130, s14, v130
	v_lshrrev_b32_e32 v0, 2, v0
	v_and_or_b32 v132, v0, 12, v130
	s_cmp_lg_u32 s84, 0
	v_mov_b64_e32 v[130:131], s[8:9]
	s_cselect_b64 s[20:21], -1, 0
	s_lshl_b32 s2, s2, 1
	v_mad_i64_i32 v[130:131], s[22:23], v134, s33, v[130:131]
	v_lshl_add_u64 v[130:131], v[130:131], 0, s[2:3]
	v_ashrrev_i32_e32 v133, 31, v132
	v_lshl_add_u64 v[136:137], v[132:133], 1, v[130:131]
	s_movk_i32 s22, 0x4000
	v_add_co_u32_e32 v130, vcc, s22, v136
	v_ashrrev_i32_e32 v135, 31, v134
	s_nop 0
	v_addc_co_u32_e32 v131, vcc, 0, v137, vcc
	global_load_dwordx2 v[142:143], v[130:131], off
	v_lshl_add_u64 v[130:131], v[132:133], 2, s[6:7]
	global_load_dwordx4 v[138:141], v[130:131], off
	s_cmp_eq_u32 s84, 0
	s_waitcnt vmcnt(0)
	v_lshlrev_b32_e32 v0, 16, v142
	v_and_b32_e32 v142, 0xffff0000, v142
	v_lshlrev_b32_e32 v144, 16, v143
	v_and_b32_e32 v143, 0xffff0000, v143
	v_add_f32_e32 v0, v138, v0
	v_add_f32_e32 v138, v139, v142
	v_add_f32_e32 v139, v140, v144
	v_add_f32_e32 v140, v141, v143
	v_mul_f32_e32 v0, 0xbfb8aa3b, v0
	v_mul_f32_e32 v138, 0xbfb8aa3b, v138
	v_mul_f32_e32 v139, 0xbfb8aa3b, v139
	v_mul_f32_e32 v140, 0xbfb8aa3b, v140
	v_exp_f32_e32 v0, v0
	v_exp_f32_e32 v138, v138
	v_exp_f32_e32 v139, v139
	v_exp_f32_e32 v140, v140
	v_add_f32_e32 v0, 1.0, v0
	v_add_f32_e32 v141, 1.0, v138
	v_add_f32_e32 v142, 1.0, v139
	v_add_f32_e32 v143, 1.0, v140
	v_rcp_f32_e32 v138, v0
	v_rcp_f32_e32 v139, v141
	v_rcp_f32_e32 v140, v142
	v_rcp_f32_e32 v141, v143
	v_lshlrev_b64 v[142:143], 11, v[134:135]
	v_lshl_add_u64 v[142:143], s[10:11], 0, v[142:143]
	v_pk_mul_f32 v[138:139], v[126:127], v[138:139]
	v_pk_mul_f32 v[140:141], v[128:129], v[140:141]
	v_lshl_add_u64 v[126:127], v[132:133], 1, v[142:143]
	s_cbranch_scc1 .LBB0_712
	global_load_dwordx2 v[128:129], v[126:127], off
	s_waitcnt vmcnt(0)
	v_lshlrev_b32_e32 v142, 16, v128
	v_and_b32_e32 v143, 0xffff0000, v128
	v_lshlrev_b32_e32 v128, 16, v129
	v_and_b32_e32 v129, 0xffff0000, v129
	v_pk_add_f32 v[138:139], v[138:139], v[142:143]
	v_pk_add_f32 v[140:141], v[140:141], v[128:129]
.LBB0_712:
	s_mov_b64 s[6:7], 0x4000
	v_lshl_add_u64 v[128:129], v[136:137], 0, s[6:7]
	v_cvt_pk_bf16_f32 v148, v138, v139
	v_cvt_pk_bf16_f32 v149, v140, v141
	global_load_dwordx2 v[142:143], v[128:129], off offset:32
	v_cndmask_b32_e64 v0, 0, 1, s[20:21]
	s_nop 0
	global_load_dwordx4 v[136:139], v[130:131], off offset:64
	v_cmp_ne_u32_e64 s[6:7], 1, v0
	s_andn2_b64 vcc, exec, s[20:21]
	s_waitcnt vmcnt(1)
	v_lshlrev_b32_e32 v135, 16, v142
	v_and_b32_e32 v140, 0xffff0000, v142
	v_lshlrev_b32_e32 v141, 16, v143
	v_and_b32_e32 v142, 0xffff0000, v143
	s_waitcnt vmcnt(0)
	v_add_f32_e32 v135, v136, v135
	v_add_f32_e32 v136, v137, v140
	v_add_f32_e32 v137, v138, v141
	v_add_f32_e32 v138, v139, v142
	v_mul_f32_e32 v135, 0xbfb8aa3b, v135
	v_mul_f32_e32 v136, 0xbfb8aa3b, v136
	v_mul_f32_e32 v137, 0xbfb8aa3b, v137
	v_mul_f32_e32 v138, 0xbfb8aa3b, v138
	v_exp_f32_e32 v135, v135
	v_exp_f32_e32 v136, v136
	v_exp_f32_e32 v137, v137
	v_exp_f32_e32 v138, v138
	v_add_f32_e32 v135, 1.0, v135
	v_add_f32_e32 v139, 1.0, v136
	v_add_f32_e32 v140, 1.0, v137
	v_add_f32_e32 v141, 1.0, v138
	v_rcp_f32_e32 v136, v135
	v_rcp_f32_e32 v137, v139
	v_rcp_f32_e32 v138, v140
	v_rcp_f32_e32 v139, v141
	v_pk_mul_f32 v[122:123], v[122:123], v[136:137]
	v_pk_mul_f32 v[124:125], v[124:125], v[138:139]
	s_cbranch_vccnz .LBB0_714
	global_load_dwordx2 v[136:137], v[126:127], off offset:32
	s_waitcnt vmcnt(0)
	v_lshlrev_b32_e32 v138, 16, v136
	v_and_b32_e32 v139, 0xffff0000, v136
	v_lshlrev_b32_e32 v136, 16, v137
	v_and_b32_e32 v137, 0xffff0000, v137
	v_pk_add_f32 v[122:123], v[122:123], v[138:139]
	v_pk_add_f32 v[124:125], v[124:125], v[136:137]
.LBB0_714:
	v_cvt_pk_bf16_f32 v150, v122, v123
	v_cvt_pk_bf16_f32 v151, v124, v125
	global_load_dwordx2 v[136:137], v[128:129], off offset:64
	s_and_b64 vcc, exec, s[6:7]
	v_lshl_add_u64 v[166:167], v[126:127], 0, v[164:165]
	s_nop 1
	v_permlane16_swap_b32_e32 v148, v150
	v_permlane16_swap_b32_e32 v149, v151
	global_store_dwordx4 v[166:167], v[148:151], off
	global_load_dwordx4 v[122:125], v[130:131], off offset:128
	s_waitcnt vmcnt(2)
	v_lshlrev_b32_e32 v0, 16, v136
	v_and_b32_e32 v135, 0xffff0000, v136
	v_lshlrev_b32_e32 v136, 16, v137
	v_and_b32_e32 v137, 0xffff0000, v137
	s_waitcnt vmcnt(0)
	v_add_f32_e32 v0, v122, v0
	v_add_f32_e32 v122, v123, v135
	v_add_f32_e32 v123, v124, v136
	v_add_f32_e32 v124, v125, v137
	v_mul_f32_e32 v0, 0xbfb8aa3b, v0
	v_mul_f32_e32 v122, 0xbfb8aa3b, v122
	v_mul_f32_e32 v123, 0xbfb8aa3b, v123
	v_mul_f32_e32 v124, 0xbfb8aa3b, v124
	v_exp_f32_e32 v0, v0
	v_exp_f32_e32 v122, v122
	v_exp_f32_e32 v123, v123
	v_exp_f32_e32 v124, v124
	v_add_f32_e32 v0, 1.0, v0
	v_add_f32_e32 v125, 1.0, v122
	v_add_f32_e32 v135, 1.0, v123
	v_add_f32_e32 v136, 1.0, v124
	v_rcp_f32_e32 v122, v0
	v_rcp_f32_e32 v123, v125
	v_rcp_f32_e32 v124, v135
	v_rcp_f32_e32 v125, v136
	v_pk_mul_f32 v[118:119], v[118:119], v[122:123]
	v_pk_mul_f32 v[120:121], v[120:121], v[124:125]
	s_cbranch_vccnz .LBB0_716
	global_load_dwordx2 v[122:123], v[126:127], off offset:64
	s_waitcnt vmcnt(0)
	v_lshlrev_b32_e32 v124, 16, v122
	v_and_b32_e32 v125, 0xffff0000, v122
	v_lshlrev_b32_e32 v122, 16, v123
	v_and_b32_e32 v123, 0xffff0000, v123
	v_pk_add_f32 v[118:119], v[118:119], v[124:125]
	v_pk_add_f32 v[120:121], v[120:121], v[122:123]
; DI u32 pack2(float a, float b) { f2_t v = {a, b}; bf2_t r = __builtin_convertvector(v, bf2_t); return __builtin_bit_cast(u32, r); }
; DI float bflo(u32 v) { return __uint_as_float(v << 16); }
; DI float bfhi(u32 v) { return __uint_as_float(v & 0xffff0000u); }
; DI float sigmoidf_(float x) { return __builtin_amdgcn_rcpf(1.f + __builtin_amdgcn_exp2f(-LOG2E * x)); }
; DI void branch_tile8(const Params& P, const WsPtrs& W, int layer, int mt, int nt, unsigned char* smem) {
;     ...
;         const int row = m0 + bj * 128 + wc * 32 + n * 16 + fr;
;         const u16* gp = W.Y + (size_t)row * LDY + O_GT + jb * 1024;
;         u16* mp = W.MERGED + (size_t)row * 1024;
; #pragma unroll
;         for (int ai = 0; ai < 2; ++ai)
; #pragma unroll
;           for (int m = 0; m < 4; ++m) {
;             const int f = n0 + ai * 128 + wr * 64 + m * 16 + fq * 4;
;             const u32x2 gv = *(const u32x2*)(gp + f);
;             const f32x4 b4 = *(const f32x4*)(gbp + f);
;             f32x4v a = acc[ai][bj][m][n];
;             float v0 = sigmoidf_(bflo(gv.x) + b4.x) * a.x, v1 = sigmoidf_(bfhi(gv.x) + b4.y) * a.y;
;             float v2 = sigmoidf_(bflo(gv.y) + b4.z) * a.z, v3 = sigmoidf_(bfhi(gv.y) + b4.w) * a.w;
;             if (jb > 0) { const u32x2 pv = *(const u32x2*)(mp + f); v0 += bflo(pv.x); v1 += bfhi(pv.x); v2 += bflo(pv.y); v3 += bfhi(pv.y); }
;             u32x2 o2; o2.x = pack2(v0, v1); o2.y = pack2(v2, v3);
;             *(u32x2*)(mp + f) = o2;
;           }
.LBB0_716:
	v_cvt_pk_bf16_f32 v152, v118, v119
	v_cvt_pk_bf16_f32 v153, v120, v121
	global_load_dwordx2 v[122:123], v[128:129], off offset:96
	s_and_b64 vcc, exec, s[6:7]
	s_nop 0
	global_load_dwordx4 v[118:121], v[130:131], off offset:192
	s_waitcnt vmcnt(1)
	v_lshlrev_b32_e32 v0, 16, v122
	v_and_b32_e32 v122, 0xffff0000, v122
	v_lshlrev_b32_e32 v124, 16, v123
	v_and_b32_e32 v123, 0xffff0000, v123
	s_waitcnt vmcnt(0)
	v_add_f32_e32 v0, v118, v0
	v_add_f32_e32 v118, v119, v122
	v_add_f32_e32 v119, v120, v124
	v_add_f32_e32 v120, v121, v123
	v_mul_f32_e32 v0, 0xbfb8aa3b, v0
	v_mul_f32_e32 v118, 0xbfb8aa3b, v118
	v_mul_f32_e32 v119, 0xbfb8aa3b, v119
	v_mul_f32_e32 v120, 0xbfb8aa3b, v120
	v_exp_f32_e32 v0, v0
	v_exp_f32_e32 v118, v118
	v_exp_f32_e32 v119, v119
	v_exp_f32_e32 v120, v120
	v_add_f32_e32 v0, 1.0, v0
	v_add_f32_e32 v121, 1.0, v118
	v_add_f32_e32 v122, 1.0, v119
	v_add_f32_e32 v123, 1.0, v120
	v_rcp_f32_e32 v118, v0
	v_rcp_f32_e32 v119, v121
	v_rcp_f32_e32 v120, v122
	v_rcp_f32_e32 v121, v123
	v_pk_mul_f32 v[114:115], v[114:115], v[118:119]
	v_pk_mul_f32 v[116:117], v[116:117], v[120:121]
	s_cbranch_vccnz .LBB0_718
	global_load_dwordx2 v[118:119], v[126:127], off offset:96
	s_waitcnt vmcnt(0)
	v_lshlrev_b32_e32 v120, 16, v118
	v_and_b32_e32 v121, 0xffff0000, v118
	v_lshlrev_b32_e32 v118, 16, v119
	v_and_b32_e32 v119, 0xffff0000, v119
	v_pk_add_f32 v[114:115], v[114:115], v[120:121]
	v_pk_add_f32 v[116:117], v[116:117], v[118:119]
.LBB0_718:
	v_cvt_pk_bf16_f32 v154, v114, v115
	v_cvt_pk_bf16_f32 v155, v116, v117
	global_load_dwordx2 v[118:119], v[128:129], off offset:256
	s_and_b64 vcc, exec, s[6:7]
	v_lshl_add_u64 v[166:167], v[126:127], 0, v[164:165]
	s_nop 1
	v_permlane16_swap_b32_e32 v152, v154
	v_permlane16_swap_b32_e32 v153, v155
	global_store_dwordx4 v[166:167], v[152:155], off offset:64
	global_load_dwordx4 v[114:117], v[130:131], off offset:512
	s_waitcnt vmcnt(2)
	v_lshlrev_b32_e32 v0, 16, v118
	v_and_b32_e32 v118, 0xffff0000, v118
	v_lshlrev_b32_e32 v120, 16, v119
	v_and_b32_e32 v119, 0xffff0000, v119
	s_waitcnt vmcnt(0)
	v_add_f32_e32 v0, v114, v0
	v_add_f32_e32 v114, v115, v118
	v_add_f32_e32 v115, v116, v120
	v_add_f32_e32 v116, v117, v119
	v_mul_f32_e32 v0, 0xbfb8aa3b, v0
	v_mul_f32_e32 v114, 0xbfb8aa3b, v114
	v_mul_f32_e32 v115, 0xbfb8aa3b, v115
	v_mul_f32_e32 v116, 0xbfb8aa3b, v116
	v_exp_f32_e32 v0, v0
	v_exp_f32_e32 v114, v114
	v_exp_f32_e32 v115, v115
	v_exp_f32_e32 v116, v116
	v_add_f32_e32 v0, 1.0, v0
	v_add_f32_e32 v117, 1.0, v114
	v_add_f32_e32 v118, 1.0, v115
	v_add_f32_e32 v119, 1.0, v116
	v_rcp_f32_e32 v114, v0
	v_rcp_f32_e32 v115, v117
	v_rcp_f32_e32 v116, v118
	v_rcp_f32_e32 v117, v119
	v_pk_mul_f32 v[110:111], v[110:111], v[114:115]
	v_pk_mul_f32 v[112:113], v[112:113], v[116:117]
	s_cbranch_vccnz .LBB0_720
	global_load_dwordx2 v[114:115], v[126:127], off offset:256
	s_waitcnt vmcnt(0)
	v_lshlrev_b32_e32 v116, 16, v114
	v_and_b32_e32 v117, 0xffff0000, v114
	v_lshlrev_b32_e32 v114, 16, v115
	v_and_b32_e32 v115, 0xffff0000, v115
	v_pk_add_f32 v[110:111], v[110:111], v[116:117]
	v_pk_add_f32 v[112:113], v[112:113], v[114:115]
.LBB0_720:
	v_cvt_pk_bf16_f32 v156, v110, v111
	v_cvt_pk_bf16_f32 v157, v112, v113
	global_load_dwordx2 v[114:115], v[128:129], off offset:288
	s_and_b64 vcc, exec, s[6:7]
	s_nop 0
	global_load_dwordx4 v[110:113], v[130:131], off offset:576
	s_waitcnt vmcnt(1)
	v_lshlrev_b32_e32 v0, 16, v114
	v_and_b32_e32 v114, 0xffff0000, v114
	v_lshlrev_b32_e32 v116, 16, v115
	v_and_b32_e32 v115, 0xffff0000, v115
	s_waitcnt vmcnt(0)
	v_add_f32_e32 v0, v110, v0
	v_add_f32_e32 v110, v111, v114
	v_add_f32_e32 v111, v112, v116
	v_add_f32_e32 v112, v113, v115
	v_mul_f32_e32 v0, 0xbfb8aa3b, v0
	v_mul_f32_e32 v110, 0xbfb8aa3b, v110
	v_mul_f32_e32 v111, 0xbfb8aa3b, v111
	v_mul_f32_e32 v112, 0xbfb8aa3b, v112
	v_exp_f32_e32 v0, v0
	v_exp_f32_e32 v110, v110
	v_exp_f32_e32 v111, v111
	v_exp_f32_e32 v112, v112
	v_add_f32_e32 v0, 1.0, v0
	v_add_f32_e32 v113, 1.0, v110
	v_add_f32_e32 v114, 1.0, v111
	v_add_f32_e32 v115, 1.0, v112
	v_rcp_f32_e32 v110, v0
	v_rcp_f32_e32 v111, v113
	v_rcp_f32_e32 v112, v114
	v_rcp_f32_e32 v113, v115
	v_pk_mul_f32 v[106:107], v[106:107], v[110:111]
	v_pk_mul_f32 v[108:109], v[108:109], v[112:113]
	s_cbranch_vccnz .LBB0_722
	global_load_dwordx2 v[110:111], v[126:127], off offset:288
	s_waitcnt vmcnt(0)
	v_lshlrev_b32_e32 v112, 16, v110
	v_and_b32_e32 v113, 0xffff0000, v110
	v_lshlrev_b32_e32 v110, 16, v111
	v_and_b32_e32 v111, 0xffff0000, v111
	v_pk_add_f32 v[106:107], v[106:107], v[112:113]
	v_pk_add_f32 v[108:109], v[108:109], v[110:111]
.LBB0_722:
	v_cvt_pk_bf16_f32 v158, v106, v107
	v_cvt_pk_bf16_f32 v159, v108, v109
	global_load_dwordx2 v[110:111], v[128:129], off offset:320
	s_and_b64 vcc, exec, s[6:7]
	v_lshl_add_u64 v[166:167], v[126:127], 0, v[164:165]
	s_nop 1
	v_permlane16_swap_b32_e32 v156, v158
	v_permlane16_swap_b32_e32 v157, v159
	global_store_dwordx4 v[166:167], v[156:159], off offset:256
	global_load_dwordx4 v[106:109], v[130:131], off offset:640
	s_waitcnt vmcnt(2)
	v_lshlrev_b32_e32 v0, 16, v110
	v_and_b32_e32 v110, 0xffff0000, v110
	v_lshlrev_b32_e32 v112, 16, v111
	v_and_b32_e32 v111, 0xffff0000, v111
	s_waitcnt vmcnt(0)
	v_add_f32_e32 v0, v106, v0
	v_add_f32_e32 v106, v107, v110
	v_add_f32_e32 v107, v108, v112
	v_add_f32_e32 v108, v109, v111
	v_mul_f32_e32 v0, 0xbfb8aa3b, v0
	v_mul_f32_e32 v106, 0xbfb8aa3b, v106
	v_mul_f32_e32 v107, 0xbfb8aa3b, v107
	v_mul_f32_e32 v108, 0xbfb8aa3b, v108
	v_exp_f32_e32 v0, v0
	v_exp_f32_e32 v106, v106
	v_exp_f32_e32 v107, v107
	v_exp_f32_e32 v108, v108
	v_add_f32_e32 v0, 1.0, v0
	v_add_f32_e32 v109, 1.0, v106
	v_add_f32_e32 v110, 1.0, v107
	v_add_f32_e32 v111, 1.0, v108
	v_rcp_f32_e32 v106, v0
	v_rcp_f32_e32 v107, v109
	v_rcp_f32_e32 v108, v110
	v_rcp_f32_e32 v109, v111
	v_pk_mul_f32 v[102:103], v[102:103], v[106:107]
	v_pk_mul_f32 v[104:105], v[104:105], v[108:109]
	s_cbranch_vccnz .LBB0_724
	global_load_dwordx2 v[106:107], v[126:127], off offset:320
	s_waitcnt vmcnt(0)
	v_lshlrev_b32_e32 v108, 16, v106
	v_and_b32_e32 v109, 0xffff0000, v106
	v_lshlrev_b32_e32 v106, 16, v107
	v_and_b32_e32 v107, 0xffff0000, v107
	v_pk_add_f32 v[102:103], v[102:103], v[108:109]
	v_pk_add_f32 v[104:105], v[104:105], v[106:107]
; DI u32 pack2(float a, float b) { f2_t v = {a, b}; bf2_t r = __builtin_convertvector(v, bf2_t); return __builtin_bit_cast(u32, r); }
; DI float bflo(u32 v) { return __uint_as_float(v << 16); }
; DI float bfhi(u32 v) { return __uint_as_float(v & 0xffff0000u); }
; DI float sigmoidf_(float x) { return __builtin_amdgcn_rcpf(1.f + __builtin_amdgcn_exp2f(-LOG2E * x)); }
; DI void branch_tile8(const Params& P, const WsPtrs& W, int layer, int mt, int nt, unsigned char* smem) {
;     ...
;         const int row = m0 + bj * 128 + wc * 32 + n * 16 + fr;
;         const u16* gp = W.Y + (size_t)row * LDY + O_GT + jb * 1024;
;         u16* mp = W.MERGED + (size_t)row * 1024;
; #pragma unroll
;         for (int ai = 0; ai < 2; ++ai)
; #pragma unroll
;           for (int m = 0; m < 4; ++m) {
;             const int f = n0 + ai * 128 + wr * 64 + m * 16 + fq * 4;
;             const u32x2 gv = *(const u32x2*)(gp + f);
;             const f32x4 b4 = *(const f32x4*)(gbp + f);
;             f32x4v a = acc[ai][bj][m][n];
;             float v0 = sigmoidf_(bflo(gv.x) + b4.x) * a.x, v1 = sigmoidf_(bfhi(gv.x) + b4.y) * a.y;
;             float v2 = sigmoidf_(bflo(gv.y) + b4.z) * a.z, v3 = sigmoidf_(bfhi(gv.y) + b4.w) * a.w;
;             if (jb > 0) { const u32x2 pv = *(const u32x2*)(mp + f); v0 += bflo(pv.x); v1 += bfhi(pv.x); v2 += bflo(pv.y); v3 += bfhi(pv.y); }
;             u32x2 o2; o2.x = pack2(v0, v1); o2.y = pack2(v2, v3);
;             *(u32x2*)(mp + f) = o2;
;           }
.LBB0_724:
	v_cvt_pk_bf16_f32 v160, v102, v103
	v_cvt_pk_bf16_f32 v161, v104, v105
	global_load_dwordx2 v[106:107], v[128:129], off offset:352
	s_and_b64 vcc, exec, s[6:7]
	s_nop 0
	global_load_dwordx4 v[102:105], v[130:131], off offset:704
	s_waitcnt vmcnt(1)
	v_lshlrev_b32_e32 v0, 16, v106
	v_and_b32_e32 v106, 0xffff0000, v106
	v_lshlrev_b32_e32 v108, 16, v107
	v_and_b32_e32 v107, 0xffff0000, v107
	s_waitcnt vmcnt(0)
	v_add_f32_e32 v0, v102, v0
	v_add_f32_e32 v102, v103, v106
	v_add_f32_e32 v103, v104, v108
	v_add_f32_e32 v104, v105, v107
	v_mul_f32_e32 v0, 0xbfb8aa3b, v0
	v_mul_f32_e32 v102, 0xbfb8aa3b, v102
	v_mul_f32_e32 v103, 0xbfb8aa3b, v103
	v_mul_f32_e32 v104, 0xbfb8aa3b, v104
	v_exp_f32_e32 v0, v0
	v_exp_f32_e32 v102, v102
	v_exp_f32_e32 v103, v103
	v_exp_f32_e32 v104, v104
	v_add_f32_e32 v0, 1.0, v0
	v_add_f32_e32 v105, 1.0, v102
	v_add_f32_e32 v106, 1.0, v103
	v_add_f32_e32 v107, 1.0, v104
	v_rcp_f32_e32 v102, v0
	v_rcp_f32_e32 v103, v105
	v_rcp_f32_e32 v104, v106
	v_rcp_f32_e32 v105, v107
	v_pk_mul_f32 v[98:99], v[98:99], v[102:103]
	v_pk_mul_f32 v[100:101], v[100:101], v[104:105]
	s_cbranch_vccnz .LBB0_726
	global_load_dwordx2 v[102:103], v[126:127], off offset:352
	s_waitcnt vmcnt(0)
	v_lshlrev_b32_e32 v104, 16, v102
	v_and_b32_e32 v105, 0xffff0000, v102
	v_lshlrev_b32_e32 v102, 16, v103
	v_and_b32_e32 v103, 0xffff0000, v103
	v_pk_add_f32 v[98:99], v[98:99], v[104:105]
	v_pk_add_f32 v[100:101], v[100:101], v[102:103]
.LBB0_726:
	v_cvt_pk_bf16_f32 v162, v98, v99
	v_cvt_pk_bf16_f32 v163, v100, v101
	v_lshl_add_u64 v[166:167], v[126:127], 0, v[164:165]
	s_nop 1
	v_permlane16_swap_b32_e32 v160, v162
	v_permlane16_swap_b32_e32 v161, v163
	global_store_dwordx4 v[166:167], v[160:163], off offset:320
	v_or_b32_e32 v98, 16, v134
	v_mov_b64_e32 v[100:101], s[8:9]
	v_ashrrev_i32_e32 v99, 31, v98
	v_mad_i64_i32 v[100:101], s[20:21], v98, s33, v[100:101]
	v_lshl_add_u64 v[100:101], v[100:101], 0, s[2:3]
	v_lshlrev_b64 v[98:99], 11, v[98:99]
	v_lshl_add_u64 v[104:105], s[10:11], 0, v[98:99]
	v_lshl_add_u64 v[98:99], v[132:133], 1, v[100:101]
	s_movk_i32 s20, 0x4000
	v_add_co_u32_e32 v100, vcc, s20, v98
	s_nop 1
	v_addc_co_u32_e32 v101, vcc, 0, v99, vcc
	global_load_dwordx2 v[106:107], v[100:101], off
	s_nop 0
	global_load_dwordx4 v[100:103], v[130:131], off
	s_and_b64 vcc, exec, s[6:7]
	s_waitcnt vmcnt(0)
	v_lshlrev_b32_e32 v0, 16, v106
	s_waitcnt vmcnt(0)
	v_add_f32_e32 v0, v100, v0
	v_mul_f32_e32 v0, 0xbfb8aa3b, v0
	v_exp_f32_e32 v0, v0
	s_nop 0
	v_add_f32_e32 v0, 1.0, v0
	v_rcp_f32_e32 v100, v0
	v_and_b32_e32 v0, 0xffff0000, v106
	v_add_f32_e32 v0, v101, v0
	v_mul_f32_e32 v0, 0xbfb8aa3b, v0
	v_exp_f32_e32 v0, v0
	s_nop 0
	v_add_f32_e32 v0, 1.0, v0
	v_rcp_f32_e32 v101, v0
	v_lshlrev_b32_e32 v0, 16, v107
	v_add_f32_e32 v0, v102, v0
	v_mul_f32_e32 v0, 0xbfb8aa3b, v0
	v_exp_f32_e32 v0, v0
	v_pk_mul_f32 v[100:101], v[94:95], v[100:101]
	v_add_f32_e32 v0, 1.0, v0
	v_rcp_f32_e32 v94, v0
	v_and_b32_e32 v0, 0xffff0000, v107
	v_add_f32_e32 v0, v103, v0
	v_mul_f32_e32 v0, 0xbfb8aa3b, v0
	v_exp_f32_e32 v0, v0
	s_nop 0
	v_add_f32_e32 v0, 1.0, v0
	v_rcp_f32_e32 v95, v0
	s_nop 0
	v_pk_mul_f32 v[102:103], v[96:97], v[94:95]
	v_lshl_add_u64 v[94:95], v[132:133], 1, v[104:105]
	s_cbranch_vccnz .LBB0_728
	global_load_dwordx2 v[96:97], v[94:95], off
	s_waitcnt vmcnt(0)
	v_lshlrev_b32_e32 v104, 16, v96
	v_and_b32_e32 v105, 0xffff0000, v96
	v_lshlrev_b32_e32 v96, 16, v97
	v_and_b32_e32 v97, 0xffff0000, v97
	v_pk_add_f32 v[100:101], v[100:101], v[104:105]
	v_pk_add_f32 v[102:103], v[102:103], v[96:97]
.LBB0_728:
	s_mov_b64 s[20:21], 0x4000
	v_lshl_add_u64 v[96:97], v[98:99], 0, s[20:21]
	v_cvt_pk_bf16_f32 v148, v100, v101
	v_cvt_pk_bf16_f32 v149, v102, v103
	global_load_dwordx2 v[104:105], v[96:97], off offset:32
	s_and_b64 vcc, exec, s[6:7]
	s_nop 0
	global_load_dwordx4 v[98:101], v[130:131], off offset:64
	s_waitcnt vmcnt(1)
	v_lshlrev_b32_e32 v0, 16, v104
	v_and_b32_e32 v102, 0xffff0000, v104
	v_lshlrev_b32_e32 v103, 16, v105
	v_and_b32_e32 v104, 0xffff0000, v105
	s_waitcnt vmcnt(0)
	v_add_f32_e32 v0, v98, v0
	v_add_f32_e32 v98, v99, v102
	v_add_f32_e32 v99, v100, v103
	v_add_f32_e32 v100, v101, v104
	v_mul_f32_e32 v0, 0xbfb8aa3b, v0
	v_mul_f32_e32 v98, 0xbfb8aa3b, v98
	v_mul_f32_e32 v99, 0xbfb8aa3b, v99
	v_mul_f32_e32 v100, 0xbfb8aa3b, v100
	v_exp_f32_e32 v0, v0
	v_exp_f32_e32 v98, v98
	v_exp_f32_e32 v99, v99
	v_exp_f32_e32 v100, v100
	v_add_f32_e32 v0, 1.0, v0
	v_add_f32_e32 v101, 1.0, v98
	v_add_f32_e32 v102, 1.0, v99
	v_add_f32_e32 v103, 1.0, v100
	v_rcp_f32_e32 v98, v0
	v_rcp_f32_e32 v99, v101
	v_rcp_f32_e32 v100, v102
	v_rcp_f32_e32 v101, v103
	v_pk_mul_f32 v[90:91], v[90:91], v[98:99]
	v_pk_mul_f32 v[92:93], v[92:93], v[100:101]
	s_cbranch_vccnz .LBB0_730
	global_load_dwordx2 v[98:99], v[94:95], off offset:32
	s_waitcnt vmcnt(0)
	v_lshlrev_b32_e32 v100, 16, v98
	v_and_b32_e32 v101, 0xffff0000, v98
	v_lshlrev_b32_e32 v98, 16, v99
	v_and_b32_e32 v99, 0xffff0000, v99
	v_pk_add_f32 v[90:91], v[90:91], v[100:101]
	v_pk_add_f32 v[92:93], v[92:93], v[98:99]
; DI u32 pack2(float a, float b) { f2_t v = {a, b}; bf2_t r = __builtin_convertvector(v, bf2_t); return __builtin_bit_cast(u32, r); }
; DI float bflo(u32 v) { return __uint_as_float(v << 16); }
; DI float bfhi(u32 v) { return __uint_as_float(v & 0xffff0000u); }
; DI float sigmoidf_(float x) { return __builtin_amdgcn_rcpf(1.f + __builtin_amdgcn_exp2f(-LOG2E * x)); }
; DI void branch_tile8(const Params& P, const WsPtrs& W, int layer, int mt, int nt, unsigned char* smem) {
;     ...
;         const int row = m0 + bj * 128 + wc * 32 + n * 16 + fr;
;         const u16* gp = W.Y + (size_t)row * LDY + O_GT + jb * 1024;
;         u16* mp = W.MERGED + (size_t)row * 1024;
; #pragma unroll
;         for (int ai = 0; ai < 2; ++ai)
; #pragma unroll
;           for (int m = 0; m < 4; ++m) {
;             const int f = n0 + ai * 128 + wr * 64 + m * 16 + fq * 4;
;             const u32x2 gv = *(const u32x2*)(gp + f);
;             const f32x4 b4 = *(const f32x4*)(gbp + f);
;             f32x4v a = acc[ai][bj][m][n];
;             float v0 = sigmoidf_(bflo(gv.x) + b4.x) * a.x, v1 = sigmoidf_(bfhi(gv.x) + b4.y) * a.y;
;             float v2 = sigmoidf_(bflo(gv.y) + b4.z) * a.z, v3 = sigmoidf_(bfhi(gv.y) + b4.w) * a.w;
;             if (jb > 0) { const u32x2 pv = *(const u32x2*)(mp + f); v0 += bflo(pv.x); v1 += bfhi(pv.x); v2 += bflo(pv.y); v3 += bfhi(pv.y); }
;             u32x2 o2; o2.x = pack2(v0, v1); o2.y = pack2(v2, v3);
;             *(u32x2*)(mp + f) = o2;
;           }
.LBB0_730:
	v_cvt_pk_bf16_f32 v150, v90, v91
	v_cvt_pk_bf16_f32 v151, v92, v93
	global_load_dwordx2 v[98:99], v[96:97], off offset:64
	s_and_b64 vcc, exec, s[6:7]
	v_lshl_add_u64 v[166:167], v[94:95], 0, v[164:165]
	s_nop 1
	v_permlane16_swap_b32_e32 v148, v150
	v_permlane16_swap_b32_e32 v149, v151
	global_store_dwordx4 v[166:167], v[148:151], off
	global_load_dwordx4 v[90:93], v[130:131], off offset:128
	s_waitcnt vmcnt(2)
	v_lshlrev_b32_e32 v0, 16, v98
	v_and_b32_e32 v98, 0xffff0000, v98
	v_lshlrev_b32_e32 v100, 16, v99
	v_and_b32_e32 v99, 0xffff0000, v99
	s_waitcnt vmcnt(0)
	v_add_f32_e32 v0, v90, v0
	v_add_f32_e32 v90, v91, v98
	v_add_f32_e32 v91, v92, v100
	v_add_f32_e32 v92, v93, v99
	v_mul_f32_e32 v0, 0xbfb8aa3b, v0
	v_mul_f32_e32 v90, 0xbfb8aa3b, v90
	v_mul_f32_e32 v91, 0xbfb8aa3b, v91
	v_mul_f32_e32 v92, 0xbfb8aa3b, v92
	v_exp_f32_e32 v0, v0
	v_exp_f32_e32 v90, v90
	v_exp_f32_e32 v91, v91
	v_exp_f32_e32 v92, v92
	v_add_f32_e32 v0, 1.0, v0
	v_add_f32_e32 v93, 1.0, v90
	v_add_f32_e32 v98, 1.0, v91
	v_add_f32_e32 v99, 1.0, v92
	v_rcp_f32_e32 v90, v0
	v_rcp_f32_e32 v91, v93
	v_rcp_f32_e32 v92, v98
	v_rcp_f32_e32 v93, v99
	v_pk_mul_f32 v[86:87], v[86:87], v[90:91]
	v_pk_mul_f32 v[88:89], v[88:89], v[92:93]
	s_cbranch_vccnz .LBB0_732
	global_load_dwordx2 v[90:91], v[94:95], off offset:64
	s_waitcnt vmcnt(0)
	v_lshlrev_b32_e32 v92, 16, v90
	v_and_b32_e32 v93, 0xffff0000, v90
	v_lshlrev_b32_e32 v90, 16, v91
	v_and_b32_e32 v91, 0xffff0000, v91
	v_pk_add_f32 v[86:87], v[86:87], v[92:93]
	v_pk_add_f32 v[88:89], v[88:89], v[90:91]
.LBB0_732:
	v_cvt_pk_bf16_f32 v152, v86, v87
	v_cvt_pk_bf16_f32 v153, v88, v89
	global_load_dwordx2 v[90:91], v[96:97], off offset:96
	s_and_b64 vcc, exec, s[6:7]
	s_nop 0
	global_load_dwordx4 v[86:89], v[130:131], off offset:192
	s_waitcnt vmcnt(1)
	v_lshlrev_b32_e32 v0, 16, v90
	v_and_b32_e32 v90, 0xffff0000, v90
	v_lshlrev_b32_e32 v92, 16, v91
	v_and_b32_e32 v91, 0xffff0000, v91
	s_waitcnt vmcnt(0)
	v_add_f32_e32 v0, v86, v0
	v_add_f32_e32 v86, v87, v90
	v_add_f32_e32 v87, v88, v92
	v_add_f32_e32 v88, v89, v91
	v_mul_f32_e32 v0, 0xbfb8aa3b, v0
	v_mul_f32_e32 v86, 0xbfb8aa3b, v86
	v_mul_f32_e32 v87, 0xbfb8aa3b, v87
	v_mul_f32_e32 v88, 0xbfb8aa3b, v88
	v_exp_f32_e32 v0, v0
	v_exp_f32_e32 v86, v86
	v_exp_f32_e32 v87, v87
	v_exp_f32_e32 v88, v88
	v_add_f32_e32 v0, 1.0, v0
	v_add_f32_e32 v89, 1.0, v86
	v_add_f32_e32 v90, 1.0, v87
	v_add_f32_e32 v91, 1.0, v88
	v_rcp_f32_e32 v86, v0
	v_rcp_f32_e32 v87, v89
	v_rcp_f32_e32 v88, v90
	v_rcp_f32_e32 v89, v91
	v_pk_mul_f32 v[82:83], v[82:83], v[86:87]
	v_pk_mul_f32 v[84:85], v[84:85], v[88:89]
	s_cbranch_vccnz .LBB0_734
	global_load_dwordx2 v[86:87], v[94:95], off offset:96
	s_waitcnt vmcnt(0)
	v_lshlrev_b32_e32 v88, 16, v86
	v_and_b32_e32 v89, 0xffff0000, v86
	v_lshlrev_b32_e32 v86, 16, v87
	v_and_b32_e32 v87, 0xffff0000, v87
	v_pk_add_f32 v[82:83], v[82:83], v[88:89]
	v_pk_add_f32 v[84:85], v[84:85], v[86:87]
.LBB0_734:
	v_cvt_pk_bf16_f32 v154, v82, v83
	v_cvt_pk_bf16_f32 v155, v84, v85
	global_load_dwordx2 v[86:87], v[96:97], off offset:256
	s_and_b64 vcc, exec, s[6:7]
	v_lshl_add_u64 v[166:167], v[94:95], 0, v[164:165]
	s_nop 1
	v_permlane16_swap_b32_e32 v152, v154
	v_permlane16_swap_b32_e32 v153, v155
	global_store_dwordx4 v[166:167], v[152:155], off offset:64
	global_load_dwordx4 v[82:85], v[130:131], off offset:512
	s_waitcnt vmcnt(2)
	v_lshlrev_b32_e32 v0, 16, v86
	v_and_b32_e32 v86, 0xffff0000, v86
	v_lshlrev_b32_e32 v88, 16, v87
	v_and_b32_e32 v87, 0xffff0000, v87
	s_waitcnt vmcnt(0)
	v_add_f32_e32 v0, v82, v0
	v_add_f32_e32 v82, v83, v86
	v_add_f32_e32 v83, v84, v88
	v_add_f32_e32 v84, v85, v87
	v_mul_f32_e32 v0, 0xbfb8aa3b, v0
	v_mul_f32_e32 v82, 0xbfb8aa3b, v82
	v_mul_f32_e32 v83, 0xbfb8aa3b, v83
	v_mul_f32_e32 v84, 0xbfb8aa3b, v84
	v_exp_f32_e32 v0, v0
	v_exp_f32_e32 v82, v82
	v_exp_f32_e32 v83, v83
	v_exp_f32_e32 v84, v84
	v_add_f32_e32 v0, 1.0, v0
	v_add_f32_e32 v85, 1.0, v82
	v_add_f32_e32 v86, 1.0, v83
	v_add_f32_e32 v87, 1.0, v84
	v_rcp_f32_e32 v82, v0
	v_rcp_f32_e32 v83, v85
	v_rcp_f32_e32 v84, v86
	v_rcp_f32_e32 v85, v87
	v_pk_mul_f32 v[78:79], v[78:79], v[82:83]
	v_pk_mul_f32 v[80:81], v[80:81], v[84:85]
	s_cbranch_vccnz .LBB0_736
	global_load_dwordx2 v[82:83], v[94:95], off offset:256
	s_waitcnt vmcnt(0)
	v_lshlrev_b32_e32 v84, 16, v82
	v_and_b32_e32 v85, 0xffff0000, v82
	v_lshlrev_b32_e32 v82, 16, v83
	v_and_b32_e32 v83, 0xffff0000, v83
	v_pk_add_f32 v[78:79], v[78:79], v[84:85]
	v_pk_add_f32 v[80:81], v[80:81], v[82:83]
.LBB0_736:
	v_cvt_pk_bf16_f32 v156, v78, v79
	v_cvt_pk_bf16_f32 v157, v80, v81
	global_load_dwordx2 v[82:83], v[96:97], off offset:288
	s_and_b64 vcc, exec, s[6:7]
	s_nop 0
	global_load_dwordx4 v[78:81], v[130:131], off offset:576
	s_waitcnt vmcnt(1)
	v_lshlrev_b32_e32 v0, 16, v82
	v_and_b32_e32 v82, 0xffff0000, v82
	v_lshlrev_b32_e32 v84, 16, v83
	v_and_b32_e32 v83, 0xffff0000, v83
	s_waitcnt vmcnt(0)
	v_add_f32_e32 v0, v78, v0
	v_add_f32_e32 v78, v79, v82
	v_add_f32_e32 v79, v80, v84
	v_add_f32_e32 v80, v81, v83
	v_mul_f32_e32 v0, 0xbfb8aa3b, v0
	v_mul_f32_e32 v78, 0xbfb8aa3b, v78
	v_mul_f32_e32 v79, 0xbfb8aa3b, v79
	v_mul_f32_e32 v80, 0xbfb8aa3b, v80
	v_exp_f32_e32 v0, v0
	v_exp_f32_e32 v78, v78
	v_exp_f32_e32 v79, v79
	v_exp_f32_e32 v80, v80
	v_add_f32_e32 v0, 1.0, v0
	v_add_f32_e32 v81, 1.0, v78
	v_add_f32_e32 v82, 1.0, v79
	v_add_f32_e32 v83, 1.0, v80
	v_rcp_f32_e32 v78, v0
	v_rcp_f32_e32 v79, v81
	v_rcp_f32_e32 v80, v82
	v_rcp_f32_e32 v81, v83
	v_pk_mul_f32 v[74:75], v[74:75], v[78:79]
	v_pk_mul_f32 v[76:77], v[76:77], v[80:81]
	s_cbranch_vccnz .LBB0_738
	global_load_dwordx2 v[78:79], v[94:95], off offset:288
	s_waitcnt vmcnt(0)
	v_lshlrev_b32_e32 v80, 16, v78
	v_and_b32_e32 v81, 0xffff0000, v78
	v_lshlrev_b32_e32 v78, 16, v79
	v_and_b32_e32 v79, 0xffff0000, v79
	v_pk_add_f32 v[74:75], v[74:75], v[80:81]
	v_pk_add_f32 v[76:77], v[76:77], v[78:79]
; DI u32 pack2(float a, float b) { f2_t v = {a, b}; bf2_t r = __builtin_convertvector(v, bf2_t); return __builtin_bit_cast(u32, r); }
; DI float bflo(u32 v) { return __uint_as_float(v << 16); }
; DI float bfhi(u32 v) { return __uint_as_float(v & 0xffff0000u); }
; DI float sigmoidf_(float x) { return __builtin_amdgcn_rcpf(1.f + __builtin_amdgcn_exp2f(-LOG2E * x)); }
; DI void branch_tile8(const Params& P, const WsPtrs& W, int layer, int mt, int nt, unsigned char* smem) {
;     ...
;         const int row = m0 + bj * 128 + wc * 32 + n * 16 + fr;
;         const u16* gp = W.Y + (size_t)row * LDY + O_GT + jb * 1024;
;         u16* mp = W.MERGED + (size_t)row * 1024;
; #pragma unroll
;         for (int ai = 0; ai < 2; ++ai)
; #pragma unroll
;           for (int m = 0; m < 4; ++m) {
;             const int f = n0 + ai * 128 + wr * 64 + m * 16 + fq * 4;
;             const u32x2 gv = *(const u32x2*)(gp + f);
;             const f32x4 b4 = *(const f32x4*)(gbp + f);
;             f32x4v a = acc[ai][bj][m][n];
;             float v0 = sigmoidf_(bflo(gv.x) + b4.x) * a.x, v1 = sigmoidf_(bfhi(gv.x) + b4.y) * a.y;
;             float v2 = sigmoidf_(bflo(gv.y) + b4.z) * a.z, v3 = sigmoidf_(bfhi(gv.y) + b4.w) * a.w;
;             if (jb > 0) { const u32x2 pv = *(const u32x2*)(mp + f); v0 += bflo(pv.x); v1 += bfhi(pv.x); v2 += bflo(pv.y); v3 += bfhi(pv.y); }
;             u32x2 o2; o2.x = pack2(v0, v1); o2.y = pack2(v2, v3);
;             *(u32x2*)(mp + f) = o2;
;           }
.LBB0_738:
	v_cvt_pk_bf16_f32 v158, v74, v75
	v_cvt_pk_bf16_f32 v159, v76, v77
	global_load_dwordx2 v[78:79], v[96:97], off offset:320
	s_and_b64 vcc, exec, s[6:7]
	v_lshl_add_u64 v[166:167], v[94:95], 0, v[164:165]
	s_nop 1
	v_permlane16_swap_b32_e32 v156, v158
	v_permlane16_swap_b32_e32 v157, v159
	global_store_dwordx4 v[166:167], v[156:159], off offset:256
	global_load_dwordx4 v[74:77], v[130:131], off offset:640
	s_waitcnt vmcnt(2)
	v_lshlrev_b32_e32 v0, 16, v78
	v_and_b32_e32 v78, 0xffff0000, v78
	v_lshlrev_b32_e32 v80, 16, v79
	v_and_b32_e32 v79, 0xffff0000, v79
	s_waitcnt vmcnt(0)
	v_add_f32_e32 v0, v74, v0
	v_add_f32_e32 v74, v75, v78
	v_add_f32_e32 v75, v76, v80
	v_add_f32_e32 v76, v77, v79
	v_mul_f32_e32 v0, 0xbfb8aa3b, v0
	v_mul_f32_e32 v74, 0xbfb8aa3b, v74
	v_mul_f32_e32 v75, 0xbfb8aa3b, v75
	v_mul_f32_e32 v76, 0xbfb8aa3b, v76
	v_exp_f32_e32 v0, v0
	v_exp_f32_e32 v74, v74
	v_exp_f32_e32 v75, v75
	v_exp_f32_e32 v76, v76
	v_add_f32_e32 v0, 1.0, v0
	v_add_f32_e32 v77, 1.0, v74
	v_add_f32_e32 v78, 1.0, v75
	v_add_f32_e32 v79, 1.0, v76
	v_rcp_f32_e32 v74, v0
	v_rcp_f32_e32 v75, v77
	v_rcp_f32_e32 v76, v78
	v_rcp_f32_e32 v77, v79
	v_pk_mul_f32 v[70:71], v[70:71], v[74:75]
	v_pk_mul_f32 v[72:73], v[72:73], v[76:77]
	s_cbranch_vccnz .LBB0_740
	global_load_dwordx2 v[74:75], v[94:95], off offset:320
	s_waitcnt vmcnt(0)
	v_lshlrev_b32_e32 v76, 16, v74
	v_and_b32_e32 v77, 0xffff0000, v74
	v_lshlrev_b32_e32 v74, 16, v75
	v_and_b32_e32 v75, 0xffff0000, v75
	v_pk_add_f32 v[70:71], v[70:71], v[76:77]
	v_pk_add_f32 v[72:73], v[72:73], v[74:75]
.LBB0_740:
	v_cvt_pk_bf16_f32 v160, v70, v71
	v_cvt_pk_bf16_f32 v161, v72, v73
	global_load_dwordx2 v[74:75], v[96:97], off offset:352
	s_and_b64 vcc, exec, s[6:7]
	s_nop 0
	global_load_dwordx4 v[70:73], v[130:131], off offset:704
	s_waitcnt vmcnt(1)
	v_lshlrev_b32_e32 v0, 16, v74
	v_and_b32_e32 v74, 0xffff0000, v74
	v_lshlrev_b32_e32 v76, 16, v75
	v_and_b32_e32 v75, 0xffff0000, v75
	s_waitcnt vmcnt(0)
	v_add_f32_e32 v0, v70, v0
	v_add_f32_e32 v70, v71, v74
	v_add_f32_e32 v71, v72, v76
	v_add_f32_e32 v72, v73, v75
	v_mul_f32_e32 v0, 0xbfb8aa3b, v0
	v_mul_f32_e32 v70, 0xbfb8aa3b, v70
	v_mul_f32_e32 v71, 0xbfb8aa3b, v71
	v_mul_f32_e32 v72, 0xbfb8aa3b, v72
	v_exp_f32_e32 v0, v0
	v_exp_f32_e32 v70, v70
	v_exp_f32_e32 v71, v71
	v_exp_f32_e32 v72, v72
	v_add_f32_e32 v0, 1.0, v0
	v_add_f32_e32 v73, 1.0, v70
	v_add_f32_e32 v74, 1.0, v71
	v_add_f32_e32 v75, 1.0, v72
	v_rcp_f32_e32 v70, v0
	v_rcp_f32_e32 v71, v73
	v_rcp_f32_e32 v72, v74
	v_rcp_f32_e32 v73, v75
	v_pk_mul_f32 v[66:67], v[66:67], v[70:71]
	v_pk_mul_f32 v[68:69], v[68:69], v[72:73]
	s_cbranch_vccnz .LBB0_742
	global_load_dwordx2 v[70:71], v[94:95], off offset:352
	s_waitcnt vmcnt(0)
	v_lshlrev_b32_e32 v72, 16, v70
	v_and_b32_e32 v73, 0xffff0000, v70
	v_lshlrev_b32_e32 v70, 16, v71
	v_and_b32_e32 v71, 0xffff0000, v71
	v_pk_add_f32 v[66:67], v[66:67], v[72:73]
	v_pk_add_f32 v[68:69], v[68:69], v[70:71]
.LBB0_742:
	v_cvt_pk_bf16_f32 v162, v66, v67
	v_cvt_pk_bf16_f32 v163, v68, v69
	v_lshl_add_u64 v[166:167], v[94:95], 0, v[164:165]
	s_nop 1
	v_permlane16_swap_b32_e32 v160, v162
	v_permlane16_swap_b32_e32 v161, v163
	global_store_dwordx4 v[166:167], v[160:163], off offset:320
	v_or_b32_e32 v66, 0x80, v134
	v_mov_b64_e32 v[68:69], s[8:9]
	v_ashrrev_i32_e32 v67, 31, v66
	v_mad_i64_i32 v[68:69], s[20:21], v66, s33, v[68:69]
	v_lshl_add_u64 v[68:69], v[68:69], 0, s[2:3]
	v_lshlrev_b64 v[66:67], 11, v[66:67]
	v_lshl_add_u64 v[72:73], s[10:11], 0, v[66:67]
	v_lshl_add_u64 v[66:67], v[132:133], 1, v[68:69]
	s_movk_i32 s20, 0x4000
	v_add_co_u32_e32 v68, vcc, s20, v66
	s_nop 1
	v_addc_co_u32_e32 v69, vcc, 0, v67, vcc
	global_load_dwordx2 v[74:75], v[68:69], off
	s_nop 0
	global_load_dwordx4 v[68:71], v[130:131], off
	s_and_b64 vcc, exec, s[6:7]
	s_waitcnt vmcnt(0)
	v_lshlrev_b32_e32 v0, 16, v74
	s_waitcnt vmcnt(0)
	v_add_f32_e32 v0, v68, v0
	v_mul_f32_e32 v0, 0xbfb8aa3b, v0
	v_exp_f32_e32 v0, v0
	s_nop 0
	v_add_f32_e32 v0, 1.0, v0
	v_rcp_f32_e32 v68, v0
	v_and_b32_e32 v0, 0xffff0000, v74
	v_add_f32_e32 v0, v69, v0
	v_mul_f32_e32 v0, 0xbfb8aa3b, v0
	v_exp_f32_e32 v0, v0
	s_nop 0
	v_add_f32_e32 v0, 1.0, v0
	v_rcp_f32_e32 v69, v0
	v_lshlrev_b32_e32 v0, 16, v75
	v_add_f32_e32 v0, v70, v0
	v_mul_f32_e32 v0, 0xbfb8aa3b, v0
	v_exp_f32_e32 v0, v0
	v_pk_mul_f32 v[68:69], v[62:63], v[68:69]
	v_add_f32_e32 v0, 1.0, v0
	v_rcp_f32_e32 v62, v0
	v_and_b32_e32 v0, 0xffff0000, v75
	v_add_f32_e32 v0, v71, v0
	v_mul_f32_e32 v0, 0xbfb8aa3b, v0
	v_exp_f32_e32 v0, v0
	s_nop 0
	v_add_f32_e32 v0, 1.0, v0
	v_rcp_f32_e32 v63, v0
	s_nop 0
	v_pk_mul_f32 v[70:71], v[64:65], v[62:63]
	v_lshl_add_u64 v[62:63], v[132:133], 1, v[72:73]
	s_cbranch_vccnz .LBB0_744
	global_load_dwordx2 v[64:65], v[62:63], off
	s_waitcnt vmcnt(0)
	v_lshlrev_b32_e32 v72, 16, v64
	v_and_b32_e32 v73, 0xffff0000, v64
	v_lshlrev_b32_e32 v64, 16, v65
	v_and_b32_e32 v65, 0xffff0000, v65
	v_pk_add_f32 v[68:69], v[68:69], v[72:73]
	v_pk_add_f32 v[70:71], v[70:71], v[64:65]
; DI u32 pack2(float a, float b) { f2_t v = {a, b}; bf2_t r = __builtin_convertvector(v, bf2_t); return __builtin_bit_cast(u32, r); }
; DI float bflo(u32 v) { return __uint_as_float(v << 16); }
; DI float bfhi(u32 v) { return __uint_as_float(v & 0xffff0000u); }
; DI float sigmoidf_(float x) { return __builtin_amdgcn_rcpf(1.f + __builtin_amdgcn_exp2f(-LOG2E * x)); }
; DI void branch_tile8(const Params& P, const WsPtrs& W, int layer, int mt, int nt, unsigned char* smem) {
;     ...
;         const int row = m0 + bj * 128 + wc * 32 + n * 16 + fr;
;         const u16* gp = W.Y + (size_t)row * LDY + O_GT + jb * 1024;
;         u16* mp = W.MERGED + (size_t)row * 1024;
; #pragma unroll
;         for (int ai = 0; ai < 2; ++ai)
; #pragma unroll
;           for (int m = 0; m < 4; ++m) {
;             const int f = n0 + ai * 128 + wr * 64 + m * 16 + fq * 4;
;             const u32x2 gv = *(const u32x2*)(gp + f);
;             const f32x4 b4 = *(const f32x4*)(gbp + f);
;             f32x4v a = acc[ai][bj][m][n];
;             float v0 = sigmoidf_(bflo(gv.x) + b4.x) * a.x, v1 = sigmoidf_(bfhi(gv.x) + b4.y) * a.y;
;             float v2 = sigmoidf_(bflo(gv.y) + b4.z) * a.z, v3 = sigmoidf_(bfhi(gv.y) + b4.w) * a.w;
;             if (jb > 0) { const u32x2 pv = *(const u32x2*)(mp + f); v0 += bflo(pv.x); v1 += bfhi(pv.x); v2 += bflo(pv.y); v3 += bfhi(pv.y); }
;             u32x2 o2; o2.x = pack2(v0, v1); o2.y = pack2(v2, v3);
;             *(u32x2*)(mp + f) = o2;
;           }
.LBB0_744:
	s_mov_b64 s[20:21], 0x4000
	v_lshl_add_u64 v[64:65], v[66:67], 0, s[20:21]
	v_cvt_pk_bf16_f32 v148, v68, v69
	v_cvt_pk_bf16_f32 v149, v70, v71
	global_load_dwordx2 v[72:73], v[64:65], off offset:32
	s_and_b64 vcc, exec, s[6:7]
	s_nop 0
	global_load_dwordx4 v[66:69], v[130:131], off offset:64
	s_waitcnt vmcnt(1)
	v_lshlrev_b32_e32 v0, 16, v72
	v_and_b32_e32 v70, 0xffff0000, v72
	v_lshlrev_b32_e32 v71, 16, v73
	v_and_b32_e32 v72, 0xffff0000, v73
	s_waitcnt vmcnt(0)
	v_add_f32_e32 v0, v66, v0
	v_add_f32_e32 v66, v67, v70
	v_add_f32_e32 v67, v68, v71
	v_add_f32_e32 v68, v69, v72
	v_mul_f32_e32 v0, 0xbfb8aa3b, v0
	v_mul_f32_e32 v66, 0xbfb8aa3b, v66
	v_mul_f32_e32 v67, 0xbfb8aa3b, v67
	v_mul_f32_e32 v68, 0xbfb8aa3b, v68
	v_exp_f32_e32 v0, v0
	v_exp_f32_e32 v66, v66
	v_exp_f32_e32 v67, v67
	v_exp_f32_e32 v68, v68
	v_add_f32_e32 v0, 1.0, v0
	v_add_f32_e32 v69, 1.0, v66
	v_add_f32_e32 v70, 1.0, v67
	v_add_f32_e32 v71, 1.0, v68
	v_rcp_f32_e32 v66, v0
	v_rcp_f32_e32 v67, v69
	v_rcp_f32_e32 v68, v70
	v_rcp_f32_e32 v69, v71
	v_pk_mul_f32 v[58:59], v[58:59], v[66:67]
	v_pk_mul_f32 v[60:61], v[60:61], v[68:69]
	s_cbranch_vccnz .LBB0_746
	global_load_dwordx2 v[66:67], v[62:63], off offset:32
	s_waitcnt vmcnt(0)
	v_lshlrev_b32_e32 v68, 16, v66
	v_and_b32_e32 v69, 0xffff0000, v66
	v_lshlrev_b32_e32 v66, 16, v67
	v_and_b32_e32 v67, 0xffff0000, v67
	v_pk_add_f32 v[58:59], v[58:59], v[68:69]
	v_pk_add_f32 v[60:61], v[60:61], v[66:67]
.LBB0_746:
	v_cvt_pk_bf16_f32 v150, v58, v59
	v_cvt_pk_bf16_f32 v151, v60, v61
	global_load_dwordx2 v[66:67], v[64:65], off offset:64
	s_and_b64 vcc, exec, s[6:7]
	v_lshl_add_u64 v[166:167], v[62:63], 0, v[164:165]
	s_nop 1
	v_permlane16_swap_b32_e32 v148, v150
	v_permlane16_swap_b32_e32 v149, v151
	global_store_dwordx4 v[166:167], v[148:151], off
	global_load_dwordx4 v[58:61], v[130:131], off offset:128
	s_waitcnt vmcnt(2)
	v_lshlrev_b32_e32 v0, 16, v66
	v_and_b32_e32 v66, 0xffff0000, v66
	v_lshlrev_b32_e32 v68, 16, v67
	v_and_b32_e32 v67, 0xffff0000, v67
	s_waitcnt vmcnt(0)
	v_add_f32_e32 v0, v58, v0
	v_add_f32_e32 v58, v59, v66
	v_add_f32_e32 v59, v60, v68
	v_add_f32_e32 v60, v61, v67
	v_mul_f32_e32 v0, 0xbfb8aa3b, v0
	v_mul_f32_e32 v58, 0xbfb8aa3b, v58
	v_mul_f32_e32 v59, 0xbfb8aa3b, v59
	v_mul_f32_e32 v60, 0xbfb8aa3b, v60
	v_exp_f32_e32 v0, v0
	v_exp_f32_e32 v58, v58
	v_exp_f32_e32 v59, v59
	v_exp_f32_e32 v60, v60
	v_add_f32_e32 v0, 1.0, v0
	v_add_f32_e32 v61, 1.0, v58
	v_add_f32_e32 v66, 1.0, v59
	v_add_f32_e32 v67, 1.0, v60
	v_rcp_f32_e32 v58, v0
	v_rcp_f32_e32 v59, v61
	v_rcp_f32_e32 v60, v66
	v_rcp_f32_e32 v61, v67
	v_pk_mul_f32 v[54:55], v[54:55], v[58:59]
	v_pk_mul_f32 v[56:57], v[56:57], v[60:61]
	s_cbranch_vccnz .LBB0_748
	global_load_dwordx2 v[58:59], v[62:63], off offset:64
	s_waitcnt vmcnt(0)
	v_lshlrev_b32_e32 v60, 16, v58
	v_and_b32_e32 v61, 0xffff0000, v58
	v_lshlrev_b32_e32 v58, 16, v59
	v_and_b32_e32 v59, 0xffff0000, v59
	v_pk_add_f32 v[54:55], v[54:55], v[60:61]
	v_pk_add_f32 v[56:57], v[56:57], v[58:59]
.LBB0_748:
	v_cvt_pk_bf16_f32 v152, v54, v55
	v_cvt_pk_bf16_f32 v153, v56, v57
	global_load_dwordx2 v[58:59], v[64:65], off offset:96
	s_and_b64 vcc, exec, s[6:7]
	s_nop 0
	global_load_dwordx4 v[54:57], v[130:131], off offset:192
	s_waitcnt vmcnt(1)
	v_lshlrev_b32_e32 v0, 16, v58
	v_and_b32_e32 v58, 0xffff0000, v58
	v_lshlrev_b32_e32 v60, 16, v59
	v_and_b32_e32 v59, 0xffff0000, v59
	s_waitcnt vmcnt(0)
	v_add_f32_e32 v0, v54, v0
	v_add_f32_e32 v54, v55, v58
	v_add_f32_e32 v55, v56, v60
	v_add_f32_e32 v56, v57, v59
	v_mul_f32_e32 v0, 0xbfb8aa3b, v0
	v_mul_f32_e32 v54, 0xbfb8aa3b, v54
	v_mul_f32_e32 v55, 0xbfb8aa3b, v55
	v_mul_f32_e32 v56, 0xbfb8aa3b, v56
	v_exp_f32_e32 v0, v0
	v_exp_f32_e32 v54, v54
	v_exp_f32_e32 v55, v55
	v_exp_f32_e32 v56, v56
	v_add_f32_e32 v0, 1.0, v0
	v_add_f32_e32 v57, 1.0, v54
	v_add_f32_e32 v58, 1.0, v55
	v_add_f32_e32 v59, 1.0, v56
	v_rcp_f32_e32 v54, v0
	v_rcp_f32_e32 v55, v57
	v_rcp_f32_e32 v56, v58
	v_rcp_f32_e32 v57, v59
	v_pk_mul_f32 v[50:51], v[50:51], v[54:55]
	v_pk_mul_f32 v[52:53], v[52:53], v[56:57]
	s_cbranch_vccnz .LBB0_750
	global_load_dwordx2 v[54:55], v[62:63], off offset:96
	s_waitcnt vmcnt(0)
	v_lshlrev_b32_e32 v56, 16, v54
	v_and_b32_e32 v57, 0xffff0000, v54
	v_lshlrev_b32_e32 v54, 16, v55
	v_and_b32_e32 v55, 0xffff0000, v55
	v_pk_add_f32 v[50:51], v[50:51], v[56:57]
	v_pk_add_f32 v[52:53], v[52:53], v[54:55]
.LBB0_750:
	v_cvt_pk_bf16_f32 v154, v50, v51
	v_cvt_pk_bf16_f32 v155, v52, v53
	global_load_dwordx2 v[54:55], v[64:65], off offset:256
	s_and_b64 vcc, exec, s[6:7]
	v_lshl_add_u64 v[166:167], v[62:63], 0, v[164:165]
	s_nop 1
	v_permlane16_swap_b32_e32 v152, v154
	v_permlane16_swap_b32_e32 v153, v155
	global_store_dwordx4 v[166:167], v[152:155], off offset:64
	global_load_dwordx4 v[50:53], v[130:131], off offset:512
	s_waitcnt vmcnt(2)
	v_lshlrev_b32_e32 v0, 16, v54
	v_and_b32_e32 v54, 0xffff0000, v54
	v_lshlrev_b32_e32 v56, 16, v55
	v_and_b32_e32 v55, 0xffff0000, v55
	s_waitcnt vmcnt(0)
	v_add_f32_e32 v0, v50, v0
	v_add_f32_e32 v50, v51, v54
	v_add_f32_e32 v51, v52, v56
	v_add_f32_e32 v52, v53, v55
	v_mul_f32_e32 v0, 0xbfb8aa3b, v0
	v_mul_f32_e32 v50, 0xbfb8aa3b, v50
	v_mul_f32_e32 v51, 0xbfb8aa3b, v51
	v_mul_f32_e32 v52, 0xbfb8aa3b, v52
	v_exp_f32_e32 v0, v0
	v_exp_f32_e32 v50, v50
	v_exp_f32_e32 v51, v51
	v_exp_f32_e32 v52, v52
	v_add_f32_e32 v0, 1.0, v0
	v_add_f32_e32 v53, 1.0, v50
	v_add_f32_e32 v54, 1.0, v51
	v_add_f32_e32 v55, 1.0, v52
	v_rcp_f32_e32 v50, v0
	v_rcp_f32_e32 v51, v53
	v_rcp_f32_e32 v52, v54
	v_rcp_f32_e32 v53, v55
	v_pk_mul_f32 v[46:47], v[46:47], v[50:51]
	v_pk_mul_f32 v[48:49], v[48:49], v[52:53]
	s_cbranch_vccnz .LBB0_752
	global_load_dwordx2 v[50:51], v[62:63], off offset:256
	s_waitcnt vmcnt(0)
	v_lshlrev_b32_e32 v52, 16, v50
	v_and_b32_e32 v53, 0xffff0000, v50
	v_lshlrev_b32_e32 v50, 16, v51
	v_and_b32_e32 v51, 0xffff0000, v51
	v_pk_add_f32 v[46:47], v[46:47], v[52:53]
	v_pk_add_f32 v[48:49], v[48:49], v[50:51]
; DI u32 pack2(float a, float b) { f2_t v = {a, b}; bf2_t r = __builtin_convertvector(v, bf2_t); return __builtin_bit_cast(u32, r); }
; DI float bflo(u32 v) { return __uint_as_float(v << 16); }
; DI float bfhi(u32 v) { return __uint_as_float(v & 0xffff0000u); }
; DI float sigmoidf_(float x) { return __builtin_amdgcn_rcpf(1.f + __builtin_amdgcn_exp2f(-LOG2E * x)); }
; DI void branch_tile8(const Params& P, const WsPtrs& W, int layer, int mt, int nt, unsigned char* smem) {
;     ...
;         const int row = m0 + bj * 128 + wc * 32 + n * 16 + fr;
;         const u16* gp = W.Y + (size_t)row * LDY + O_GT + jb * 1024;
;         u16* mp = W.MERGED + (size_t)row * 1024;
; #pragma unroll
;         for (int ai = 0; ai < 2; ++ai)
; #pragma unroll
;           for (int m = 0; m < 4; ++m) {
;             const int f = n0 + ai * 128 + wr * 64 + m * 16 + fq * 4;
;             const u32x2 gv = *(const u32x2*)(gp + f);
;             const f32x4 b4 = *(const f32x4*)(gbp + f);
;             f32x4v a = acc[ai][bj][m][n];
;             float v0 = sigmoidf_(bflo(gv.x) + b4.x) * a.x, v1 = sigmoidf_(bfhi(gv.x) + b4.y) * a.y;
;             float v2 = sigmoidf_(bflo(gv.y) + b4.z) * a.z, v3 = sigmoidf_(bfhi(gv.y) + b4.w) * a.w;
;             if (jb > 0) { const u32x2 pv = *(const u32x2*)(mp + f); v0 += bflo(pv.x); v1 += bfhi(pv.x); v2 += bflo(pv.y); v3 += bfhi(pv.y); }
;             u32x2 o2; o2.x = pack2(v0, v1); o2.y = pack2(v2, v3);
;             *(u32x2*)(mp + f) = o2;
;           }
.LBB0_752:
	v_cvt_pk_bf16_f32 v156, v46, v47
	v_cvt_pk_bf16_f32 v157, v48, v49
	global_load_dwordx2 v[50:51], v[64:65], off offset:288
	s_and_b64 vcc, exec, s[6:7]
	s_nop 0
	global_load_dwordx4 v[46:49], v[130:131], off offset:576
	s_waitcnt vmcnt(1)
	v_lshlrev_b32_e32 v0, 16, v50
	v_and_b32_e32 v50, 0xffff0000, v50
	v_lshlrev_b32_e32 v52, 16, v51
	v_and_b32_e32 v51, 0xffff0000, v51
	s_waitcnt vmcnt(0)
	v_add_f32_e32 v0, v46, v0
	v_add_f32_e32 v46, v47, v50
	v_add_f32_e32 v47, v48, v52
	v_add_f32_e32 v48, v49, v51
	v_mul_f32_e32 v0, 0xbfb8aa3b, v0
	v_mul_f32_e32 v46, 0xbfb8aa3b, v46
	v_mul_f32_e32 v47, 0xbfb8aa3b, v47
	v_mul_f32_e32 v48, 0xbfb8aa3b, v48
	v_exp_f32_e32 v0, v0
	v_exp_f32_e32 v46, v46
	v_exp_f32_e32 v47, v47
	v_exp_f32_e32 v48, v48
	v_add_f32_e32 v0, 1.0, v0
	v_add_f32_e32 v49, 1.0, v46
	v_add_f32_e32 v50, 1.0, v47
	v_add_f32_e32 v51, 1.0, v48
	v_rcp_f32_e32 v46, v0
	v_rcp_f32_e32 v47, v49
	v_rcp_f32_e32 v48, v50
	v_rcp_f32_e32 v49, v51
	v_pk_mul_f32 v[42:43], v[42:43], v[46:47]
	v_pk_mul_f32 v[44:45], v[44:45], v[48:49]
	s_cbranch_vccnz .LBB0_754
	global_load_dwordx2 v[46:47], v[62:63], off offset:288
	s_waitcnt vmcnt(0)
	v_lshlrev_b32_e32 v48, 16, v46
	v_and_b32_e32 v49, 0xffff0000, v46
	v_lshlrev_b32_e32 v46, 16, v47
	v_and_b32_e32 v47, 0xffff0000, v47
	v_pk_add_f32 v[42:43], v[42:43], v[48:49]
	v_pk_add_f32 v[44:45], v[44:45], v[46:47]
.LBB0_754:
	v_cvt_pk_bf16_f32 v158, v42, v43
	v_cvt_pk_bf16_f32 v159, v44, v45
	global_load_dwordx2 v[46:47], v[64:65], off offset:320
	s_and_b64 vcc, exec, s[6:7]
	v_lshl_add_u64 v[166:167], v[62:63], 0, v[164:165]
	s_nop 1
	v_permlane16_swap_b32_e32 v156, v158
	v_permlane16_swap_b32_e32 v157, v159
	global_store_dwordx4 v[166:167], v[156:159], off offset:256
	global_load_dwordx4 v[42:45], v[130:131], off offset:640
	s_waitcnt vmcnt(2)
	v_lshlrev_b32_e32 v0, 16, v46
	v_and_b32_e32 v46, 0xffff0000, v46
	v_lshlrev_b32_e32 v48, 16, v47
	v_and_b32_e32 v47, 0xffff0000, v47
	s_waitcnt vmcnt(0)
	v_add_f32_e32 v0, v42, v0
	v_add_f32_e32 v42, v43, v46
	v_add_f32_e32 v43, v44, v48
	v_add_f32_e32 v44, v45, v47
	v_mul_f32_e32 v0, 0xbfb8aa3b, v0
	v_mul_f32_e32 v42, 0xbfb8aa3b, v42
	v_mul_f32_e32 v43, 0xbfb8aa3b, v43
	v_mul_f32_e32 v44, 0xbfb8aa3b, v44
	v_exp_f32_e32 v0, v0
	v_exp_f32_e32 v42, v42
	v_exp_f32_e32 v43, v43
	v_exp_f32_e32 v44, v44
	v_add_f32_e32 v0, 1.0, v0
	v_add_f32_e32 v45, 1.0, v42
	v_add_f32_e32 v46, 1.0, v43
	v_add_f32_e32 v47, 1.0, v44
	v_rcp_f32_e32 v42, v0
	v_rcp_f32_e32 v43, v45
	v_rcp_f32_e32 v44, v46
	v_rcp_f32_e32 v45, v47
	v_pk_mul_f32 v[38:39], v[38:39], v[42:43]
	v_pk_mul_f32 v[40:41], v[40:41], v[44:45]
	s_cbranch_vccnz .LBB0_756
	global_load_dwordx2 v[42:43], v[62:63], off offset:320
	s_waitcnt vmcnt(0)
	v_lshlrev_b32_e32 v44, 16, v42
	v_and_b32_e32 v45, 0xffff0000, v42
	v_lshlrev_b32_e32 v42, 16, v43
	v_and_b32_e32 v43, 0xffff0000, v43
	v_pk_add_f32 v[38:39], v[38:39], v[44:45]
	v_pk_add_f32 v[40:41], v[40:41], v[42:43]
.LBB0_756:
	v_cvt_pk_bf16_f32 v160, v38, v39
	v_cvt_pk_bf16_f32 v161, v40, v41
	global_load_dwordx2 v[42:43], v[64:65], off offset:352
	s_and_b64 vcc, exec, s[6:7]
	s_nop 0
	global_load_dwordx4 v[38:41], v[130:131], off offset:704
	s_waitcnt vmcnt(1)
	v_lshlrev_b32_e32 v0, 16, v42
	v_and_b32_e32 v42, 0xffff0000, v42
	v_lshlrev_b32_e32 v44, 16, v43
	v_and_b32_e32 v43, 0xffff0000, v43
	s_waitcnt vmcnt(0)
	v_add_f32_e32 v0, v38, v0
	v_add_f32_e32 v38, v39, v42
	v_add_f32_e32 v39, v40, v44
	v_add_f32_e32 v40, v41, v43
	v_mul_f32_e32 v0, 0xbfb8aa3b, v0
	v_mul_f32_e32 v38, 0xbfb8aa3b, v38
	v_mul_f32_e32 v39, 0xbfb8aa3b, v39
	v_mul_f32_e32 v40, 0xbfb8aa3b, v40
	v_exp_f32_e32 v0, v0
	v_exp_f32_e32 v38, v38
	v_exp_f32_e32 v39, v39
	v_exp_f32_e32 v40, v40
	v_add_f32_e32 v0, 1.0, v0
	v_add_f32_e32 v41, 1.0, v38
	v_add_f32_e32 v42, 1.0, v39
	v_add_f32_e32 v43, 1.0, v40
	v_rcp_f32_e32 v38, v0
	v_rcp_f32_e32 v39, v41
	v_rcp_f32_e32 v40, v42
	v_rcp_f32_e32 v41, v43
	v_pk_mul_f32 v[34:35], v[34:35], v[38:39]
	v_pk_mul_f32 v[36:37], v[36:37], v[40:41]
	s_cbranch_vccnz .LBB0_758
	global_load_dwordx2 v[38:39], v[62:63], off offset:352
	s_waitcnt vmcnt(0)
	v_lshlrev_b32_e32 v40, 16, v38
	v_and_b32_e32 v41, 0xffff0000, v38
	v_lshlrev_b32_e32 v38, 16, v39
	v_and_b32_e32 v39, 0xffff0000, v39
	v_pk_add_f32 v[34:35], v[34:35], v[40:41]
	v_pk_add_f32 v[36:37], v[36:37], v[38:39]
.LBB0_758:
	v_cvt_pk_bf16_f32 v162, v34, v35
	v_cvt_pk_bf16_f32 v163, v36, v37
	v_lshl_add_u64 v[166:167], v[62:63], 0, v[164:165]
	s_nop 1
	v_permlane16_swap_b32_e32 v160, v162
	v_permlane16_swap_b32_e32 v161, v163
	global_store_dwordx4 v[166:167], v[160:163], off offset:320
	v_or_b32_e32 v34, 0x90, v134
	v_mov_b64_e32 v[36:37], s[8:9]
	v_ashrrev_i32_e32 v35, 31, v34
	v_mad_i64_i32 v[36:37], s[20:21], v34, s33, v[36:37]
	v_lshl_add_u64 v[36:37], v[36:37], 0, s[2:3]
	v_lshlrev_b64 v[34:35], 11, v[34:35]
	v_lshl_add_u64 v[40:41], s[10:11], 0, v[34:35]
	v_lshl_add_u64 v[34:35], v[132:133], 1, v[36:37]
	s_movk_i32 s2, 0x4000
	v_add_co_u32_e32 v36, vcc, s2, v34
	s_nop 1
	v_addc_co_u32_e32 v37, vcc, 0, v35, vcc
	global_load_dwordx2 v[42:43], v[36:37], off
	s_nop 0
	global_load_dwordx4 v[36:39], v[130:131], off
	s_and_b64 vcc, exec, s[6:7]
	s_waitcnt vmcnt(0)
	v_lshlrev_b32_e32 v0, 16, v42
	s_waitcnt vmcnt(0)
	v_add_f32_e32 v0, v36, v0
	v_mul_f32_e32 v0, 0xbfb8aa3b, v0
	v_exp_f32_e32 v0, v0
	s_nop 0
	v_add_f32_e32 v0, 1.0, v0
	v_rcp_f32_e32 v36, v0
	v_and_b32_e32 v0, 0xffff0000, v42
	v_add_f32_e32 v0, v37, v0
	v_mul_f32_e32 v0, 0xbfb8aa3b, v0
	v_exp_f32_e32 v0, v0
	s_nop 0
	v_add_f32_e32 v0, 1.0, v0
	v_rcp_f32_e32 v37, v0
	v_lshlrev_b32_e32 v0, 16, v43
	v_add_f32_e32 v0, v38, v0
	v_mul_f32_e32 v0, 0xbfb8aa3b, v0
	v_exp_f32_e32 v0, v0
	v_pk_mul_f32 v[36:37], v[30:31], v[36:37]
	v_add_f32_e32 v0, 1.0, v0
	v_rcp_f32_e32 v30, v0
	v_and_b32_e32 v0, 0xffff0000, v43
	v_add_f32_e32 v0, v39, v0
	v_mul_f32_e32 v0, 0xbfb8aa3b, v0
	v_exp_f32_e32 v0, v0
	s_nop 0
	v_add_f32_e32 v0, 1.0, v0
	v_rcp_f32_e32 v31, v0
	s_nop 0
	v_pk_mul_f32 v[38:39], v[32:33], v[30:31]
	v_lshl_add_u64 v[30:31], v[132:133], 1, v[40:41]
	s_cbranch_vccnz .LBB0_760
	global_load_dwordx2 v[32:33], v[30:31], off
	s_waitcnt vmcnt(0)
	v_lshlrev_b32_e32 v40, 16, v32
	v_and_b32_e32 v41, 0xffff0000, v32
	v_lshlrev_b32_e32 v32, 16, v33
	v_and_b32_e32 v33, 0xffff0000, v33
	v_pk_add_f32 v[36:37], v[36:37], v[40:41]
	v_pk_add_f32 v[38:39], v[38:39], v[32:33]
; DI u32 pack2(float a, float b) { f2_t v = {a, b}; bf2_t r = __builtin_convertvector(v, bf2_t); return __builtin_bit_cast(u32, r); }
; DI float bflo(u32 v) { return __uint_as_float(v << 16); }
; DI float bfhi(u32 v) { return __uint_as_float(v & 0xffff0000u); }
; DI float sigmoidf_(float x) { return __builtin_amdgcn_rcpf(1.f + __builtin_amdgcn_exp2f(-LOG2E * x)); }
; DI void branch_tile8(const Params& P, const WsPtrs& W, int layer, int mt, int nt, unsigned char* smem) {
;     ...
;     const float* gbp = P.in[I_GATEB] + layer * 4096 + jb * 1024;
; #pragma unroll
;     for (int bj = 0; bj < 2; ++bj)
; #pragma unroll
;       for (int n = 0; n < 2; ++n) {
;         const int row = m0 + bj * 128 + wc * 32 + n * 16 + fr;
;         const u16* gp = W.Y + (size_t)row * LDY + O_GT + jb * 1024;
;         u16* mp = W.MERGED + (size_t)row * 1024;
; #pragma unroll
;         for (int ai = 0; ai < 2; ++ai)
; #pragma unroll
;           for (int m = 0; m < 4; ++m) {
;             const int f = n0 + ai * 128 + wr * 64 + m * 16 + fq * 4;
;             const u32x2 gv = *(const u32x2*)(gp + f);
;             const f32x4 b4 = *(const f32x4*)(gbp + f);
;             f32x4v a = acc[ai][bj][m][n];
;             float v0 = sigmoidf_(bflo(gv.x) + b4.x) * a.x, v1 = sigmoidf_(bfhi(gv.x) + b4.y) * a.y;
;             float v2 = sigmoidf_(bflo(gv.y) + b4.z) * a.z, v3 = sigmoidf_(bfhi(gv.y) + b4.w) * a.w;
;             if (jb > 0) { const u32x2 pv = *(const u32x2*)(mp + f); v0 += bflo(pv.x); v1 += bfhi(pv.x); v2 += bflo(pv.y); v3 += bfhi(pv.y); }
;             u32x2 o2; o2.x = pack2(v0, v1); o2.y = pack2(v2, v3);
;             *(u32x2*)(mp + f) = o2;
;           }
;       }
.LBB0_760:
	s_mov_b64 s[20:21], 0x4000
	v_lshl_add_u64 v[32:33], v[34:35], 0, s[20:21]
	v_cvt_pk_bf16_f32 v148, v36, v37
	v_cvt_pk_bf16_f32 v149, v38, v39
	global_load_dwordx2 v[40:41], v[32:33], off offset:32
	s_and_b64 vcc, exec, s[6:7]
	s_nop 0
	global_load_dwordx4 v[34:37], v[130:131], off offset:64
	s_waitcnt vmcnt(1)
	v_lshlrev_b32_e32 v0, 16, v40
	v_and_b32_e32 v38, 0xffff0000, v40
	v_lshlrev_b32_e32 v39, 16, v41
	v_and_b32_e32 v40, 0xffff0000, v41
	s_waitcnt vmcnt(0)
	v_add_f32_e32 v0, v34, v0
	v_add_f32_e32 v34, v35, v38
	v_add_f32_e32 v35, v36, v39
	v_add_f32_e32 v36, v37, v40
	v_mul_f32_e32 v0, 0xbfb8aa3b, v0
	v_mul_f32_e32 v34, 0xbfb8aa3b, v34
	v_mul_f32_e32 v35, 0xbfb8aa3b, v35
	v_mul_f32_e32 v36, 0xbfb8aa3b, v36
	v_exp_f32_e32 v0, v0
	v_exp_f32_e32 v34, v34
	v_exp_f32_e32 v35, v35
	v_exp_f32_e32 v36, v36
	v_add_f32_e32 v0, 1.0, v0
	v_add_f32_e32 v37, 1.0, v34
	v_add_f32_e32 v38, 1.0, v35
	v_add_f32_e32 v39, 1.0, v36
	v_rcp_f32_e32 v34, v0
	v_rcp_f32_e32 v35, v37
	v_rcp_f32_e32 v36, v38
	v_rcp_f32_e32 v37, v39
	v_pk_mul_f32 v[26:27], v[26:27], v[34:35]
	v_pk_mul_f32 v[28:29], v[28:29], v[36:37]
	s_cbranch_vccnz .LBB0_762
	global_load_dwordx2 v[34:35], v[30:31], off offset:32
	s_waitcnt vmcnt(0)
	v_lshlrev_b32_e32 v36, 16, v34
	v_and_b32_e32 v37, 0xffff0000, v34
	v_lshlrev_b32_e32 v34, 16, v35
	v_and_b32_e32 v35, 0xffff0000, v35
	v_pk_add_f32 v[26:27], v[26:27], v[36:37]
	v_pk_add_f32 v[28:29], v[28:29], v[34:35]
.LBB0_762:
	v_cvt_pk_bf16_f32 v150, v26, v27
	v_cvt_pk_bf16_f32 v151, v28, v29
	global_load_dwordx2 v[34:35], v[32:33], off offset:64
	s_and_b64 vcc, exec, s[6:7]
	v_lshl_add_u64 v[166:167], v[30:31], 0, v[164:165]
	s_nop 1
	v_permlane16_swap_b32_e32 v148, v150
	v_permlane16_swap_b32_e32 v149, v151
	global_store_dwordx4 v[166:167], v[148:151], off
	global_load_dwordx4 v[26:29], v[130:131], off offset:128
	s_waitcnt vmcnt(2)
	v_lshlrev_b32_e32 v0, 16, v34
	v_and_b32_e32 v34, 0xffff0000, v34
	v_lshlrev_b32_e32 v36, 16, v35
	v_and_b32_e32 v35, 0xffff0000, v35
	s_waitcnt vmcnt(0)
	v_add_f32_e32 v0, v26, v0
	v_add_f32_e32 v26, v27, v34
	v_add_f32_e32 v27, v28, v36
	v_add_f32_e32 v28, v29, v35
	v_mul_f32_e32 v0, 0xbfb8aa3b, v0
	v_mul_f32_e32 v26, 0xbfb8aa3b, v26
	v_mul_f32_e32 v27, 0xbfb8aa3b, v27
	v_mul_f32_e32 v28, 0xbfb8aa3b, v28
	v_exp_f32_e32 v0, v0
	v_exp_f32_e32 v26, v26
	v_exp_f32_e32 v27, v27
	v_exp_f32_e32 v28, v28
	v_add_f32_e32 v0, 1.0, v0
	v_add_f32_e32 v29, 1.0, v26
	v_add_f32_e32 v34, 1.0, v27
	v_add_f32_e32 v35, 1.0, v28
	v_rcp_f32_e32 v26, v0
	v_rcp_f32_e32 v27, v29
	v_rcp_f32_e32 v28, v34
	v_rcp_f32_e32 v29, v35
	v_pk_mul_f32 v[22:23], v[22:23], v[26:27]
	v_pk_mul_f32 v[24:25], v[24:25], v[28:29]
	s_cbranch_vccnz .LBB0_764
	global_load_dwordx2 v[26:27], v[30:31], off offset:64
	s_waitcnt vmcnt(0)
	v_lshlrev_b32_e32 v28, 16, v26
	v_and_b32_e32 v29, 0xffff0000, v26
	v_lshlrev_b32_e32 v26, 16, v27
	v_and_b32_e32 v27, 0xffff0000, v27
	v_pk_add_f32 v[22:23], v[22:23], v[28:29]
	v_pk_add_f32 v[24:25], v[24:25], v[26:27]
.LBB0_764:
	v_cvt_pk_bf16_f32 v152, v22, v23
	v_cvt_pk_bf16_f32 v153, v24, v25
	global_load_dwordx2 v[26:27], v[32:33], off offset:96
	s_and_b64 vcc, exec, s[6:7]
	s_nop 0
	global_load_dwordx4 v[22:25], v[130:131], off offset:192
	s_waitcnt vmcnt(1)
	v_lshlrev_b32_e32 v0, 16, v26
	v_and_b32_e32 v26, 0xffff0000, v26
	v_lshlrev_b32_e32 v28, 16, v27
	v_and_b32_e32 v27, 0xffff0000, v27
	s_waitcnt vmcnt(0)
	v_add_f32_e32 v0, v22, v0
	v_add_f32_e32 v22, v23, v26
	v_add_f32_e32 v23, v24, v28
	v_add_f32_e32 v24, v25, v27
	v_mul_f32_e32 v0, 0xbfb8aa3b, v0
	v_mul_f32_e32 v22, 0xbfb8aa3b, v22
	v_mul_f32_e32 v23, 0xbfb8aa3b, v23
	v_mul_f32_e32 v24, 0xbfb8aa3b, v24
	v_exp_f32_e32 v0, v0
	v_exp_f32_e32 v22, v22
	v_exp_f32_e32 v23, v23
	v_exp_f32_e32 v24, v24
	v_add_f32_e32 v0, 1.0, v0
	v_add_f32_e32 v25, 1.0, v22
	v_add_f32_e32 v26, 1.0, v23
	v_add_f32_e32 v27, 1.0, v24
	v_rcp_f32_e32 v22, v0
	v_rcp_f32_e32 v23, v25
	v_rcp_f32_e32 v24, v26
	v_rcp_f32_e32 v25, v27
	v_pk_mul_f32 v[18:19], v[18:19], v[22:23]
	v_pk_mul_f32 v[20:21], v[20:21], v[24:25]
	s_cbranch_vccnz .LBB0_766
	global_load_dwordx2 v[22:23], v[30:31], off offset:96
	s_waitcnt vmcnt(0)
	v_lshlrev_b32_e32 v24, 16, v22
	v_and_b32_e32 v25, 0xffff0000, v22
	v_lshlrev_b32_e32 v22, 16, v23
	v_and_b32_e32 v23, 0xffff0000, v23
	v_pk_add_f32 v[18:19], v[18:19], v[24:25]
	v_pk_add_f32 v[20:21], v[20:21], v[22:23]
; DI u32 pack2(float a, float b) { f2_t v = {a, b}; bf2_t r = __builtin_convertvector(v, bf2_t); return __builtin_bit_cast(u32, r); }
; DI float bflo(u32 v) { return __uint_as_float(v << 16); }
; DI float bfhi(u32 v) { return __uint_as_float(v & 0xffff0000u); }
; DI float sigmoidf_(float x) { return __builtin_amdgcn_rcpf(1.f + __builtin_amdgcn_exp2f(-LOG2E * x)); }
; DI void branch_tile8(const Params& P, const WsPtrs& W, int layer, int mt, int nt, unsigned char* smem) {
;     ...
;     const float* gbp = P.in[I_GATEB] + layer * 4096 + jb * 1024;
; #pragma unroll
;     for (int bj = 0; bj < 2; ++bj)
; #pragma unroll
;       for (int n = 0; n < 2; ++n) {
;         const int row = m0 + bj * 128 + wc * 32 + n * 16 + fr;
;         const u16* gp = W.Y + (size_t)row * LDY + O_GT + jb * 1024;
;         u16* mp = W.MERGED + (size_t)row * 1024;
; #pragma unroll
;         for (int ai = 0; ai < 2; ++ai)
; #pragma unroll
;           for (int m = 0; m < 4; ++m) {
;             const int f = n0 + ai * 128 + wr * 64 + m * 16 + fq * 4;
;             const u32x2 gv = *(const u32x2*)(gp + f);
;             const f32x4 b4 = *(const f32x4*)(gbp + f);
;             f32x4v a = acc[ai][bj][m][n];
;             float v0 = sigmoidf_(bflo(gv.x) + b4.x) * a.x, v1 = sigmoidf_(bfhi(gv.x) + b4.y) * a.y;
;             float v2 = sigmoidf_(bflo(gv.y) + b4.z) * a.z, v3 = sigmoidf_(bfhi(gv.y) + b4.w) * a.w;
;             if (jb > 0) { const u32x2 pv = *(const u32x2*)(mp + f); v0 += bflo(pv.x); v1 += bfhi(pv.x); v2 += bflo(pv.y); v3 += bfhi(pv.y); }
;             u32x2 o2; o2.x = pack2(v0, v1); o2.y = pack2(v2, v3);
;             *(u32x2*)(mp + f) = o2;
;           }
;       }
.LBB0_766:
	v_cvt_pk_bf16_f32 v154, v18, v19
	v_cvt_pk_bf16_f32 v155, v20, v21
	global_load_dwordx2 v[22:23], v[32:33], off offset:256
	s_and_b64 vcc, exec, s[6:7]
	v_lshl_add_u64 v[166:167], v[30:31], 0, v[164:165]
	s_nop 1
	v_permlane16_swap_b32_e32 v152, v154
	v_permlane16_swap_b32_e32 v153, v155
	global_store_dwordx4 v[166:167], v[152:155], off offset:64
	global_load_dwordx4 v[18:21], v[130:131], off offset:512
	s_waitcnt vmcnt(2)
	v_lshlrev_b32_e32 v0, 16, v22
	v_and_b32_e32 v22, 0xffff0000, v22
	v_lshlrev_b32_e32 v24, 16, v23
	v_and_b32_e32 v23, 0xffff0000, v23
	s_waitcnt vmcnt(0)
	v_add_f32_e32 v0, v18, v0
	v_add_f32_e32 v18, v19, v22
	v_add_f32_e32 v19, v20, v24
	v_add_f32_e32 v20, v21, v23
	v_mul_f32_e32 v0, 0xbfb8aa3b, v0
	v_mul_f32_e32 v18, 0xbfb8aa3b, v18
	v_mul_f32_e32 v19, 0xbfb8aa3b, v19
	v_mul_f32_e32 v20, 0xbfb8aa3b, v20
	v_exp_f32_e32 v0, v0
	v_exp_f32_e32 v18, v18
	v_exp_f32_e32 v19, v19
	v_exp_f32_e32 v20, v20
	v_add_f32_e32 v0, 1.0, v0
	v_add_f32_e32 v21, 1.0, v18
	v_add_f32_e32 v22, 1.0, v19
	v_add_f32_e32 v23, 1.0, v20
	v_rcp_f32_e32 v18, v0
	v_rcp_f32_e32 v19, v21
	v_rcp_f32_e32 v20, v22
	v_rcp_f32_e32 v21, v23
	v_pk_mul_f32 v[14:15], v[14:15], v[18:19]
	v_pk_mul_f32 v[16:17], v[16:17], v[20:21]
	s_cbranch_vccnz .LBB0_768
	global_load_dwordx2 v[18:19], v[30:31], off offset:256
	s_waitcnt vmcnt(0)
	v_lshlrev_b32_e32 v20, 16, v18
	v_and_b32_e32 v21, 0xffff0000, v18
	v_lshlrev_b32_e32 v18, 16, v19
	v_and_b32_e32 v19, 0xffff0000, v19
	v_pk_add_f32 v[14:15], v[14:15], v[20:21]
	v_pk_add_f32 v[16:17], v[16:17], v[18:19]
.LBB0_768:
	v_cvt_pk_bf16_f32 v156, v14, v15
	v_cvt_pk_bf16_f32 v157, v16, v17
	global_load_dwordx2 v[18:19], v[32:33], off offset:288
	s_and_b64 vcc, exec, s[6:7]
	s_nop 0
	global_load_dwordx4 v[14:17], v[130:131], off offset:576
	s_waitcnt vmcnt(1)
	v_lshlrev_b32_e32 v0, 16, v18
	v_and_b32_e32 v18, 0xffff0000, v18
	v_lshlrev_b32_e32 v20, 16, v19
	v_and_b32_e32 v19, 0xffff0000, v19
	s_waitcnt vmcnt(0)
	v_add_f32_e32 v0, v14, v0
	v_add_f32_e32 v14, v15, v18
	v_add_f32_e32 v15, v16, v20
	v_add_f32_e32 v16, v17, v19
	v_mul_f32_e32 v0, 0xbfb8aa3b, v0
	v_mul_f32_e32 v14, 0xbfb8aa3b, v14
	v_mul_f32_e32 v15, 0xbfb8aa3b, v15
	v_mul_f32_e32 v16, 0xbfb8aa3b, v16
	v_exp_f32_e32 v0, v0
	v_exp_f32_e32 v14, v14
	v_exp_f32_e32 v15, v15
	v_exp_f32_e32 v16, v16
	v_add_f32_e32 v0, 1.0, v0
	v_add_f32_e32 v17, 1.0, v14
	v_add_f32_e32 v18, 1.0, v15
	v_add_f32_e32 v19, 1.0, v16
	v_rcp_f32_e32 v14, v0
	v_rcp_f32_e32 v15, v17
	v_rcp_f32_e32 v16, v18
	v_rcp_f32_e32 v17, v19
	v_pk_mul_f32 v[10:11], v[10:11], v[14:15]
	v_pk_mul_f32 v[12:13], v[12:13], v[16:17]
	s_cbranch_vccnz .LBB0_770
	global_load_dwordx2 v[14:15], v[30:31], off offset:288
	s_waitcnt vmcnt(0)
	v_lshlrev_b32_e32 v16, 16, v14
	v_and_b32_e32 v17, 0xffff0000, v14
	v_lshlrev_b32_e32 v14, 16, v15
	v_and_b32_e32 v15, 0xffff0000, v15
	v_pk_add_f32 v[10:11], v[10:11], v[16:17]
	v_pk_add_f32 v[12:13], v[12:13], v[14:15]
.LBB0_770:
	v_cvt_pk_bf16_f32 v158, v10, v11
	v_cvt_pk_bf16_f32 v159, v12, v13
	global_load_dwordx2 v[14:15], v[32:33], off offset:320
	s_and_b64 vcc, exec, s[6:7]
	v_lshl_add_u64 v[166:167], v[30:31], 0, v[164:165]
	s_nop 1
	v_permlane16_swap_b32_e32 v156, v158
	v_permlane16_swap_b32_e32 v157, v159
	global_store_dwordx4 v[166:167], v[156:159], off offset:256
	global_load_dwordx4 v[10:13], v[130:131], off offset:640
	s_waitcnt vmcnt(2)
	v_lshlrev_b32_e32 v0, 16, v14
	v_and_b32_e32 v14, 0xffff0000, v14
	v_lshlrev_b32_e32 v16, 16, v15
	v_and_b32_e32 v15, 0xffff0000, v15
	s_waitcnt vmcnt(0)
	v_add_f32_e32 v0, v10, v0
	v_add_f32_e32 v10, v11, v14
	v_add_f32_e32 v11, v12, v16
	v_add_f32_e32 v12, v13, v15
	v_mul_f32_e32 v0, 0xbfb8aa3b, v0
	v_mul_f32_e32 v10, 0xbfb8aa3b, v10
	v_mul_f32_e32 v11, 0xbfb8aa3b, v11
	v_mul_f32_e32 v12, 0xbfb8aa3b, v12
	v_exp_f32_e32 v0, v0
	v_exp_f32_e32 v10, v10
	v_exp_f32_e32 v11, v11
	v_exp_f32_e32 v12, v12
	v_add_f32_e32 v0, 1.0, v0
	v_add_f32_e32 v13, 1.0, v10
	v_add_f32_e32 v14, 1.0, v11
	v_add_f32_e32 v15, 1.0, v12
	v_rcp_f32_e32 v10, v0
	v_rcp_f32_e32 v11, v13
	v_rcp_f32_e32 v12, v14
	v_rcp_f32_e32 v13, v15
	v_pk_mul_f32 v[6:7], v[6:7], v[10:11]
	v_pk_mul_f32 v[8:9], v[8:9], v[12:13]
	s_cbranch_vccnz .LBB0_772
	global_load_dwordx2 v[10:11], v[30:31], off offset:320
	s_waitcnt vmcnt(0)
	v_lshlrev_b32_e32 v12, 16, v10
	v_and_b32_e32 v13, 0xffff0000, v10
	v_lshlrev_b32_e32 v10, 16, v11
	v_and_b32_e32 v11, 0xffff0000, v11
	v_pk_add_f32 v[6:7], v[6:7], v[12:13]
	v_pk_add_f32 v[8:9], v[8:9], v[10:11]
.LBB0_772:
	v_cvt_pk_bf16_f32 v6, v6, v7
	v_cvt_pk_bf16_f32 v7, v8, v9
	global_store_dwordx2 v[30:31], v[6:7], off offset:320
	global_load_dwordx2 v[10:11], v[32:33], off offset:352
	s_nop 0
	global_load_dwordx4 v[6:9], v[130:131], off offset:704
	s_and_b64 vcc, exec, s[6:7]
	s_waitcnt vmcnt(0)
	v_lshlrev_b32_e32 v0, 16, v10
	s_waitcnt vmcnt(0)
	v_add_f32_e32 v0, v6, v0
	v_mul_f32_e32 v0, 0xbfb8aa3b, v0
	v_exp_f32_e32 v0, v0
	s_nop 0
	v_add_f32_e32 v0, 1.0, v0
	v_rcp_f32_e32 v6, v0
	v_and_b32_e32 v0, 0xffff0000, v10
	v_add_f32_e32 v0, v7, v0
	v_mul_f32_e32 v0, 0xbfb8aa3b, v0
	v_exp_f32_e32 v0, v0
	s_nop 0
	v_add_f32_e32 v0, 1.0, v0
	v_rcp_f32_e32 v7, v0
	v_lshlrev_b32_e32 v0, 16, v11
	v_add_f32_e32 v0, v8, v0
	v_mul_f32_e32 v0, 0xbfb8aa3b, v0
	v_exp_f32_e32 v0, v0
	v_pk_mul_f32 v[2:3], v[2:3], v[6:7]
	v_add_f32_e32 v0, 1.0, v0
	v_rcp_f32_e32 v6, v0
	v_and_b32_e32 v0, 0xffff0000, v11
	v_add_f32_e32 v0, v9, v0
	v_mul_f32_e32 v0, 0xbfb8aa3b, v0
	v_exp_f32_e32 v0, v0
	s_nop 0
	v_add_f32_e32 v0, 1.0, v0
	v_rcp_f32_e32 v7, v0
	s_nop 0
	v_pk_mul_f32 v[4:5], v[4:5], v[6:7]
	s_cbranch_vccnz .LBB0_703
	global_load_dwordx2 v[6:7], v[30:31], off offset:352
	s_waitcnt vmcnt(0)
	v_lshlrev_b32_e32 v8, 16, v6
	v_and_b32_e32 v9, 0xffff0000, v6
	v_lshlrev_b32_e32 v6, 16, v7
	v_and_b32_e32 v7, 0xffff0000, v7
	v_pk_add_f32 v[2:3], v[2:3], v[8:9]
	v_pk_add_f32 v[4:5], v[4:5], v[6:7]
	s_branch .LBB0_703

; DI u32 pack2(float a, float b) { f2_t v = {a, b}; bf2_t r = __builtin_convertvector(v, bf2_t); return __builtin_bit_cast(u32, r); }
; DI float shx(float v, int k) { return __int_as_float(__builtin_amdgcn_ds_bpermute((lane_id_l() ^ k) << 2, __float_as_int(v))); }
; DI int get_tid() { int t = threadIdx.x; asm volatile("" : "+v"(t)); return t; }
; DI void resid_store8(const f32x4v (&acc)[2][2][4][2], const float* xin, float* xout, u16* xb, float* ssp, int m0, int n0, bool wr_norm = true) {
;   const int tid2 = get_tid();
;   const int wid = tid2 >> 6, lane = tid2 & 63, wr = wid >> 2, wc = wid & 3, fr = lane & 15, fq = lane >> 4;
; #pragma unroll
;   for (int bj = 0; bj < 2; ++bj)
; #pragma unroll
;     for (int n = 0; n < 2; ++n) {
;       const int row = m0 + bj * 128 + wc * 32 + n * 16 + fr;
; #pragma unroll
;       for (int ai = 0; ai < 2; ++ai) {
;         float ss = 0.f;
;         const int cb = n0 + ai * 128 + wr * 64;
; #pragma unroll
;         for (int m = 0; m < 4; ++m) {
;           const size_t off = (size_t)row * 1024 + cb + m * 16 + fq * 4;
;           f32x4 v = *(const f32x4*)(xin + off);
;           f32x4v a = acc[ai][bj][m][n];
;           v.x += a.x; v.y += a.y; v.z += a.z; v.w += a.w;
;           *(f32x4*)(xout + off) = v;
;           ss += v.x * v.x + v.y * v.y + v.z * v.z + v.w * v.w;
;           if (wr_norm) { u32x2 o2; o2.x = pack2(v.x, v.y); o2.y = pack2(v.z, v.w); *(u32x2*)(xb + off) = o2; }
;         }
;         ss += shx(ss, 16);
;         ss += shx(ss, 32);
;         if (wr_norm && fq == 0) ssp[(size_t)row * 16 + (cb >> 6)] = ss;
;       }
;     }
; }
.LBB0_835:
	s_or_b64 exec, exec, s[14:15]
	v_mbcnt_lo_u32_b32 v176, -1, 0
	v_mbcnt_hi_u32_b32 v176, -1, v176
	v_bfe_u32 v176, v176, 4, 1
	v_mul_u32_u24_e32 v176, 24, v176
	v_mov_b32_e32 v177, 0
	v_mov_b32_e32 v0, v250
	s_nop 0
	v_lshrrev_b32_e32 v131, 1, v0
	v_and_b32_e32 v130, 15, v0
	v_and_b32_e32 v131, 0x60, v131
	v_bfe_u32 v146, v0, 4, 2
	v_or3_b32 v132, v130, v131, s12
	v_ashrrev_i32_e32 v0, 2, v0
	v_and_b32_e32 v0, 0xffffffc0, v0
	v_ashrrev_i32_e32 v133, 31, v132
	v_add_u32_e32 v130, s10, v0
	v_lshlrev_b32_e32 v0, 2, v146
	v_lshlrev_b64 v[134:135], 10, v[132:133]
	v_or_b32_e32 v134, v134, v0
	v_ashrrev_i32_e32 v131, 31, v130
	v_lshl_add_u64 v[140:141], v[134:135], 0, v[130:131]
	v_readlane_b32 s10, v255, 11
	v_lshlrev_b64 v[142:143], 2, v[140:141]
	v_readlane_b32 s11, v255, 12
	v_cmp_eq_u32_e32 vcc, 0, v146
	s_nop 0
	v_lshl_add_u64 v[144:145], s[10:11], 0, v[142:143]
	global_load_dwordx4 v[136:139], v[144:145], off
	global_load_dwordx4 v[148:151], v[144:145], off offset:64
	global_load_dwordx4 v[152:155], v[144:145], off offset:128
	global_load_dwordx4 v[156:159], v[144:145], off offset:192
	s_mul_i32 s11, s6, 0x5800000
	s_mul_hi_i32 s10, s6, 0x5800000
	s_add_u32 s11, s62, s11
	s_addc_u32 s12, s63, s10
	s_add_u32 s10, s11, s25
	s_addc_u32 s11, s12, s26
	v_readlane_b32 s12, v254, 60
	v_readlane_b32 s13, v254, 61
	v_lshl_add_u64 v[140:141], v[140:141], 1, s[10:11]
	s_lshl_b64 s[6:7], s[6:7], 18
	v_lshl_add_u64 v[142:143], s[12:13], 0, v[142:143]
	s_add_u32 s8, s10, s8
	s_addc_u32 s9, s11, s9
	s_add_u32 s6, s8, s6
	s_addc_u32 s7, s9, s7
	s_waitcnt vmcnt(1)
	v_pk_add_f32 v[128:129], v[128:129], v[138:139]
	v_pk_add_f32 v[126:127], v[126:127], v[136:137]
	v_cvt_pk_bf16_f32 v161, v128, v129
	v_cvt_pk_bf16_f32 v160, v126, v127
	global_store_dwordx4 v[142:143], v[126:129], off
	s_nop 0
	s_nop 0
	v_pk_mul_f32 v[126:127], v[126:127], v[126:127]
	v_pk_mul_f32 v[128:129], v[128:129], v[128:129]
	v_add_f32_e32 v126, v126, v127
	v_add_f32_e32 v126, v128, v126
	v_add_f32_e32 v126, v129, v126
	s_waitcnt vmcnt(0)
	v_pk_add_f32 v[124:125], v[124:125], v[150:151]
	v_pk_add_f32 v[122:123], v[122:123], v[148:149]
	v_cvt_pk_bf16_f32 v163, v124, v125
	v_cvt_pk_bf16_f32 v162, v122, v123
	global_store_dwordx4 v[142:143], v[122:125], off offset:64
	v_lshl_add_u64 v[178:179], v[140:141], 0, v[176:177]
	s_nop 1
	v_permlane16_swap_b32_e32 v160, v162
	v_permlane16_swap_b32_e32 v161, v163
	global_store_dwordx4 v[178:179], v[160:163], off
	s_nop 0
	v_pk_mul_f32 v[122:123], v[122:123], v[122:123]
	v_pk_mul_f32 v[124:125], v[124:125], v[124:125]
	v_add_f32_e32 v122, v122, v123
	v_add_f32_e32 v122, v124, v122
	v_add_f32_e32 v122, v125, v122
	v_add_f32_e32 v122, v126, v122
	s_waitcnt vmcnt(0)
	v_pk_add_f32 v[120:121], v[120:121], v[154:155]
	v_pk_add_f32 v[118:119], v[118:119], v[152:153]
	v_cvt_pk_bf16_f32 v165, v120, v121
	v_cvt_pk_bf16_f32 v164, v118, v119
	global_store_dwordx4 v[142:143], v[118:121], off offset:128
	s_nop 0
	s_nop 0
	v_pk_mul_f32 v[118:119], v[118:119], v[118:119]
	v_pk_mul_f32 v[120:121], v[120:121], v[120:121]
	v_add_f32_e32 v118, v118, v119
	v_add_f32_e32 v118, v120, v118
	v_add_f32_e32 v118, v121, v118
	v_add_f32_e32 v122, v122, v118
	v_mov_b32_e32 v144, v229
	v_mov_b32_e32 v145, v229
	s_waitcnt vmcnt(0)
	v_pk_add_f32 v[114:115], v[114:115], v[156:157]
	v_pk_add_f32 v[116:117], v[116:117], v[158:159]
	v_pk_mul_f32 v[120:121], v[114:115], v[114:115]
	global_store_dwordx4 v[142:143], v[114:117], off offset:192
	v_pk_mul_f32 v[118:119], v[116:117], v[116:117]
	s_nop 0
	v_cvt_pk_bf16_f32 v166, v114, v115
	v_cvt_pk_bf16_f32 v167, v116, v117
	v_add_f32_e32 v116, v120, v121
	v_lshl_add_u64 v[178:179], v[140:141], 0, v[176:177]
	s_nop 1
	v_permlane16_swap_b32_e32 v164, v166
	v_permlane16_swap_b32_e32 v165, v167
	global_store_dwordx4 v[178:179], v[164:167], off offset:64
	v_add_f32_e32 v114, v118, v116
	v_add_f32_e32 v114, v119, v114
	v_lshlrev_b32_e32 v115, 2, v144
	v_xor_b32_e32 v115, 64, v115
	v_add_f32_e32 v114, v122, v114
	ds_bpermute_b32 v115, v115, v114
	s_waitcnt lgkmcnt(0)
	v_add_f32_e32 v116, v114, v115
	v_lshlrev_b32_e32 v117, 2, v145
	v_xor_b32_e32 v114, 0x80, v117
	ds_bpermute_b32 v117, v114, v116
	v_lshlrev_b64 v[114:115], 6, v[132:133]
	v_lshl_add_u64 v[118:119], s[6:7], 0, v[114:115]
	v_ashrrev_i32_e32 v114, 6, v130
	s_and_saveexec_b64 s[8:9], vcc
	s_cbranch_execz .LBB0_837
	v_ashrrev_i32_e32 v115, 31, v114
	v_lshl_add_u64 v[120:121], v[114:115], 2, v[118:119]
	s_waitcnt lgkmcnt(0)
	v_add_f32_e32 v115, v116, v117
	global_store_dword v[120:121], v115, off
; DI u32 pack2(float a, float b) { f2_t v = {a, b}; bf2_t r = __builtin_convertvector(v, bf2_t); return __builtin_bit_cast(u32, r); }
; DI float shx(float v, int k) { return __int_as_float(__builtin_amdgcn_ds_bpermute((lane_id_l() ^ k) << 2, __float_as_int(v))); }
; DI int get_tid() { int t = threadIdx.x; asm volatile("" : "+v"(t)); return t; }
; DI void resid_store8(const f32x4v (&acc)[2][2][4][2], const float* xin, float* xout, u16* xb, float* ssp, int m0, int n0, bool wr_norm = true) {
;   const int tid2 = get_tid();
;   const int wid = tid2 >> 6, lane = tid2 & 63, wr = wid >> 2, wc = wid & 3, fr = lane & 15, fq = lane >> 4;
; #pragma unroll
;   for (int bj = 0; bj < 2; ++bj)
; #pragma unroll
;     for (int n = 0; n < 2; ++n) {
;       const int row = m0 + bj * 128 + wc * 32 + n * 16 + fr;
; #pragma unroll
;       for (int ai = 0; ai < 2; ++ai) {
;         float ss = 0.f;
;         const int cb = n0 + ai * 128 + wr * 64;
; #pragma unroll
;         for (int m = 0; m < 4; ++m) {
;           const size_t off = (size_t)row * 1024 + cb + m * 16 + fq * 4;
;           f32x4 v = *(const f32x4*)(xin + off);
;           f32x4v a = acc[ai][bj][m][n];
;           v.x += a.x; v.y += a.y; v.z += a.z; v.w += a.w;
;           *(f32x4*)(xout + off) = v;
;           ss += v.x * v.x + v.y * v.y + v.z * v.z + v.w * v.w;
;           if (wr_norm) { u32x2 o2; o2.x = pack2(v.x, v.y); o2.y = pack2(v.z, v.w); *(u32x2*)(xb + off) = o2; }
;         }
;         ss += shx(ss, 16);
;         ss += shx(ss, 32);
;         if (wr_norm && fq == 0) ssp[(size_t)row * 16 + (cb >> 6)] = ss;
;       }
;     }
; }
.LBB0_837:
	s_or_b64 exec, exec, s[8:9]
	v_mbcnt_lo_u32_b32 v176, -1, 0
	v_mbcnt_hi_u32_b32 v176, -1, v176
	v_bfe_u32 v176, v176, 4, 1
	v_mul_u32_u24_e32 v176, 24, v176
	v_mov_b32_e32 v177, 0
	v_add_u32_e32 v116, 0x80, v130
	s_waitcnt lgkmcnt(0)
	v_ashrrev_i32_e32 v117, 31, v116
	v_lshl_add_u64 v[124:125], v[134:135], 0, v[116:117]
	v_readlane_b32 s8, v255, 11
	v_lshlrev_b64 v[126:127], 2, v[124:125]
	v_readlane_b32 s9, v255, 12
	v_lshl_add_u64 v[124:125], v[124:125], 1, s[10:11]
	v_mov_b32_e32 v115, v229
	v_lshl_add_u64 v[128:129], s[8:9], 0, v[126:127]
	global_load_dwordx4 v[120:123], v[128:129], off
	global_load_dwordx4 v[148:151], v[128:129], off offset:64
	global_load_dwordx4 v[152:155], v[128:129], off offset:128
	global_load_dwordx4 v[156:159], v[128:129], off offset:192
	v_readlane_b32 s8, v254, 60
	v_readlane_b32 s9, v254, 61
	s_waitcnt vmcnt(3)
	v_pk_add_f32 v[112:113], v[112:113], v[122:123]
	v_pk_add_f32 v[110:111], v[110:111], v[120:121]
	v_lshl_add_u64 v[126:127], s[8:9], 0, v[126:127]
	v_cvt_pk_bf16_f32 v160, v110, v111
	v_cvt_pk_bf16_f32 v161, v112, v113
	global_store_dwordx4 v[126:127], v[110:113], off
	s_nop 0
	s_nop 0
	v_pk_mul_f32 v[110:111], v[110:111], v[110:111]
	v_pk_mul_f32 v[112:113], v[112:113], v[112:113]
	v_add_f32_e32 v110, v110, v111
	v_add_f32_e32 v110, v112, v110
	v_add_f32_e32 v110, v113, v110
	s_waitcnt vmcnt(2)
	v_pk_add_f32 v[108:109], v[108:109], v[150:151]
	v_pk_add_f32 v[106:107], v[106:107], v[148:149]
	v_cvt_pk_bf16_f32 v163, v108, v109
	v_cvt_pk_bf16_f32 v162, v106, v107
	global_store_dwordx4 v[126:127], v[106:109], off offset:64
	v_lshl_add_u64 v[178:179], v[124:125], 0, v[176:177]
	s_nop 1
	v_permlane16_swap_b32_e32 v160, v162
	v_permlane16_swap_b32_e32 v161, v163
	global_store_dwordx4 v[178:179], v[160:163], off
	s_nop 0
	v_pk_mul_f32 v[106:107], v[106:107], v[106:107]
	v_pk_mul_f32 v[108:109], v[108:109], v[108:109]
	v_add_f32_e32 v106, v106, v107
	v_add_f32_e32 v106, v108, v106
	v_add_f32_e32 v106, v109, v106
	v_add_f32_e32 v106, v110, v106
	s_waitcnt vmcnt(2)
	v_pk_add_f32 v[104:105], v[104:105], v[154:155]
	v_pk_add_f32 v[102:103], v[102:103], v[152:153]
	v_cvt_pk_bf16_f32 v165, v104, v105
	v_cvt_pk_bf16_f32 v164, v102, v103
	global_store_dwordx4 v[126:127], v[102:105], off offset:128
	s_nop 0
	s_nop 0
	v_pk_mul_f32 v[102:103], v[102:103], v[102:103]
	v_pk_mul_f32 v[104:105], v[104:105], v[104:105]
	v_add_f32_e32 v102, v102, v103
	v_add_f32_e32 v102, v104, v102
	v_add_f32_e32 v102, v105, v102
	v_add_f32_e32 v106, v106, v102
	s_waitcnt vmcnt(1)
	v_pk_add_f32 v[98:99], v[98:99], v[156:157]
	v_pk_add_f32 v[100:101], v[100:101], v[158:159]
	v_pk_mul_f32 v[104:105], v[98:99], v[98:99]
	global_store_dwordx4 v[126:127], v[98:101], off offset:192
	v_pk_mul_f32 v[102:103], v[100:101], v[100:101]
	s_nop 0
	v_cvt_pk_bf16_f32 v166, v98, v99
	v_cvt_pk_bf16_f32 v167, v100, v101
	v_add_f32_e32 v100, v104, v105
	v_lshl_add_u64 v[178:179], v[124:125], 0, v[176:177]
	s_nop 1
	v_permlane16_swap_b32_e32 v164, v166
	v_permlane16_swap_b32_e32 v165, v167
	global_store_dwordx4 v[178:179], v[164:167], off offset:64
	v_add_f32_e32 v98, v102, v100
	v_add_f32_e32 v98, v103, v98
	v_lshlrev_b32_e32 v99, 2, v115
	v_xor_b32_e32 v99, 64, v99
	v_add_f32_e32 v98, v106, v98
	ds_bpermute_b32 v99, v99, v98
	v_mov_b32_e32 v100, v229
	s_nop 0
	v_lshlrev_b32_e32 v101, 2, v100
	s_waitcnt lgkmcnt(0)
	v_add_f32_e32 v100, v98, v99
	v_xor_b32_e32 v98, 0x80, v101
	ds_bpermute_b32 v101, v98, v100
	v_ashrrev_i32_e32 v98, 6, v116
	s_and_saveexec_b64 s[8:9], vcc
	s_cbranch_execz .LBB0_839
	v_ashrrev_i32_e32 v99, 31, v98
	v_lshl_add_u64 v[102:103], v[98:99], 2, v[118:119]
	s_waitcnt lgkmcnt(0)
	v_add_f32_e32 v99, v100, v101
	global_store_dword v[102:103], v99, off
.LBB0_839:
	s_or_b64 exec, exec, s[8:9]
	v_mbcnt_lo_u32_b32 v176, -1, 0
	v_mbcnt_hi_u32_b32 v176, -1, v176
	v_bfe_u32 v176, v176, 4, 1
	v_mul_u32_u24_e32 v176, 24, v176
	v_mov_b32_e32 v177, 0
	v_or_b32_e32 v106, 16, v132
	v_ashrrev_i32_e32 v107, 31, v106
	s_waitcnt lgkmcnt(0)
	v_lshlrev_b64 v[100:101], 10, v[106:107]
	v_or_b32_e32 v100, v100, v0
	v_lshl_add_u64 v[108:109], v[100:101], 0, v[130:131]
	v_readlane_b32 s8, v255, 11
	v_lshlrev_b64 v[110:111], 2, v[108:109]
	v_readlane_b32 s9, v255, 12
	v_lshl_add_u64 v[108:109], v[108:109], 1, s[10:11]
	v_mov_b32_e32 v99, v229
	v_lshl_add_u64 v[112:113], s[8:9], 0, v[110:111]
	global_load_dwordx4 v[102:105], v[112:113], off
	global_load_dwordx4 v[148:151], v[112:113], off offset:64
	global_load_dwordx4 v[152:155], v[112:113], off offset:128
	global_load_dwordx4 v[156:159], v[112:113], off offset:192
	v_readlane_b32 s8, v254, 60
	v_readlane_b32 s9, v254, 61
	s_waitcnt vmcnt(3)
	v_pk_add_f32 v[96:97], v[96:97], v[104:105]
	v_pk_add_f32 v[94:95], v[94:95], v[102:103]
	v_lshl_add_u64 v[110:111], s[8:9], 0, v[110:111]
	v_cvt_pk_bf16_f32 v160, v94, v95
	v_cvt_pk_bf16_f32 v161, v96, v97
	global_store_dwordx4 v[110:111], v[94:97], off
	s_nop 0
	s_nop 0
	v_pk_mul_f32 v[94:95], v[94:95], v[94:95]
	v_pk_mul_f32 v[96:97], v[96:97], v[96:97]
	v_add_f32_e32 v94, v94, v95
	v_add_f32_e32 v94, v96, v94
	v_add_f32_e32 v94, v97, v94
	s_waitcnt vmcnt(2)
	v_pk_add_f32 v[92:93], v[92:93], v[150:151]
	v_pk_add_f32 v[90:91], v[90:91], v[148:149]
	v_cvt_pk_bf16_f32 v163, v92, v93
	v_cvt_pk_bf16_f32 v162, v90, v91
	global_store_dwordx4 v[110:111], v[90:93], off offset:64
	v_lshl_add_u64 v[178:179], v[108:109], 0, v[176:177]
	s_nop 1
	v_permlane16_swap_b32_e32 v160, v162
	v_permlane16_swap_b32_e32 v161, v163
	global_store_dwordx4 v[178:179], v[160:163], off
	s_nop 0
	v_pk_mul_f32 v[90:91], v[90:91], v[90:91]
	v_pk_mul_f32 v[92:93], v[92:93], v[92:93]
	v_add_f32_e32 v90, v90, v91
	v_add_f32_e32 v90, v92, v90
	v_add_f32_e32 v90, v93, v90
	v_add_f32_e32 v90, v94, v90
	s_waitcnt vmcnt(2)
; DI u32 pack2(float a, float b) { f2_t v = {a, b}; bf2_t r = __builtin_convertvector(v, bf2_t); return __builtin_bit_cast(u32, r); }
; DI float shx(float v, int k) { return __int_as_float(__builtin_amdgcn_ds_bpermute((lane_id_l() ^ k) << 2, __float_as_int(v))); }
; DI int get_tid() { int t = threadIdx.x; asm volatile("" : "+v"(t)); return t; }
; DI void resid_store8(const f32x4v (&acc)[2][2][4][2], const float* xin, float* xout, u16* xb, float* ssp, int m0, int n0, bool wr_norm = true) {
;   const int tid2 = get_tid();
;   const int wid = tid2 >> 6, lane = tid2 & 63, wr = wid >> 2, wc = wid & 3, fr = lane & 15, fq = lane >> 4;
; #pragma unroll
;   for (int bj = 0; bj < 2; ++bj)
; #pragma unroll
;     for (int n = 0; n < 2; ++n) {
;       const int row = m0 + bj * 128 + wc * 32 + n * 16 + fr;
; #pragma unroll
;       for (int ai = 0; ai < 2; ++ai) {
;         float ss = 0.f;
;         const int cb = n0 + ai * 128 + wr * 64;
; #pragma unroll
;         for (int m = 0; m < 4; ++m) {
;           const size_t off = (size_t)row * 1024 + cb + m * 16 + fq * 4;
;           f32x4 v = *(const f32x4*)(xin + off);
;           f32x4v a = acc[ai][bj][m][n];
;           v.x += a.x; v.y += a.y; v.z += a.z; v.w += a.w;
;           *(f32x4*)(xout + off) = v;
;           ss += v.x * v.x + v.y * v.y + v.z * v.z + v.w * v.w;
;           if (wr_norm) { u32x2 o2; o2.x = pack2(v.x, v.y); o2.y = pack2(v.z, v.w); *(u32x2*)(xb + off) = o2; }
;         }
;         ss += shx(ss, 16);
;         ss += shx(ss, 32);
;         if (wr_norm && fq == 0) ssp[(size_t)row * 16 + (cb >> 6)] = ss;
;       }
;     }
; }
	v_pk_add_f32 v[88:89], v[88:89], v[154:155]
	v_pk_add_f32 v[86:87], v[86:87], v[152:153]
	v_cvt_pk_bf16_f32 v165, v88, v89
	v_cvt_pk_bf16_f32 v164, v86, v87
	global_store_dwordx4 v[110:111], v[86:89], off offset:128
	s_nop 0
	s_nop 0
	v_pk_mul_f32 v[86:87], v[86:87], v[86:87]
	v_pk_mul_f32 v[88:89], v[88:89], v[88:89]
	v_add_f32_e32 v86, v86, v87
	v_add_f32_e32 v86, v88, v86
	v_add_f32_e32 v86, v89, v86
	v_add_f32_e32 v90, v90, v86
	s_waitcnt vmcnt(1)
	v_pk_add_f32 v[82:83], v[82:83], v[156:157]
	v_pk_add_f32 v[84:85], v[84:85], v[158:159]
	v_pk_mul_f32 v[88:89], v[82:83], v[82:83]
	global_store_dwordx4 v[110:111], v[82:85], off offset:192
	v_pk_mul_f32 v[86:87], v[84:85], v[84:85]
	s_nop 0
	v_cvt_pk_bf16_f32 v166, v82, v83
	v_cvt_pk_bf16_f32 v167, v84, v85
	v_add_f32_e32 v84, v88, v89
	v_lshl_add_u64 v[178:179], v[108:109], 0, v[176:177]
	s_nop 1
	v_permlane16_swap_b32_e32 v164, v166
	v_permlane16_swap_b32_e32 v165, v167
	global_store_dwordx4 v[178:179], v[164:167], off offset:64
	v_add_f32_e32 v82, v86, v84
	v_add_f32_e32 v82, v87, v82
	v_lshlrev_b32_e32 v83, 2, v99
	v_xor_b32_e32 v83, 64, v83
	v_add_f32_e32 v82, v90, v82
	ds_bpermute_b32 v83, v83, v82
	v_mov_b32_e32 v84, v229
	s_nop 0
	v_lshlrev_b32_e32 v85, 2, v84
	s_waitcnt lgkmcnt(0)
	v_add_f32_e32 v84, v82, v83
	v_xor_b32_e32 v82, 0x80, v85
	ds_bpermute_b32 v85, v82, v84
	v_lshlrev_b64 v[82:83], 6, v[106:107]
	v_lshl_add_u64 v[82:83], s[6:7], 0, v[82:83]
	s_and_saveexec_b64 s[8:9], vcc
	s_cbranch_execz .LBB0_841
	v_ashrrev_i32_e32 v115, 31, v114
	v_lshl_add_u64 v[86:87], v[114:115], 2, v[82:83]
	s_waitcnt lgkmcnt(0)
	v_add_f32_e32 v84, v84, v85
	global_store_dword v[86:87], v84, off
.LBB0_841:
	s_or_b64 exec, exec, s[8:9]
	v_mbcnt_lo_u32_b32 v176, -1, 0
	v_mbcnt_hi_u32_b32 v176, -1, v176
	v_bfe_u32 v176, v176, 4, 1
	v_mul_u32_u24_e32 v176, 24, v176
	v_mov_b32_e32 v177, 0
	v_lshl_add_u64 v[88:89], v[100:101], 0, v[116:117]
	v_readlane_b32 s8, v255, 11
	v_lshlrev_b64 v[90:91], 2, v[88:89]
	v_readlane_b32 s9, v255, 12
	v_lshl_add_u64 v[88:89], v[88:89], 1, s[10:11]
	s_nop 0
	v_lshl_add_u64 v[92:93], s[8:9], 0, v[90:91]
	s_waitcnt lgkmcnt(0)
	global_load_dwordx4 v[84:87], v[92:93], off
	global_load_dwordx4 v[148:151], v[92:93], off offset:64
	global_load_dwordx4 v[152:155], v[92:93], off offset:128
	global_load_dwordx4 v[156:159], v[92:93], off offset:192
	v_readlane_b32 s8, v254, 60
	v_readlane_b32 s9, v254, 61
	s_waitcnt vmcnt(2)
	v_pk_add_f32 v[80:81], v[80:81], v[86:87]
	v_pk_add_f32 v[78:79], v[78:79], v[84:85]
	v_lshl_add_u64 v[90:91], s[8:9], 0, v[90:91]
	v_cvt_pk_bf16_f32 v160, v78, v79
	v_cvt_pk_bf16_f32 v161, v80, v81
	global_store_dwordx4 v[90:91], v[78:81], off
	s_nop 0
	s_nop 0
	v_pk_mul_f32 v[78:79], v[78:79], v[78:79]
	v_pk_mul_f32 v[80:81], v[80:81], v[80:81]
	v_add_f32_e32 v78, v78, v79
	v_add_f32_e32 v78, v80, v78
	v_add_f32_e32 v78, v81, v78
	s_waitcnt vmcnt(1)
	v_pk_add_f32 v[76:77], v[76:77], v[150:151]
	v_pk_add_f32 v[74:75], v[74:75], v[148:149]
	v_cvt_pk_bf16_f32 v163, v76, v77
	v_cvt_pk_bf16_f32 v162, v74, v75
	global_store_dwordx4 v[90:91], v[74:77], off offset:64
	v_lshl_add_u64 v[178:179], v[88:89], 0, v[176:177]
	s_nop 1
	v_permlane16_swap_b32_e32 v160, v162
	v_permlane16_swap_b32_e32 v161, v163
	global_store_dwordx4 v[178:179], v[160:163], off
	s_nop 0
	v_pk_mul_f32 v[74:75], v[74:75], v[74:75]
	v_pk_mul_f32 v[76:77], v[76:77], v[76:77]
	v_add_f32_e32 v74, v74, v75
	v_add_f32_e32 v74, v76, v74
	v_add_f32_e32 v74, v77, v74
	v_add_f32_e32 v74, v78, v74
	s_waitcnt vmcnt(1)
	v_pk_add_f32 v[72:73], v[72:73], v[154:155]
	v_pk_add_f32 v[70:71], v[70:71], v[152:153]
	v_cvt_pk_bf16_f32 v165, v72, v73
	v_cvt_pk_bf16_f32 v164, v70, v71
	global_store_dwordx4 v[90:91], v[70:73], off offset:128
	s_nop 0
	s_nop 0
	v_pk_mul_f32 v[70:71], v[70:71], v[70:71]
	v_pk_mul_f32 v[72:73], v[72:73], v[72:73]
	v_add_f32_e32 v70, v70, v71
	v_add_f32_e32 v70, v72, v70
	v_add_f32_e32 v70, v73, v70
	v_add_f32_e32 v74, v74, v70
	v_mov_b32_e32 v92, v229
	s_waitcnt vmcnt(0)
	v_pk_add_f32 v[66:67], v[66:67], v[156:157]
	v_pk_add_f32 v[68:69], v[68:69], v[158:159]
	v_pk_mul_f32 v[72:73], v[66:67], v[66:67]
	global_store_dwordx4 v[90:91], v[66:69], off offset:192
	v_pk_mul_f32 v[70:71], v[68:69], v[68:69]
	s_nop 0
	v_cvt_pk_bf16_f32 v166, v66, v67
	v_cvt_pk_bf16_f32 v167, v68, v69
	v_add_f32_e32 v68, v72, v73
	v_lshl_add_u64 v[178:179], v[88:89], 0, v[176:177]
	s_nop 1
	v_permlane16_swap_b32_e32 v164, v166
	v_permlane16_swap_b32_e32 v165, v167
	global_store_dwordx4 v[178:179], v[164:167], off offset:64
	v_add_f32_e32 v66, v70, v68
	v_add_f32_e32 v66, v71, v66
	v_lshlrev_b32_e32 v67, 2, v92
	v_xor_b32_e32 v67, 64, v67
	v_add_f32_e32 v66, v74, v66
	ds_bpermute_b32 v67, v67, v66
	v_mov_b32_e32 v68, v229
	s_waitcnt lgkmcnt(0)
	v_add_f32_e32 v66, v66, v67
	v_lshlrev_b32_e32 v68, 2, v68
	v_xor_b32_e32 v67, 0x80, v68
	ds_bpermute_b32 v67, v67, v66
	s_and_saveexec_b64 s[8:9], vcc
	s_cbranch_execz .LBB0_843
	v_ashrrev_i32_e32 v99, 31, v98
	v_lshl_add_u64 v[68:69], v[98:99], 2, v[82:83]
	s_waitcnt lgkmcnt(0)
	v_add_f32_e32 v66, v66, v67
	global_store_dword v[68:69], v66, off
; DI u32 pack2(float a, float b) { f2_t v = {a, b}; bf2_t r = __builtin_convertvector(v, bf2_t); return __builtin_bit_cast(u32, r); }
; DI float shx(float v, int k) { return __int_as_float(__builtin_amdgcn_ds_bpermute((lane_id_l() ^ k) << 2, __float_as_int(v))); }
; DI int get_tid() { int t = threadIdx.x; asm volatile("" : "+v"(t)); return t; }
; DI void resid_store8(const f32x4v (&acc)[2][2][4][2], const float* xin, float* xout, u16* xb, float* ssp, int m0, int n0, bool wr_norm = true) {
;   const int tid2 = get_tid();
;   const int wid = tid2 >> 6, lane = tid2 & 63, wr = wid >> 2, wc = wid & 3, fr = lane & 15, fq = lane >> 4;
; #pragma unroll
;   for (int bj = 0; bj < 2; ++bj)
; #pragma unroll
;     for (int n = 0; n < 2; ++n) {
;       const int row = m0 + bj * 128 + wc * 32 + n * 16 + fr;
; #pragma unroll
;       for (int ai = 0; ai < 2; ++ai) {
;         float ss = 0.f;
;         const int cb = n0 + ai * 128 + wr * 64;
; #pragma unroll
;         for (int m = 0; m < 4; ++m) {
;           const size_t off = (size_t)row * 1024 + cb + m * 16 + fq * 4;
;           f32x4 v = *(const f32x4*)(xin + off);
;           f32x4v a = acc[ai][bj][m][n];
;           v.x += a.x; v.y += a.y; v.z += a.z; v.w += a.w;
;           *(f32x4*)(xout + off) = v;
;           ss += v.x * v.x + v.y * v.y + v.z * v.z + v.w * v.w;
;           if (wr_norm) { u32x2 o2; o2.x = pack2(v.x, v.y); o2.y = pack2(v.z, v.w); *(u32x2*)(xb + off) = o2; }
;         }
;         ss += shx(ss, 16);
;         ss += shx(ss, 32);
;         if (wr_norm && fq == 0) ssp[(size_t)row * 16 + (cb >> 6)] = ss;
;       }
;     }
; }
.LBB0_843:
	s_or_b64 exec, exec, s[8:9]
	v_mbcnt_lo_u32_b32 v176, -1, 0
	v_mbcnt_hi_u32_b32 v176, -1, v176
	v_bfe_u32 v176, v176, 4, 1
	v_mul_u32_u24_e32 v176, 24, v176
	v_mov_b32_e32 v177, 0
	v_or_b32_e32 v72, 0x80, v132
	v_ashrrev_i32_e32 v73, 31, v72
	s_waitcnt lgkmcnt(0)
	v_lshlrev_b64 v[66:67], 10, v[72:73]
	v_or_b32_e32 v66, v66, v0
	v_lshl_add_u64 v[74:75], v[66:67], 0, v[130:131]
	v_readlane_b32 s8, v255, 11
	v_lshlrev_b64 v[76:77], 2, v[74:75]
	v_readlane_b32 s9, v255, 12
	v_lshl_add_u64 v[74:75], v[74:75], 1, s[10:11]
	s_nop 0
	v_lshl_add_u64 v[78:79], s[8:9], 0, v[76:77]
	global_load_dwordx4 v[68:71], v[78:79], off
	global_load_dwordx4 v[148:151], v[78:79], off offset:64
	global_load_dwordx4 v[152:155], v[78:79], off offset:128
	global_load_dwordx4 v[156:159], v[78:79], off offset:192
	v_readlane_b32 s8, v254, 60
	v_readlane_b32 s9, v254, 61
	s_waitcnt vmcnt(2)
	v_pk_add_f32 v[64:65], v[64:65], v[70:71]
	v_pk_add_f32 v[62:63], v[62:63], v[68:69]
	v_lshl_add_u64 v[76:77], s[8:9], 0, v[76:77]
	v_cvt_pk_bf16_f32 v160, v62, v63
	v_cvt_pk_bf16_f32 v161, v64, v65
	global_store_dwordx4 v[76:77], v[62:65], off
	s_nop 0
	s_nop 0
	v_pk_mul_f32 v[62:63], v[62:63], v[62:63]
	v_pk_mul_f32 v[64:65], v[64:65], v[64:65]
	v_add_f32_e32 v62, v62, v63
	v_add_f32_e32 v62, v64, v62
	v_add_f32_e32 v62, v65, v62
	s_waitcnt vmcnt(1)
	v_pk_add_f32 v[60:61], v[60:61], v[150:151]
	v_pk_add_f32 v[58:59], v[58:59], v[148:149]
	v_cvt_pk_bf16_f32 v163, v60, v61
	v_cvt_pk_bf16_f32 v162, v58, v59
	global_store_dwordx4 v[76:77], v[58:61], off offset:64
	v_lshl_add_u64 v[178:179], v[74:75], 0, v[176:177]
	s_nop 1
	v_permlane16_swap_b32_e32 v160, v162
	v_permlane16_swap_b32_e32 v161, v163
	global_store_dwordx4 v[178:179], v[160:163], off
	s_nop 0
	v_pk_mul_f32 v[58:59], v[58:59], v[58:59]
	v_pk_mul_f32 v[60:61], v[60:61], v[60:61]
	v_add_f32_e32 v58, v58, v59
	v_add_f32_e32 v58, v60, v58
	v_add_f32_e32 v58, v61, v58
	v_add_f32_e32 v58, v62, v58
	s_waitcnt vmcnt(1)
	v_pk_add_f32 v[56:57], v[56:57], v[154:155]
	v_pk_add_f32 v[54:55], v[54:55], v[152:153]
	v_cvt_pk_bf16_f32 v165, v56, v57
	v_cvt_pk_bf16_f32 v164, v54, v55
	global_store_dwordx4 v[76:77], v[54:57], off offset:128
	s_nop 0
	s_nop 0
	v_pk_mul_f32 v[54:55], v[54:55], v[54:55]
	v_pk_mul_f32 v[56:57], v[56:57], v[56:57]
	v_add_f32_e32 v54, v54, v55
	v_add_f32_e32 v54, v56, v54
	v_add_f32_e32 v54, v57, v54
	v_add_f32_e32 v58, v58, v54
	v_mov_b32_e32 v78, v229
	s_waitcnt vmcnt(0)
	v_pk_add_f32 v[50:51], v[50:51], v[156:157]
	v_pk_add_f32 v[52:53], v[52:53], v[158:159]
	v_pk_mul_f32 v[56:57], v[50:51], v[50:51]
	global_store_dwordx4 v[76:77], v[50:53], off offset:192
	v_pk_mul_f32 v[54:55], v[52:53], v[52:53]
	s_nop 0
	v_cvt_pk_bf16_f32 v166, v50, v51
	v_cvt_pk_bf16_f32 v167, v52, v53
	v_add_f32_e32 v52, v56, v57
	v_lshl_add_u64 v[178:179], v[74:75], 0, v[176:177]
	s_nop 1
	v_permlane16_swap_b32_e32 v164, v166
	v_permlane16_swap_b32_e32 v165, v167
	global_store_dwordx4 v[178:179], v[164:167], off offset:64
	v_add_f32_e32 v50, v54, v52
	v_add_f32_e32 v50, v55, v50
	v_lshlrev_b32_e32 v51, 2, v78
	v_xor_b32_e32 v51, 64, v51
	v_add_f32_e32 v50, v58, v50
	ds_bpermute_b32 v51, v51, v50
	v_mov_b32_e32 v52, v229
	s_nop 0
	v_lshlrev_b32_e32 v53, 2, v52
	s_waitcnt lgkmcnt(0)
	v_add_f32_e32 v52, v50, v51
	v_xor_b32_e32 v50, 0x80, v53
	ds_bpermute_b32 v53, v50, v52
	v_lshlrev_b64 v[50:51], 6, v[72:73]
	v_lshl_add_u64 v[50:51], s[6:7], 0, v[50:51]
	s_and_saveexec_b64 s[8:9], vcc
	s_cbranch_execz .LBB0_845
	v_ashrrev_i32_e32 v115, 31, v114
	v_lshl_add_u64 v[54:55], v[114:115], 2, v[50:51]
	s_waitcnt lgkmcnt(0)
	v_add_f32_e32 v52, v52, v53
	global_store_dword v[54:55], v52, off
.LBB0_845:
	s_or_b64 exec, exec, s[8:9]
	v_mbcnt_lo_u32_b32 v176, -1, 0
	v_mbcnt_hi_u32_b32 v176, -1, v176
	v_bfe_u32 v176, v176, 4, 1
	v_mul_u32_u24_e32 v176, 24, v176
	v_mov_b32_e32 v177, 0
	v_lshl_add_u64 v[56:57], v[66:67], 0, v[116:117]
	v_readlane_b32 s8, v255, 11
	v_lshlrev_b64 v[58:59], 2, v[56:57]
	v_readlane_b32 s9, v255, 12
	v_lshl_add_u64 v[56:57], v[56:57], 1, s[10:11]
	s_nop 0
	v_lshl_add_u64 v[60:61], s[8:9], 0, v[58:59]
	s_waitcnt lgkmcnt(0)
	global_load_dwordx4 v[52:55], v[60:61], off
	global_load_dwordx4 v[148:151], v[60:61], off offset:64
	global_load_dwordx4 v[152:155], v[60:61], off offset:128
	global_load_dwordx4 v[156:159], v[60:61], off offset:192
	v_readlane_b32 s8, v254, 60
	v_readlane_b32 s9, v254, 61
	s_waitcnt vmcnt(2)
	v_pk_add_f32 v[48:49], v[48:49], v[54:55]
	v_pk_add_f32 v[46:47], v[46:47], v[52:53]
	v_lshl_add_u64 v[58:59], s[8:9], 0, v[58:59]
	v_cvt_pk_bf16_f32 v160, v46, v47
	v_cvt_pk_bf16_f32 v161, v48, v49
	global_store_dwordx4 v[58:59], v[46:49], off
	s_nop 0
	s_nop 0
	v_pk_mul_f32 v[46:47], v[46:47], v[46:47]
	v_pk_mul_f32 v[48:49], v[48:49], v[48:49]
	v_add_f32_e32 v46, v46, v47
	v_add_f32_e32 v46, v48, v46
	v_add_f32_e32 v46, v49, v46
	s_waitcnt vmcnt(1)
	v_pk_add_f32 v[44:45], v[44:45], v[150:151]
	v_pk_add_f32 v[42:43], v[42:43], v[148:149]
	v_cvt_pk_bf16_f32 v163, v44, v45
	v_cvt_pk_bf16_f32 v162, v42, v43
	global_store_dwordx4 v[58:59], v[42:45], off offset:64
	v_lshl_add_u64 v[178:179], v[56:57], 0, v[176:177]
	s_nop 1
	v_permlane16_swap_b32_e32 v160, v162
	v_permlane16_swap_b32_e32 v161, v163
	global_store_dwordx4 v[178:179], v[160:163], off
	s_nop 0
	v_pk_mul_f32 v[42:43], v[42:43], v[42:43]
	v_pk_mul_f32 v[44:45], v[44:45], v[44:45]
	v_add_f32_e32 v42, v42, v43
	v_add_f32_e32 v42, v44, v42
	v_add_f32_e32 v42, v45, v42
	v_add_f32_e32 v42, v46, v42
	s_waitcnt vmcnt(1)
	v_pk_add_f32 v[40:41], v[40:41], v[154:155]
	v_pk_add_f32 v[38:39], v[38:39], v[152:153]
	v_cvt_pk_bf16_f32 v165, v40, v41
	v_cvt_pk_bf16_f32 v164, v38, v39
	global_store_dwordx4 v[58:59], v[38:41], off offset:128
	s_nop 0
	s_nop 0
	v_pk_mul_f32 v[38:39], v[38:39], v[38:39]
	v_pk_mul_f32 v[40:41], v[40:41], v[40:41]
	v_add_f32_e32 v38, v38, v39
	v_add_f32_e32 v38, v40, v38
	v_add_f32_e32 v38, v41, v38
	v_add_f32_e32 v42, v42, v38
	v_mov_b32_e32 v60, v229
	s_waitcnt vmcnt(0)
	v_pk_add_f32 v[34:35], v[34:35], v[156:157]
	v_pk_add_f32 v[36:37], v[36:37], v[158:159]
	v_pk_mul_f32 v[40:41], v[34:35], v[34:35]
	global_store_dwordx4 v[58:59], v[34:37], off offset:192
	v_pk_mul_f32 v[38:39], v[36:37], v[36:37]
	s_nop 0
	v_cvt_pk_bf16_f32 v166, v34, v35
	v_cvt_pk_bf16_f32 v167, v36, v37
	v_add_f32_e32 v36, v40, v41
	v_lshl_add_u64 v[178:179], v[56:57], 0, v[176:177]
	s_nop 1
	v_permlane16_swap_b32_e32 v164, v166
	v_permlane16_swap_b32_e32 v165, v167
	global_store_dwordx4 v[178:179], v[164:167], off offset:64
	v_add_f32_e32 v34, v38, v36
	v_add_f32_e32 v34, v39, v34
	v_lshlrev_b32_e32 v35, 2, v60
	v_xor_b32_e32 v35, 64, v35
	v_add_f32_e32 v34, v42, v34
	ds_bpermute_b32 v35, v35, v34
	v_mov_b32_e32 v36, v229
	s_waitcnt lgkmcnt(0)
	v_add_f32_e32 v34, v34, v35
	v_lshlrev_b32_e32 v36, 2, v36
	v_xor_b32_e32 v35, 0x80, v36
	ds_bpermute_b32 v35, v35, v34
	s_and_saveexec_b64 s[8:9], vcc
	s_cbranch_execz .LBB0_847
; DI u32 pack2(float a, float b) { f2_t v = {a, b}; bf2_t r = __builtin_convertvector(v, bf2_t); return __builtin_bit_cast(u32, r); }
; DI float shx(float v, int k) { return __int_as_float(__builtin_amdgcn_ds_bpermute((lane_id_l() ^ k) << 2, __float_as_int(v))); }
; DI int get_tid() { int t = threadIdx.x; asm volatile("" : "+v"(t)); return t; }
; DI void resid_store8(const f32x4v (&acc)[2][2][4][2], const float* xin, float* xout, u16* xb, float* ssp, int m0, int n0, bool wr_norm = true) {
;   const int tid2 = get_tid();
;   const int wid = tid2 >> 6, lane = tid2 & 63, wr = wid >> 2, wc = wid & 3, fr = lane & 15, fq = lane >> 4;
; #pragma unroll
;   for (int bj = 0; bj < 2; ++bj)
; #pragma unroll
;     for (int n = 0; n < 2; ++n) {
;       const int row = m0 + bj * 128 + wc * 32 + n * 16 + fr;
; #pragma unroll
;       for (int ai = 0; ai < 2; ++ai) {
;         float ss = 0.f;
;         const int cb = n0 + ai * 128 + wr * 64;
; #pragma unroll
;         for (int m = 0; m < 4; ++m) {
;           const size_t off = (size_t)row * 1024 + cb + m * 16 + fq * 4;
;           f32x4 v = *(const f32x4*)(xin + off);
;           f32x4v a = acc[ai][bj][m][n];
;           v.x += a.x; v.y += a.y; v.z += a.z; v.w += a.w;
;           *(f32x4*)(xout + off) = v;
;           ss += v.x * v.x + v.y * v.y + v.z * v.z + v.w * v.w;
;           if (wr_norm) { u32x2 o2; o2.x = pack2(v.x, v.y); o2.y = pack2(v.z, v.w); *(u32x2*)(xb + off) = o2; }
;         }
;         ss += shx(ss, 16);
;         ss += shx(ss, 32);
;         if (wr_norm && fq == 0) ssp[(size_t)row * 16 + (cb >> 6)] = ss;
;       }
;     }
; }
	v_ashrrev_i32_e32 v99, 31, v98
	v_lshl_add_u64 v[36:37], v[98:99], 2, v[50:51]
	s_waitcnt lgkmcnt(0)
	v_add_f32_e32 v34, v34, v35
	global_store_dword v[36:37], v34, off
.LBB0_847:
	s_or_b64 exec, exec, s[8:9]
	v_mbcnt_lo_u32_b32 v176, -1, 0
	v_mbcnt_hi_u32_b32 v176, -1, v176
	v_bfe_u32 v176, v176, 4, 1
	v_mul_u32_u24_e32 v176, 24, v176
	v_mov_b32_e32 v177, 0
	v_or_b32_e32 v40, 0x90, v132
	v_ashrrev_i32_e32 v41, 31, v40
	s_waitcnt lgkmcnt(0)
	v_lshlrev_b64 v[34:35], 10, v[40:41]
	v_or_b32_e32 v34, v34, v0
	v_lshl_add_u64 v[42:43], v[34:35], 0, v[130:131]
	v_readlane_b32 s8, v255, 11
	v_lshlrev_b64 v[44:45], 2, v[42:43]
	v_readlane_b32 s9, v255, 12
	v_lshl_add_u64 v[42:43], v[42:43], 1, s[10:11]
	v_mov_b32_e32 v0, v229
	v_lshl_add_u64 v[46:47], s[8:9], 0, v[44:45]
	global_load_dwordx4 v[36:39], v[46:47], off
	global_load_dwordx4 v[148:151], v[46:47], off offset:64
	global_load_dwordx4 v[152:155], v[46:47], off offset:128
	global_load_dwordx4 v[156:159], v[46:47], off offset:192
	v_readlane_b32 s8, v254, 60
	v_readlane_b32 s9, v254, 61
	s_waitcnt vmcnt(3)
	v_pk_add_f32 v[32:33], v[32:33], v[38:39]
	v_pk_add_f32 v[30:31], v[30:31], v[36:37]
	v_lshl_add_u64 v[44:45], s[8:9], 0, v[44:45]
	v_cvt_pk_bf16_f32 v160, v30, v31
	v_cvt_pk_bf16_f32 v161, v32, v33
	global_store_dwordx4 v[44:45], v[30:33], off
	s_nop 0
	s_nop 0
	v_pk_mul_f32 v[30:31], v[30:31], v[30:31]
	v_pk_mul_f32 v[32:33], v[32:33], v[32:33]
	v_add_f32_e32 v30, v30, v31
	v_add_f32_e32 v30, v32, v30
	v_add_f32_e32 v30, v33, v30
	s_waitcnt vmcnt(2)
	v_pk_add_f32 v[28:29], v[28:29], v[150:151]
	v_pk_add_f32 v[26:27], v[26:27], v[148:149]
	v_cvt_pk_bf16_f32 v163, v28, v29
	v_cvt_pk_bf16_f32 v162, v26, v27
	global_store_dwordx4 v[44:45], v[26:29], off offset:64
	v_lshl_add_u64 v[178:179], v[42:43], 0, v[176:177]
	s_nop 1
	v_permlane16_swap_b32_e32 v160, v162
	v_permlane16_swap_b32_e32 v161, v163
	global_store_dwordx4 v[178:179], v[160:163], off
	s_nop 0
	v_pk_mul_f32 v[26:27], v[26:27], v[26:27]
	v_pk_mul_f32 v[28:29], v[28:29], v[28:29]
	v_add_f32_e32 v26, v26, v27
	v_add_f32_e32 v26, v28, v26
	v_add_f32_e32 v26, v29, v26
	v_add_f32_e32 v26, v30, v26
	s_waitcnt vmcnt(2)
	v_pk_add_f32 v[24:25], v[24:25], v[154:155]
	v_pk_add_f32 v[22:23], v[22:23], v[152:153]
	v_cvt_pk_bf16_f32 v165, v24, v25
	v_cvt_pk_bf16_f32 v164, v22, v23
	global_store_dwordx4 v[44:45], v[22:25], off offset:128
	s_nop 0
	s_nop 0
	v_pk_mul_f32 v[22:23], v[22:23], v[22:23]
	v_pk_mul_f32 v[24:25], v[24:25], v[24:25]
	v_add_f32_e32 v22, v22, v23
	v_add_f32_e32 v22, v24, v22
	v_add_f32_e32 v22, v25, v22
	v_add_f32_e32 v26, v26, v22
	s_waitcnt vmcnt(1)
	v_pk_add_f32 v[18:19], v[18:19], v[156:157]
	v_pk_add_f32 v[20:21], v[20:21], v[158:159]
	v_pk_mul_f32 v[24:25], v[18:19], v[18:19]
	global_store_dwordx4 v[44:45], v[18:21], off offset:192
	v_pk_mul_f32 v[22:23], v[20:21], v[20:21]
	s_nop 0
	v_cvt_pk_bf16_f32 v166, v18, v19
	v_cvt_pk_bf16_f32 v167, v20, v21
	v_add_f32_e32 v20, v24, v25
	v_lshl_add_u64 v[178:179], v[42:43], 0, v[176:177]
	s_nop 1
	v_permlane16_swap_b32_e32 v164, v166
	v_permlane16_swap_b32_e32 v165, v167
	global_store_dwordx4 v[178:179], v[164:167], off offset:64
	v_add_f32_e32 v18, v22, v20
	v_lshlrev_b32_e32 v0, 2, v0
	v_add_f32_e32 v18, v23, v18
	v_xor_b32_e32 v0, 64, v0
	v_add_f32_e32 v18, v26, v18
	ds_bpermute_b32 v0, v0, v18
	v_mov_b32_e32 v19, v229
	s_waitcnt lgkmcnt(0)
	v_add_f32_e32 v0, v18, v0
	v_lshlrev_b32_e32 v19, 2, v19
	v_xor_b32_e32 v18, 0x80, v19
	ds_bpermute_b32 v20, v18, v0
	v_lshlrev_b64 v[18:19], 6, v[40:41]
	v_lshl_add_u64 v[18:19], s[6:7], 0, v[18:19]
	s_and_saveexec_b64 s[6:7], vcc
	s_cbranch_execz .LBB0_849
	v_ashrrev_i32_e32 v115, 31, v114
	v_lshl_add_u64 v[22:23], v[114:115], 2, v[18:19]
	s_waitcnt lgkmcnt(0)
	v_add_f32_e32 v0, v0, v20
	global_store_dword v[22:23], v0, off
; DI u32 pack2(float a, float b) { f2_t v = {a, b}; bf2_t r = __builtin_convertvector(v, bf2_t); return __builtin_bit_cast(u32, r); }
; DI float shx(float v, int k) { return __int_as_float(__builtin_amdgcn_ds_bpermute((lane_id_l() ^ k) << 2, __float_as_int(v))); }
; DI int get_tid() { int t = threadIdx.x; asm volatile("" : "+v"(t)); return t; }
; DI void resid_store8(const f32x4v (&acc)[2][2][4][2], const float* xin, float* xout, u16* xb, float* ssp, int m0, int n0, bool wr_norm = true) {
;   const int tid2 = get_tid();
;   const int wid = tid2 >> 6, lane = tid2 & 63, wr = wid >> 2, wc = wid & 3, fr = lane & 15, fq = lane >> 4;
; #pragma unroll
;   for (int bj = 0; bj < 2; ++bj)
; #pragma unroll
;     for (int n = 0; n < 2; ++n) {
;       const int row = m0 + bj * 128 + wc * 32 + n * 16 + fr;
; #pragma unroll
;       for (int ai = 0; ai < 2; ++ai) {
;         float ss = 0.f;
;         const int cb = n0 + ai * 128 + wr * 64;
; #pragma unroll
;         for (int m = 0; m < 4; ++m) {
;           const size_t off = (size_t)row * 1024 + cb + m * 16 + fq * 4;
;           f32x4 v = *(const f32x4*)(xin + off);
;           f32x4v a = acc[ai][bj][m][n];
;           v.x += a.x; v.y += a.y; v.z += a.z; v.w += a.w;
;           *(f32x4*)(xout + off) = v;
;           ss += v.x * v.x + v.y * v.y + v.z * v.z + v.w * v.w;
;           if (wr_norm) { u32x2 o2; o2.x = pack2(v.x, v.y); o2.y = pack2(v.z, v.w); *(u32x2*)(xb + off) = o2; }
;         }
;         ss += shx(ss, 16);
;         ss += shx(ss, 32);
;         if (wr_norm && fq == 0) ssp[(size_t)row * 16 + (cb >> 6)] = ss;
;       }
;     }
; }
.LBB0_849:
	s_or_b64 exec, exec, s[6:7]
	v_mbcnt_lo_u32_b32 v176, -1, 0
	v_mbcnt_hi_u32_b32 v176, -1, v176
	v_bfe_u32 v176, v176, 4, 1
	v_mul_u32_u24_e32 v176, 24, v176
	v_mov_b32_e32 v177, 0
	v_lshl_add_u64 v[24:25], v[34:35], 0, v[116:117]
	v_readlane_b32 s6, v255, 11
	v_lshlrev_b64 v[26:27], 2, v[24:25]
	v_readlane_b32 s7, v255, 12
	v_lshl_add_u64 v[24:25], v[24:25], 1, s[10:11]
	v_mov_b32_e32 v0, v229
	v_lshl_add_u64 v[28:29], s[6:7], 0, v[26:27]
	s_waitcnt lgkmcnt(0)
	global_load_dwordx4 v[20:23], v[28:29], off
	global_load_dwordx4 v[148:151], v[28:29], off offset:64
	global_load_dwordx4 v[152:155], v[28:29], off offset:128
	global_load_dwordx4 v[156:159], v[28:29], off offset:192
	v_readlane_b32 s6, v254, 60
	v_readlane_b32 s7, v254, 61
	s_waitcnt vmcnt(3)
	v_pk_add_f32 v[16:17], v[16:17], v[22:23]
	v_pk_add_f32 v[14:15], v[14:15], v[20:21]
	v_lshl_add_u64 v[26:27], s[6:7], 0, v[26:27]
	v_cvt_pk_bf16_f32 v160, v14, v15
	v_cvt_pk_bf16_f32 v161, v16, v17
	global_store_dwordx4 v[26:27], v[14:17], off
	s_nop 0
	s_nop 0
	v_pk_mul_f32 v[14:15], v[14:15], v[14:15]
	v_pk_mul_f32 v[16:17], v[16:17], v[16:17]
	v_add_f32_e32 v14, v14, v15
	v_add_f32_e32 v14, v16, v14
	v_add_f32_e32 v14, v17, v14
	s_waitcnt vmcnt(2)
	v_pk_add_f32 v[12:13], v[12:13], v[150:151]
	v_pk_add_f32 v[10:11], v[10:11], v[148:149]
	v_cvt_pk_bf16_f32 v163, v12, v13
	v_cvt_pk_bf16_f32 v162, v10, v11
	global_store_dwordx4 v[26:27], v[10:13], off offset:64
	v_lshl_add_u64 v[178:179], v[24:25], 0, v[176:177]
	s_nop 1
	v_permlane16_swap_b32_e32 v160, v162
	v_permlane16_swap_b32_e32 v161, v163
	global_store_dwordx4 v[178:179], v[160:163], off
	s_nop 0
	v_pk_mul_f32 v[10:11], v[10:11], v[10:11]
	v_pk_mul_f32 v[12:13], v[12:13], v[12:13]
	v_add_f32_e32 v10, v10, v11
	v_add_f32_e32 v10, v12, v10
	v_add_f32_e32 v10, v13, v10
	v_add_f32_e32 v10, v14, v10
	s_waitcnt vmcnt(2)
	v_pk_add_f32 v[8:9], v[8:9], v[154:155]
	v_pk_add_f32 v[6:7], v[6:7], v[152:153]
	v_cvt_pk_bf16_f32 v165, v8, v9
	v_cvt_pk_bf16_f32 v164, v6, v7
	global_store_dwordx4 v[26:27], v[6:9], off offset:128
	s_nop 0
	s_nop 0
	v_pk_mul_f32 v[6:7], v[6:7], v[6:7]
	v_pk_mul_f32 v[8:9], v[8:9], v[8:9]
	v_add_f32_e32 v6, v6, v7
	v_add_f32_e32 v6, v8, v6
	v_add_f32_e32 v6, v9, v6
	v_add_f32_e32 v10, v10, v6
	s_waitcnt vmcnt(1)
	v_pk_add_f32 v[2:3], v[2:3], v[156:157]
	v_pk_add_f32 v[4:5], v[4:5], v[158:159]
	v_pk_mul_f32 v[8:9], v[2:3], v[2:3]
	global_store_dwordx4 v[26:27], v[2:5], off offset:192
	v_pk_mul_f32 v[6:7], v[4:5], v[4:5]
	s_nop 0
	v_cvt_pk_bf16_f32 v166, v2, v3
	v_cvt_pk_bf16_f32 v167, v4, v5
	v_add_f32_e32 v4, v8, v9
	v_lshl_add_u64 v[178:179], v[24:25], 0, v[176:177]
	s_nop 1
	v_permlane16_swap_b32_e32 v164, v166
	v_permlane16_swap_b32_e32 v165, v167
	global_store_dwordx4 v[178:179], v[164:167], off offset:64
	v_add_f32_e32 v2, v6, v4
	v_lshlrev_b32_e32 v0, 2, v0
	v_add_f32_e32 v2, v7, v2
	v_xor_b32_e32 v0, 64, v0
	v_add_f32_e32 v2, v10, v2
	ds_bpermute_b32 v0, v0, v2
	v_mov_b32_e32 v3, v229
	s_waitcnt lgkmcnt(0)
	v_add_f32_e32 v0, v2, v0
	v_lshlrev_b32_e32 v3, 2, v3
	v_xor_b32_e32 v2, 0x80, v3
	ds_bpermute_b32 v2, v2, v0
	s_and_saveexec_b64 s[6:7], vcc
	s_cbranch_execz .LBB0_828
	v_ashrrev_i32_e32 v99, 31, v98
	v_lshl_add_u64 v[4:5], v[98:99], 2, v[18:19]
	s_waitcnt lgkmcnt(0)
	v_add_f32_e32 v0, v0, v2
	global_store_dword v[4:5], v0, off
	s_branch .LBB0_828

; DI u32 pack2(float a, float b) { f2_t v = {a, b}; bf2_t r = __builtin_convertvector(v, bf2_t); return __builtin_bit_cast(u32, r); }
; DI float shx(float v, int k) { return __int_as_float(__builtin_amdgcn_ds_bpermute((lane_id_l() ^ k) << 2, __float_as_int(v))); }
; DI int get_tid() { int t = threadIdx.x; asm volatile("" : "+v"(t)); return t; }
; DI void resid_store8(const f32x4v (&acc)[2][2][4][2], const float* xin, float* xout, u16* xb, float* ssp, int m0, int n0, bool wr_norm = true) {
;   const int tid2 = get_tid();
;   const int wid = tid2 >> 6, lane = tid2 & 63, wr = wid >> 2, wc = wid & 3, fr = lane & 15, fq = lane >> 4;
; #pragma unroll
;   for (int bj = 0; bj < 2; ++bj)
; #pragma unroll
;     for (int n = 0; n < 2; ++n) {
;       const int row = m0 + bj * 128 + wc * 32 + n * 16 + fr;
; #pragma unroll
;       for (int ai = 0; ai < 2; ++ai) {
;         float ss = 0.f;
;         const int cb = n0 + ai * 128 + wr * 64;
; #pragma unroll
;         for (int m = 0; m < 4; ++m) {
;           const size_t off = (size_t)row * 1024 + cb + m * 16 + fq * 4;
;           f32x4 v = *(const f32x4*)(xin + off);
;           f32x4v a = acc[ai][bj][m][n];
;           v.x += a.x; v.y += a.y; v.z += a.z; v.w += a.w;
;           *(f32x4*)(xout + off) = v;
;           ss += v.x * v.x + v.y * v.y + v.z * v.z + v.w * v.w;
;           if (wr_norm) { u32x2 o2; o2.x = pack2(v.x, v.y); o2.y = pack2(v.z, v.w); *(u32x2*)(xb + off) = o2; }
;         }
;         ss += shx(ss, 16);
;         ss += shx(ss, 32);
;         if (wr_norm && fq == 0) ssp[(size_t)row * 16 + (cb >> 6)] = ss;
;       }
;     }
; }
.LBB0_983:
	s_or_b64 exec, exec, s[12:13]
	v_mbcnt_lo_u32_b32 v176, -1, 0
	v_mbcnt_hi_u32_b32 v176, -1, v176
	v_bfe_u32 v176, v176, 4, 1
	v_mul_u32_u24_e32 v176, 24, v176
	v_mov_b32_e32 v177, 0
	v_mov_b32_e32 v0, v250
	v_mov_b32_e32 v145, v229
	v_lshrrev_b32_e32 v131, 1, v0
	v_and_b32_e32 v130, 15, v0
	v_and_b32_e32 v131, 0x60, v131
	v_bfe_u32 v144, v0, 4, 2
	v_or3_b32 v132, v130, v131, s10
	v_ashrrev_i32_e32 v0, 2, v0
	v_and_b32_e32 v0, 0xffffffc0, v0
	v_ashrrev_i32_e32 v133, 31, v132
	v_add_u32_e32 v130, s6, v0
	v_lshlrev_b32_e32 v0, 2, v144
	v_lshlrev_b64 v[134:135], 10, v[132:133]
	v_or_b32_e32 v134, v134, v0
	v_ashrrev_i32_e32 v131, 31, v130
	v_readlane_b32 s6, v254, 60
	v_lshl_add_u64 v[140:141], v[134:135], 0, v[130:131]
	v_readlane_b32 s7, v254, 61
	s_lshl_b64 s[10:11], s[8:9], 23
	v_mov_b32_e32 v146, v229
	v_lshl_add_u64 v[142:143], v[140:141], 2, s[6:7]
	global_load_dwordx4 v[136:139], v[142:143], off
	global_load_dwordx4 v[148:151], v[142:143], off offset:64
	global_load_dwordx4 v[152:155], v[142:143], off offset:128
	global_load_dwordx4 v[156:159], v[142:143], off offset:192
	s_mul_i32 s7, s8, 0xc600000
	s_mul_hi_i32 s6, s8, 0xc600000
	s_add_u32 s7, s62, s7
	s_addc_u32 s12, s63, s6
	s_add_u32 s6, s7, s53
	s_addc_u32 s7, s12, s70
	v_lshl_add_u64 v[140:141], v[140:141], 1, s[6:7]
	s_lshl_b64 s[8:9], s[8:9], 18
	s_add_u32 s10, s6, s10
	s_addc_u32 s11, s7, s11
	s_add_u32 s10, s10, s8
	s_addc_u32 s11, s11, s9
	s_add_u32 s8, s10, s8
	s_addc_u32 s9, s11, s9
	v_cmp_eq_u32_e32 vcc, 0, v144
	s_waitcnt vmcnt(3)
	v_pk_add_f32 v[128:129], v[128:129], v[138:139]
	v_pk_add_f32 v[126:127], v[126:127], v[136:137]
	v_cvt_pk_bf16_f32 v161, v128, v129
	v_cvt_pk_bf16_f32 v160, v126, v127
	global_store_dwordx4 v[142:143], v[126:129], off
	s_nop 0
	s_nop 0
	v_pk_mul_f32 v[126:127], v[126:127], v[126:127]
	v_pk_mul_f32 v[128:129], v[128:129], v[128:129]
	v_add_f32_e32 v126, v126, v127
	v_add_f32_e32 v126, v128, v126
	v_add_f32_e32 v126, v129, v126
	s_waitcnt vmcnt(2)
	v_pk_add_f32 v[124:125], v[124:125], v[150:151]
	v_pk_add_f32 v[122:123], v[122:123], v[148:149]
	v_cvt_pk_bf16_f32 v163, v124, v125
	v_cvt_pk_bf16_f32 v162, v122, v123
	global_store_dwordx4 v[142:143], v[122:125], off offset:64
	v_lshl_add_u64 v[178:179], v[140:141], 0, v[176:177]
	s_nop 1
	v_permlane16_swap_b32_e32 v160, v162
	v_permlane16_swap_b32_e32 v161, v163
	global_store_dwordx4 v[178:179], v[160:163], off
	s_nop 0
	v_pk_mul_f32 v[122:123], v[122:123], v[122:123]
	v_pk_mul_f32 v[124:125], v[124:125], v[124:125]
	v_add_f32_e32 v122, v122, v123
	v_add_f32_e32 v122, v124, v122
	v_add_f32_e32 v122, v125, v122
	v_add_f32_e32 v122, v126, v122
	s_waitcnt vmcnt(2)
	v_pk_add_f32 v[120:121], v[120:121], v[154:155]
	v_pk_add_f32 v[118:119], v[118:119], v[152:153]
	v_cvt_pk_bf16_f32 v165, v120, v121
	v_cvt_pk_bf16_f32 v164, v118, v119
	global_store_dwordx4 v[142:143], v[118:121], off offset:128
	s_nop 0
	s_nop 0
	v_pk_mul_f32 v[118:119], v[118:119], v[118:119]
	v_pk_mul_f32 v[120:121], v[120:121], v[120:121]
	v_add_f32_e32 v118, v118, v119
	v_add_f32_e32 v118, v120, v118
	v_add_f32_e32 v118, v121, v118
	v_add_f32_e32 v122, v122, v118
	s_waitcnt vmcnt(1)
	v_pk_add_f32 v[114:115], v[114:115], v[156:157]
	v_pk_add_f32 v[116:117], v[116:117], v[158:159]
	v_pk_mul_f32 v[120:121], v[114:115], v[114:115]
	global_store_dwordx4 v[142:143], v[114:117], off offset:192
	v_pk_mul_f32 v[118:119], v[116:117], v[116:117]
	s_nop 0
	v_cvt_pk_bf16_f32 v166, v114, v115
	v_cvt_pk_bf16_f32 v167, v116, v117
	v_add_f32_e32 v116, v120, v121
	v_lshl_add_u64 v[178:179], v[140:141], 0, v[176:177]
	s_nop 1
	v_permlane16_swap_b32_e32 v164, v166
	v_permlane16_swap_b32_e32 v165, v167
	global_store_dwordx4 v[178:179], v[164:167], off offset:64
	v_add_f32_e32 v114, v118, v116
	v_add_f32_e32 v114, v119, v114
	v_lshlrev_b32_e32 v115, 2, v145
	v_xor_b32_e32 v115, 64, v115
	v_add_f32_e32 v114, v122, v114
	ds_bpermute_b32 v115, v115, v114
	s_waitcnt lgkmcnt(0)
	v_add_f32_e32 v116, v114, v115
	v_lshlrev_b32_e32 v117, 2, v146
	v_xor_b32_e32 v114, 0x80, v117
	ds_bpermute_b32 v117, v114, v116
	v_lshlrev_b64 v[114:115], 6, v[132:133]
	v_lshl_add_u64 v[118:119], s[8:9], 0, v[114:115]
	v_ashrrev_i32_e32 v114, 6, v130
	s_and_saveexec_b64 s[10:11], vcc
	s_cbranch_execz .LBB0_985
	v_ashrrev_i32_e32 v115, 31, v114
	v_lshl_add_u64 v[120:121], v[114:115], 2, v[118:119]
	s_waitcnt lgkmcnt(0)
	v_add_f32_e32 v115, v116, v117
	global_store_dword v[120:121], v115, off
; DI u32 pack2(float a, float b) { f2_t v = {a, b}; bf2_t r = __builtin_convertvector(v, bf2_t); return __builtin_bit_cast(u32, r); }
; DI float shx(float v, int k) { return __int_as_float(__builtin_amdgcn_ds_bpermute((lane_id_l() ^ k) << 2, __float_as_int(v))); }
; DI int get_tid() { int t = threadIdx.x; asm volatile("" : "+v"(t)); return t; }
; DI void resid_store8(const f32x4v (&acc)[2][2][4][2], const float* xin, float* xout, u16* xb, float* ssp, int m0, int n0, bool wr_norm = true) {
;   const int tid2 = get_tid();
;   const int wid = tid2 >> 6, lane = tid2 & 63, wr = wid >> 2, wc = wid & 3, fr = lane & 15, fq = lane >> 4;
; #pragma unroll
;   for (int bj = 0; bj < 2; ++bj)
; #pragma unroll
;     for (int n = 0; n < 2; ++n) {
;       const int row = m0 + bj * 128 + wc * 32 + n * 16 + fr;
; #pragma unroll
;       for (int ai = 0; ai < 2; ++ai) {
;         float ss = 0.f;
;         const int cb = n0 + ai * 128 + wr * 64;
; #pragma unroll
;         for (int m = 0; m < 4; ++m) {
;           const size_t off = (size_t)row * 1024 + cb + m * 16 + fq * 4;
;           f32x4 v = *(const f32x4*)(xin + off);
;           f32x4v a = acc[ai][bj][m][n];
;           v.x += a.x; v.y += a.y; v.z += a.z; v.w += a.w;
;           *(f32x4*)(xout + off) = v;
;           ss += v.x * v.x + v.y * v.y + v.z * v.z + v.w * v.w;
;           if (wr_norm) { u32x2 o2; o2.x = pack2(v.x, v.y); o2.y = pack2(v.z, v.w); *(u32x2*)(xb + off) = o2; }
;         }
;         ss += shx(ss, 16);
;         ss += shx(ss, 32);
;         if (wr_norm && fq == 0) ssp[(size_t)row * 16 + (cb >> 6)] = ss;
;       }
;     }
; }
.LBB0_985:
	s_or_b64 exec, exec, s[10:11]
	v_mbcnt_lo_u32_b32 v176, -1, 0
	v_mbcnt_hi_u32_b32 v176, -1, v176
	v_bfe_u32 v176, v176, 4, 1
	v_mul_u32_u24_e32 v176, 24, v176
	v_mov_b32_e32 v177, 0
	v_add_u32_e32 v116, 0x80, v130
	s_waitcnt lgkmcnt(0)
	v_ashrrev_i32_e32 v117, 31, v116
	v_readlane_b32 s10, v254, 60
	v_lshl_add_u64 v[124:125], v[134:135], 0, v[116:117]
	v_readlane_b32 s11, v254, 61
	s_nop 1
	v_lshl_add_u64 v[126:127], v[124:125], 2, s[10:11]
	global_load_dwordx4 v[120:123], v[126:127], off
	global_load_dwordx4 v[148:151], v[126:127], off offset:64
	global_load_dwordx4 v[152:155], v[126:127], off offset:128
	global_load_dwordx4 v[156:159], v[126:127], off offset:192
	v_lshl_add_u64 v[124:125], v[124:125], 1, s[6:7]
	s_waitcnt vmcnt(3)
	v_pk_add_f32 v[112:113], v[112:113], v[122:123]
	v_pk_add_f32 v[110:111], v[110:111], v[120:121]
	global_store_dwordx4 v[126:127], v[110:113], off
	v_pk_mul_f32 v[122:123], v[110:111], v[110:111]
	v_pk_mul_f32 v[120:121], v[112:113], v[112:113]
	v_cvt_pk_bf16_f32 v160, v110, v111
	v_cvt_pk_bf16_f32 v161, v112, v113
	s_nop 0
	s_nop 0
	v_add_f32_e32 v115, v122, v123
	v_add_f32_e32 v115, v120, v115
	v_add_f32_e32 v115, v121, v115
	s_waitcnt vmcnt(2)
	v_pk_add_f32 v[108:109], v[108:109], v[150:151]
	v_pk_add_f32 v[106:107], v[106:107], v[148:149]
	global_store_dwordx4 v[126:127], v[106:109], off offset:64
	v_pk_mul_f32 v[112:113], v[106:107], v[106:107]
	v_pk_mul_f32 v[110:111], v[108:109], v[108:109]
	v_cvt_pk_bf16_f32 v162, v106, v107
	v_cvt_pk_bf16_f32 v163, v108, v109
	v_lshl_add_u64 v[178:179], v[124:125], 0, v[176:177]
	s_nop 1
	v_permlane16_swap_b32_e32 v160, v162
	v_permlane16_swap_b32_e32 v161, v163
	global_store_dwordx4 v[178:179], v[160:163], off
	s_nop 0
	v_add_f32_e32 v112, v112, v113
	v_add_f32_e32 v110, v110, v112
	v_add_f32_e32 v110, v111, v110
	v_add_f32_e32 v110, v115, v110
	s_waitcnt vmcnt(2)
	v_pk_add_f32 v[104:105], v[104:105], v[154:155]
	v_pk_add_f32 v[102:103], v[102:103], v[152:153]
	global_store_dwordx4 v[126:127], v[102:105], off offset:128
	v_pk_mul_f32 v[108:109], v[102:103], v[102:103]
	v_pk_mul_f32 v[106:107], v[104:105], v[104:105]
	v_cvt_pk_bf16_f32 v164, v102, v103
	v_cvt_pk_bf16_f32 v165, v104, v105
	s_nop 0
	s_nop 0
	v_add_f32_e32 v108, v108, v109
	v_add_f32_e32 v106, v106, v108
	v_add_f32_e32 v106, v107, v106
	v_add_f32_e32 v106, v110, v106
	s_waitcnt vmcnt(1)
	v_pk_add_f32 v[100:101], v[100:101], v[158:159]
	v_pk_add_f32 v[98:99], v[98:99], v[156:157]
	global_store_dwordx4 v[126:127], v[98:101], off offset:192
	v_pk_mul_f32 v[104:105], v[98:99], v[98:99]
	v_pk_mul_f32 v[102:103], v[100:101], v[100:101]
	v_cvt_pk_bf16_f32 v166, v98, v99
	v_cvt_pk_bf16_f32 v167, v100, v101
	v_add_f32_e32 v104, v104, v105
	v_lshl_add_u64 v[178:179], v[124:125], 0, v[176:177]
	s_nop 1
	v_permlane16_swap_b32_e32 v164, v166
	v_permlane16_swap_b32_e32 v165, v167
	global_store_dwordx4 v[178:179], v[164:167], off offset:64
	v_mov_b32_e32 v98, v229
	v_add_f32_e32 v102, v102, v104
	v_add_f32_e32 v102, v103, v102
	v_lshlrev_b32_e32 v98, 2, v98
	v_add_f32_e32 v102, v106, v102
	v_xor_b32_e32 v98, 64, v98
	ds_bpermute_b32 v98, v98, v102
	s_waitcnt lgkmcnt(0)
	v_add_f32_e32 v100, v102, v98
	v_mov_b32_e32 v98, v229
	s_nop 0
	v_lshlrev_b32_e32 v98, 2, v98
	v_xor_b32_e32 v98, 0x80, v98
	ds_bpermute_b32 v101, v98, v100
	v_ashrrev_i32_e32 v98, 6, v116
	s_and_saveexec_b64 s[10:11], vcc
	s_cbranch_execz .LBB0_987
	v_ashrrev_i32_e32 v99, 31, v98
	v_lshl_add_u64 v[102:103], v[98:99], 2, v[118:119]
	s_waitcnt lgkmcnt(0)
	v_add_f32_e32 v99, v100, v101
	global_store_dword v[102:103], v99, off
.LBB0_987:
	s_or_b64 exec, exec, s[10:11]
	v_mbcnt_lo_u32_b32 v176, -1, 0
	v_mbcnt_hi_u32_b32 v176, -1, v176
	v_bfe_u32 v176, v176, 4, 1
	v_mul_u32_u24_e32 v176, 24, v176
	v_mov_b32_e32 v177, 0
	v_or_b32_e32 v100, 16, v132
	s_waitcnt lgkmcnt(0)
	v_ashrrev_i32_e32 v101, 31, v100
	v_lshlrev_b64 v[102:103], 10, v[100:101]
	v_or_b32_e32 v102, v102, v0
	v_readlane_b32 s10, v254, 60
	v_lshl_add_u64 v[108:109], v[102:103], 0, v[130:131]
	v_readlane_b32 s11, v254, 61
	v_lshlrev_b64 v[100:101], 6, v[100:101]
	v_lshl_add_u64 v[100:101], s[8:9], 0, v[100:101]
	v_lshl_add_u64 v[110:111], v[108:109], 2, s[10:11]
	global_load_dwordx4 v[104:107], v[110:111], off
	global_load_dwordx4 v[148:151], v[110:111], off offset:64
	global_load_dwordx4 v[152:155], v[110:111], off offset:128
	global_load_dwordx4 v[156:159], v[110:111], off offset:192
	v_lshl_add_u64 v[108:109], v[108:109], 1, s[6:7]
	s_waitcnt vmcnt(3)
	v_pk_add_f32 v[96:97], v[96:97], v[106:107]
	v_pk_add_f32 v[94:95], v[94:95], v[104:105]
	global_store_dwordx4 v[110:111], v[94:97], off
	v_pk_mul_f32 v[106:107], v[94:95], v[94:95]
	v_pk_mul_f32 v[104:105], v[96:97], v[96:97]
	v_cvt_pk_bf16_f32 v160, v94, v95
	v_cvt_pk_bf16_f32 v161, v96, v97
	s_nop 0
	s_nop 0
	v_add_f32_e32 v99, v106, v107
	v_add_f32_e32 v99, v104, v99
	v_add_f32_e32 v99, v105, v99
	s_waitcnt vmcnt(2)
	v_pk_add_f32 v[92:93], v[92:93], v[150:151]
	v_pk_add_f32 v[90:91], v[90:91], v[148:149]
	global_store_dwordx4 v[110:111], v[90:93], off offset:64
	v_pk_mul_f32 v[96:97], v[90:91], v[90:91]
	v_pk_mul_f32 v[94:95], v[92:93], v[92:93]
	v_cvt_pk_bf16_f32 v162, v90, v91
	v_cvt_pk_bf16_f32 v163, v92, v93
	v_lshl_add_u64 v[178:179], v[108:109], 0, v[176:177]
	s_nop 1
	v_permlane16_swap_b32_e32 v160, v162
	v_permlane16_swap_b32_e32 v161, v163
	global_store_dwordx4 v[178:179], v[160:163], off
	s_nop 0
	v_add_f32_e32 v96, v96, v97
	v_add_f32_e32 v94, v94, v96
	v_add_f32_e32 v94, v95, v94
	v_add_f32_e32 v94, v99, v94
	s_waitcnt vmcnt(2)
	v_pk_add_f32 v[88:89], v[88:89], v[154:155]
	v_pk_add_f32 v[86:87], v[86:87], v[152:153]
	global_store_dwordx4 v[110:111], v[86:89], off offset:128
	v_pk_mul_f32 v[92:93], v[86:87], v[86:87]
	v_pk_mul_f32 v[90:91], v[88:89], v[88:89]
	v_cvt_pk_bf16_f32 v164, v86, v87
	v_cvt_pk_bf16_f32 v165, v88, v89
	s_nop 0
	s_nop 0
	v_add_f32_e32 v92, v92, v93
	v_add_f32_e32 v90, v90, v92
	v_add_f32_e32 v90, v91, v90
	v_add_f32_e32 v90, v94, v90
	s_waitcnt vmcnt(1)
	v_pk_add_f32 v[84:85], v[84:85], v[158:159]
	v_pk_add_f32 v[82:83], v[82:83], v[156:157]
	global_store_dwordx4 v[110:111], v[82:85], off offset:192
	v_pk_mul_f32 v[88:89], v[82:83], v[82:83]
	v_pk_mul_f32 v[86:87], v[84:85], v[84:85]
	v_cvt_pk_bf16_f32 v166, v82, v83
	v_cvt_pk_bf16_f32 v167, v84, v85
	v_add_f32_e32 v88, v88, v89
	v_lshl_add_u64 v[178:179], v[108:109], 0, v[176:177]
	s_nop 1
	v_permlane16_swap_b32_e32 v164, v166
	v_permlane16_swap_b32_e32 v165, v167
	global_store_dwordx4 v[178:179], v[164:167], off offset:64
	v_mov_b32_e32 v82, v229
	v_add_f32_e32 v86, v86, v88
	v_add_f32_e32 v86, v87, v86
	v_lshlrev_b32_e32 v82, 2, v82
	v_add_f32_e32 v86, v90, v86
	v_xor_b32_e32 v82, 64, v82
	ds_bpermute_b32 v82, v82, v86
	v_mov_b32_e32 v83, v229
	s_waitcnt lgkmcnt(0)
	v_add_f32_e32 v82, v86, v82
	v_lshlrev_b32_e32 v83, 2, v83
	v_xor_b32_e32 v83, 0x80, v83
	ds_bpermute_b32 v83, v83, v82
	s_and_saveexec_b64 s[10:11], vcc
	s_cbranch_execz .LBB0_989
; DI u32 pack2(float a, float b) { f2_t v = {a, b}; bf2_t r = __builtin_convertvector(v, bf2_t); return __builtin_bit_cast(u32, r); }
; DI float shx(float v, int k) { return __int_as_float(__builtin_amdgcn_ds_bpermute((lane_id_l() ^ k) << 2, __float_as_int(v))); }
; DI int get_tid() { int t = threadIdx.x; asm volatile("" : "+v"(t)); return t; }
; DI void resid_store8(const f32x4v (&acc)[2][2][4][2], const float* xin, float* xout, u16* xb, float* ssp, int m0, int n0, bool wr_norm = true) {
;   const int tid2 = get_tid();
;   const int wid = tid2 >> 6, lane = tid2 & 63, wr = wid >> 2, wc = wid & 3, fr = lane & 15, fq = lane >> 4;
; #pragma unroll
;   for (int bj = 0; bj < 2; ++bj)
; #pragma unroll
;     for (int n = 0; n < 2; ++n) {
;       const int row = m0 + bj * 128 + wc * 32 + n * 16 + fr;
; #pragma unroll
;       for (int ai = 0; ai < 2; ++ai) {
;         float ss = 0.f;
;         const int cb = n0 + ai * 128 + wr * 64;
; #pragma unroll
;         for (int m = 0; m < 4; ++m) {
;           const size_t off = (size_t)row * 1024 + cb + m * 16 + fq * 4;
;           f32x4 v = *(const f32x4*)(xin + off);
;           f32x4v a = acc[ai][bj][m][n];
;           v.x += a.x; v.y += a.y; v.z += a.z; v.w += a.w;
;           *(f32x4*)(xout + off) = v;
;           ss += v.x * v.x + v.y * v.y + v.z * v.z + v.w * v.w;
;           if (wr_norm) { u32x2 o2; o2.x = pack2(v.x, v.y); o2.y = pack2(v.z, v.w); *(u32x2*)(xb + off) = o2; }
;         }
;         ss += shx(ss, 16);
;         ss += shx(ss, 32);
;         if (wr_norm && fq == 0) ssp[(size_t)row * 16 + (cb >> 6)] = ss;
;       }
;     }
; }
	v_ashrrev_i32_e32 v115, 31, v114
	v_lshl_add_u64 v[84:85], v[114:115], 2, v[100:101]
	s_waitcnt lgkmcnt(0)
	v_add_f32_e32 v82, v82, v83
	global_store_dword v[84:85], v82, off
.LBB0_989:
	s_or_b64 exec, exec, s[10:11]
	v_mbcnt_lo_u32_b32 v176, -1, 0
	v_mbcnt_hi_u32_b32 v176, -1, v176
	v_bfe_u32 v176, v176, 4, 1
	v_mul_u32_u24_e32 v176, 24, v176
	v_mov_b32_e32 v177, 0
	v_readlane_b32 s10, v254, 60
	v_lshl_add_u64 v[86:87], v[102:103], 0, v[116:117]
	v_readlane_b32 s11, v254, 61
	s_nop 1
	v_lshl_add_u64 v[88:89], v[86:87], 2, s[10:11]
	s_waitcnt lgkmcnt(0)
	global_load_dwordx4 v[82:85], v[88:89], off
	global_load_dwordx4 v[148:151], v[88:89], off offset:64
	global_load_dwordx4 v[152:155], v[88:89], off offset:128
	global_load_dwordx4 v[156:159], v[88:89], off offset:192
	v_lshl_add_u64 v[86:87], v[86:87], 1, s[6:7]
	s_waitcnt vmcnt(3)
	v_pk_add_f32 v[80:81], v[80:81], v[84:85]
	v_pk_add_f32 v[78:79], v[78:79], v[82:83]
	global_store_dwordx4 v[88:89], v[78:81], off
	v_pk_mul_f32 v[84:85], v[78:79], v[78:79]
	v_pk_mul_f32 v[82:83], v[80:81], v[80:81]
	v_cvt_pk_bf16_f32 v160, v78, v79
	v_cvt_pk_bf16_f32 v161, v80, v81
	s_nop 0
	s_nop 0
	v_add_f32_e32 v84, v84, v85
	v_add_f32_e32 v82, v82, v84
	v_add_f32_e32 v82, v83, v82
	s_waitcnt vmcnt(2)
	v_pk_add_f32 v[76:77], v[76:77], v[150:151]
	v_pk_add_f32 v[74:75], v[74:75], v[148:149]
	global_store_dwordx4 v[88:89], v[74:77], off offset:64
	v_pk_mul_f32 v[80:81], v[74:75], v[74:75]
	v_pk_mul_f32 v[78:79], v[76:77], v[76:77]
	v_cvt_pk_bf16_f32 v162, v74, v75
	v_cvt_pk_bf16_f32 v163, v76, v77
	v_lshl_add_u64 v[178:179], v[86:87], 0, v[176:177]
	s_nop 1
	v_permlane16_swap_b32_e32 v160, v162
	v_permlane16_swap_b32_e32 v161, v163
	global_store_dwordx4 v[178:179], v[160:163], off
	s_nop 0
	v_add_f32_e32 v80, v80, v81
	v_add_f32_e32 v78, v78, v80
	v_add_f32_e32 v78, v79, v78
	v_add_f32_e32 v78, v82, v78
	s_waitcnt vmcnt(2)
	v_pk_add_f32 v[72:73], v[72:73], v[154:155]
	v_pk_add_f32 v[70:71], v[70:71], v[152:153]
	global_store_dwordx4 v[88:89], v[70:73], off offset:128
	v_pk_mul_f32 v[76:77], v[70:71], v[70:71]
	v_pk_mul_f32 v[74:75], v[72:73], v[72:73]
	v_cvt_pk_bf16_f32 v164, v70, v71
	v_cvt_pk_bf16_f32 v165, v72, v73
	s_nop 0
	s_nop 0
	v_add_f32_e32 v76, v76, v77
	v_add_f32_e32 v74, v74, v76
	v_add_f32_e32 v74, v75, v74
	v_add_f32_e32 v74, v78, v74
	s_waitcnt vmcnt(1)
	v_pk_add_f32 v[68:69], v[68:69], v[158:159]
	v_pk_add_f32 v[66:67], v[66:67], v[156:157]
	global_store_dwordx4 v[88:89], v[66:69], off offset:192
	v_pk_mul_f32 v[72:73], v[66:67], v[66:67]
	v_pk_mul_f32 v[70:71], v[68:69], v[68:69]
	v_cvt_pk_bf16_f32 v166, v66, v67
	v_cvt_pk_bf16_f32 v167, v68, v69
	v_add_f32_e32 v72, v72, v73
	v_lshl_add_u64 v[178:179], v[86:87], 0, v[176:177]
	s_nop 1
	v_permlane16_swap_b32_e32 v164, v166
	v_permlane16_swap_b32_e32 v165, v167
	global_store_dwordx4 v[178:179], v[164:167], off offset:64
	v_mov_b32_e32 v66, v229
	v_add_f32_e32 v70, v70, v72
	v_add_f32_e32 v70, v71, v70
	v_lshlrev_b32_e32 v66, 2, v66
	v_add_f32_e32 v70, v74, v70
	v_xor_b32_e32 v66, 64, v66
	ds_bpermute_b32 v66, v66, v70
	v_mov_b32_e32 v67, v229
	s_waitcnt lgkmcnt(0)
	v_add_f32_e32 v66, v70, v66
	v_lshlrev_b32_e32 v67, 2, v67
	v_xor_b32_e32 v67, 0x80, v67
	ds_bpermute_b32 v67, v67, v66
	s_and_saveexec_b64 s[10:11], vcc
	s_cbranch_execz .LBB0_991
	v_ashrrev_i32_e32 v99, 31, v98
	v_lshl_add_u64 v[68:69], v[98:99], 2, v[100:101]
	s_waitcnt lgkmcnt(0)
	v_add_f32_e32 v66, v66, v67
	global_store_dword v[68:69], v66, off
.LBB0_991:
	s_or_b64 exec, exec, s[10:11]
	v_mbcnt_lo_u32_b32 v176, -1, 0
	v_mbcnt_hi_u32_b32 v176, -1, v176
	v_bfe_u32 v176, v176, 4, 1
	v_mul_u32_u24_e32 v176, 24, v176
	v_mov_b32_e32 v177, 0
	v_or_b32_e32 v66, 0x80, v132
	s_waitcnt lgkmcnt(0)
	v_ashrrev_i32_e32 v67, 31, v66
	v_lshlrev_b64 v[68:69], 10, v[66:67]
	v_or_b32_e32 v68, v68, v0
	v_readlane_b32 s10, v254, 60
	v_lshl_add_u64 v[74:75], v[68:69], 0, v[130:131]
	v_readlane_b32 s11, v254, 61
	v_lshlrev_b64 v[66:67], 6, v[66:67]
	v_lshl_add_u64 v[66:67], s[8:9], 0, v[66:67]
	v_lshl_add_u64 v[76:77], v[74:75], 2, s[10:11]
	global_load_dwordx4 v[70:73], v[76:77], off
	global_load_dwordx4 v[148:151], v[76:77], off offset:64
	global_load_dwordx4 v[152:155], v[76:77], off offset:128
	global_load_dwordx4 v[156:159], v[76:77], off offset:192
	v_lshl_add_u64 v[74:75], v[74:75], 1, s[6:7]
	s_waitcnt vmcnt(3)
	v_pk_add_f32 v[64:65], v[64:65], v[72:73]
	v_pk_add_f32 v[62:63], v[62:63], v[70:71]
	global_store_dwordx4 v[76:77], v[62:65], off
	v_pk_mul_f32 v[72:73], v[62:63], v[62:63]
	v_pk_mul_f32 v[70:71], v[64:65], v[64:65]
	v_cvt_pk_bf16_f32 v160, v62, v63
	v_cvt_pk_bf16_f32 v161, v64, v65
	s_nop 0
	s_nop 0
	v_add_f32_e32 v72, v72, v73
	v_add_f32_e32 v70, v70, v72
	v_add_f32_e32 v70, v71, v70
	s_waitcnt vmcnt(2)
	v_pk_add_f32 v[60:61], v[60:61], v[150:151]
	v_pk_add_f32 v[58:59], v[58:59], v[148:149]
	global_store_dwordx4 v[76:77], v[58:61], off offset:64
	v_pk_mul_f32 v[64:65], v[58:59], v[58:59]
	v_pk_mul_f32 v[62:63], v[60:61], v[60:61]
	v_cvt_pk_bf16_f32 v162, v58, v59
	v_cvt_pk_bf16_f32 v163, v60, v61
	v_lshl_add_u64 v[178:179], v[74:75], 0, v[176:177]
	s_nop 1
	v_permlane16_swap_b32_e32 v160, v162
	v_permlane16_swap_b32_e32 v161, v163
	global_store_dwordx4 v[178:179], v[160:163], off
	s_nop 0
	v_add_f32_e32 v64, v64, v65
	v_add_f32_e32 v62, v62, v64
	v_add_f32_e32 v62, v63, v62
	v_add_f32_e32 v62, v70, v62
	s_waitcnt vmcnt(2)
	v_pk_add_f32 v[56:57], v[56:57], v[154:155]
	v_pk_add_f32 v[54:55], v[54:55], v[152:153]
	global_store_dwordx4 v[76:77], v[54:57], off offset:128
	v_pk_mul_f32 v[60:61], v[54:55], v[54:55]
	v_pk_mul_f32 v[58:59], v[56:57], v[56:57]
	v_cvt_pk_bf16_f32 v164, v54, v55
	v_cvt_pk_bf16_f32 v165, v56, v57
	s_nop 0
	s_nop 0
	v_add_f32_e32 v60, v60, v61
	v_add_f32_e32 v58, v58, v60
	v_add_f32_e32 v58, v59, v58
	v_add_f32_e32 v58, v62, v58
	s_waitcnt vmcnt(1)
	v_pk_add_f32 v[52:53], v[52:53], v[158:159]
	v_pk_add_f32 v[50:51], v[50:51], v[156:157]
	global_store_dwordx4 v[76:77], v[50:53], off offset:192
	v_pk_mul_f32 v[56:57], v[50:51], v[50:51]
	v_pk_mul_f32 v[54:55], v[52:53], v[52:53]
	v_cvt_pk_bf16_f32 v166, v50, v51
	v_cvt_pk_bf16_f32 v167, v52, v53
	v_add_f32_e32 v56, v56, v57
	v_lshl_add_u64 v[178:179], v[74:75], 0, v[176:177]
	s_nop 1
	v_permlane16_swap_b32_e32 v164, v166
	v_permlane16_swap_b32_e32 v165, v167
	global_store_dwordx4 v[178:179], v[164:167], off offset:64
	v_mov_b32_e32 v50, v229
	v_add_f32_e32 v54, v54, v56
	v_add_f32_e32 v54, v55, v54
	v_lshlrev_b32_e32 v50, 2, v50
	v_add_f32_e32 v54, v58, v54
	v_xor_b32_e32 v50, 64, v50
	ds_bpermute_b32 v50, v50, v54
	v_mov_b32_e32 v51, v229
	s_waitcnt lgkmcnt(0)
	v_add_f32_e32 v50, v54, v50
	v_lshlrev_b32_e32 v51, 2, v51
	v_xor_b32_e32 v51, 0x80, v51
	ds_bpermute_b32 v51, v51, v50
	s_and_saveexec_b64 s[10:11], vcc
	s_cbranch_execz .LBB0_993
	v_ashrrev_i32_e32 v115, 31, v114
	v_lshl_add_u64 v[52:53], v[114:115], 2, v[66:67]
	s_waitcnt lgkmcnt(0)
	v_add_f32_e32 v50, v50, v51
	global_store_dword v[52:53], v50, off
; DI u32 pack2(float a, float b) { f2_t v = {a, b}; bf2_t r = __builtin_convertvector(v, bf2_t); return __builtin_bit_cast(u32, r); }
; DI float shx(float v, int k) { return __int_as_float(__builtin_amdgcn_ds_bpermute((lane_id_l() ^ k) << 2, __float_as_int(v))); }
; DI int get_tid() { int t = threadIdx.x; asm volatile("" : "+v"(t)); return t; }
; DI void resid_store8(const f32x4v (&acc)[2][2][4][2], const float* xin, float* xout, u16* xb, float* ssp, int m0, int n0, bool wr_norm = true) {
;   const int tid2 = get_tid();
;   const int wid = tid2 >> 6, lane = tid2 & 63, wr = wid >> 2, wc = wid & 3, fr = lane & 15, fq = lane >> 4;
; #pragma unroll
;   for (int bj = 0; bj < 2; ++bj)
; #pragma unroll
;     for (int n = 0; n < 2; ++n) {
;       const int row = m0 + bj * 128 + wc * 32 + n * 16 + fr;
; #pragma unroll
;       for (int ai = 0; ai < 2; ++ai) {
;         float ss = 0.f;
;         const int cb = n0 + ai * 128 + wr * 64;
; #pragma unroll
;         for (int m = 0; m < 4; ++m) {
;           const size_t off = (size_t)row * 1024 + cb + m * 16 + fq * 4;
;           f32x4 v = *(const f32x4*)(xin + off);
;           f32x4v a = acc[ai][bj][m][n];
;           v.x += a.x; v.y += a.y; v.z += a.z; v.w += a.w;
;           *(f32x4*)(xout + off) = v;
;           ss += v.x * v.x + v.y * v.y + v.z * v.z + v.w * v.w;
;           if (wr_norm) { u32x2 o2; o2.x = pack2(v.x, v.y); o2.y = pack2(v.z, v.w); *(u32x2*)(xb + off) = o2; }
;         }
;         ss += shx(ss, 16);
;         ss += shx(ss, 32);
;         if (wr_norm && fq == 0) ssp[(size_t)row * 16 + (cb >> 6)] = ss;
;       }
;     }
; }
.LBB0_993:
	s_or_b64 exec, exec, s[10:11]
	v_mbcnt_lo_u32_b32 v176, -1, 0
	v_mbcnt_hi_u32_b32 v176, -1, v176
	v_bfe_u32 v176, v176, 4, 1
	v_mul_u32_u24_e32 v176, 24, v176
	v_mov_b32_e32 v177, 0
	v_readlane_b32 s10, v254, 60
	v_lshl_add_u64 v[54:55], v[68:69], 0, v[116:117]
	v_readlane_b32 s11, v254, 61
	s_nop 1
	v_lshl_add_u64 v[56:57], v[54:55], 2, s[10:11]
	s_waitcnt lgkmcnt(0)
	global_load_dwordx4 v[50:53], v[56:57], off
	global_load_dwordx4 v[148:151], v[56:57], off offset:64
	global_load_dwordx4 v[152:155], v[56:57], off offset:128
	global_load_dwordx4 v[156:159], v[56:57], off offset:192
	v_lshl_add_u64 v[54:55], v[54:55], 1, s[6:7]
	s_waitcnt vmcnt(3)
	v_pk_add_f32 v[48:49], v[48:49], v[52:53]
	v_pk_add_f32 v[46:47], v[46:47], v[50:51]
	global_store_dwordx4 v[56:57], v[46:49], off
	v_pk_mul_f32 v[52:53], v[46:47], v[46:47]
	v_pk_mul_f32 v[50:51], v[48:49], v[48:49]
	v_cvt_pk_bf16_f32 v160, v46, v47
	v_cvt_pk_bf16_f32 v161, v48, v49
	s_nop 0
	s_nop 0
	v_add_f32_e32 v52, v52, v53
	v_add_f32_e32 v50, v50, v52
	v_add_f32_e32 v50, v51, v50
	s_waitcnt vmcnt(2)
	v_pk_add_f32 v[44:45], v[44:45], v[150:151]
	v_pk_add_f32 v[42:43], v[42:43], v[148:149]
	global_store_dwordx4 v[56:57], v[42:45], off offset:64
	v_pk_mul_f32 v[48:49], v[42:43], v[42:43]
	v_pk_mul_f32 v[46:47], v[44:45], v[44:45]
	v_cvt_pk_bf16_f32 v162, v42, v43
	v_cvt_pk_bf16_f32 v163, v44, v45
	v_lshl_add_u64 v[178:179], v[54:55], 0, v[176:177]
	s_nop 1
	v_permlane16_swap_b32_e32 v160, v162
	v_permlane16_swap_b32_e32 v161, v163
	global_store_dwordx4 v[178:179], v[160:163], off
	s_nop 0
	v_add_f32_e32 v48, v48, v49
	v_add_f32_e32 v46, v46, v48
	v_add_f32_e32 v46, v47, v46
	v_add_f32_e32 v46, v50, v46
	s_waitcnt vmcnt(2)
	v_pk_add_f32 v[40:41], v[40:41], v[154:155]
	v_pk_add_f32 v[38:39], v[38:39], v[152:153]
	global_store_dwordx4 v[56:57], v[38:41], off offset:128
	v_pk_mul_f32 v[44:45], v[38:39], v[38:39]
	v_pk_mul_f32 v[42:43], v[40:41], v[40:41]
	v_cvt_pk_bf16_f32 v164, v38, v39
	v_cvt_pk_bf16_f32 v165, v40, v41
	s_nop 0
	s_nop 0
	v_add_f32_e32 v44, v44, v45
	v_add_f32_e32 v42, v42, v44
	v_add_f32_e32 v42, v43, v42
	v_add_f32_e32 v42, v46, v42
	s_waitcnt vmcnt(1)
	v_pk_add_f32 v[36:37], v[36:37], v[158:159]
	v_pk_add_f32 v[34:35], v[34:35], v[156:157]
	global_store_dwordx4 v[56:57], v[34:37], off offset:192
	v_pk_mul_f32 v[40:41], v[34:35], v[34:35]
	v_pk_mul_f32 v[38:39], v[36:37], v[36:37]
	v_cvt_pk_bf16_f32 v166, v34, v35
	v_cvt_pk_bf16_f32 v167, v36, v37
	v_add_f32_e32 v40, v40, v41
	v_lshl_add_u64 v[178:179], v[54:55], 0, v[176:177]
	s_nop 1
	v_permlane16_swap_b32_e32 v164, v166
	v_permlane16_swap_b32_e32 v165, v167
	global_store_dwordx4 v[178:179], v[164:167], off offset:64
	v_mov_b32_e32 v34, v229
	v_add_f32_e32 v38, v38, v40
	v_add_f32_e32 v38, v39, v38
	v_lshlrev_b32_e32 v34, 2, v34
	v_add_f32_e32 v38, v42, v38
	v_xor_b32_e32 v34, 64, v34
	ds_bpermute_b32 v34, v34, v38
	v_mov_b32_e32 v35, v229
	s_waitcnt lgkmcnt(0)
	v_add_f32_e32 v34, v38, v34
	v_lshlrev_b32_e32 v35, 2, v35
	v_xor_b32_e32 v35, 0x80, v35
	ds_bpermute_b32 v35, v35, v34
	s_and_saveexec_b64 s[10:11], vcc
	s_cbranch_execz .LBB0_995
	v_ashrrev_i32_e32 v99, 31, v98
	v_lshl_add_u64 v[36:37], v[98:99], 2, v[66:67]
	s_waitcnt lgkmcnt(0)
	v_add_f32_e32 v34, v34, v35
	global_store_dword v[36:37], v34, off
; DI u32 pack2(float a, float b) { f2_t v = {a, b}; bf2_t r = __builtin_convertvector(v, bf2_t); return __builtin_bit_cast(u32, r); }
; DI float shx(float v, int k) { return __int_as_float(__builtin_amdgcn_ds_bpermute((lane_id_l() ^ k) << 2, __float_as_int(v))); }
; DI int get_tid() { int t = threadIdx.x; asm volatile("" : "+v"(t)); return t; }
; DI void resid_store8(const f32x4v (&acc)[2][2][4][2], const float* xin, float* xout, u16* xb, float* ssp, int m0, int n0, bool wr_norm = true) {
;   const int tid2 = get_tid();
;   const int wid = tid2 >> 6, lane = tid2 & 63, wr = wid >> 2, wc = wid & 3, fr = lane & 15, fq = lane >> 4;
; #pragma unroll
;   for (int bj = 0; bj < 2; ++bj)
; #pragma unroll
;     for (int n = 0; n < 2; ++n) {
;       const int row = m0 + bj * 128 + wc * 32 + n * 16 + fr;
; #pragma unroll
;       for (int ai = 0; ai < 2; ++ai) {
;         float ss = 0.f;
;         const int cb = n0 + ai * 128 + wr * 64;
; #pragma unroll
;         for (int m = 0; m < 4; ++m) {
;           const size_t off = (size_t)row * 1024 + cb + m * 16 + fq * 4;
;           f32x4 v = *(const f32x4*)(xin + off);
;           f32x4v a = acc[ai][bj][m][n];
;           v.x += a.x; v.y += a.y; v.z += a.z; v.w += a.w;
;           *(f32x4*)(xout + off) = v;
;           ss += v.x * v.x + v.y * v.y + v.z * v.z + v.w * v.w;
;           if (wr_norm) { u32x2 o2; o2.x = pack2(v.x, v.y); o2.y = pack2(v.z, v.w); *(u32x2*)(xb + off) = o2; }
;         }
;         ss += shx(ss, 16);
;         ss += shx(ss, 32);
;         if (wr_norm && fq == 0) ssp[(size_t)row * 16 + (cb >> 6)] = ss;
;       }
;     }
; }
.LBB0_995:
	s_or_b64 exec, exec, s[10:11]
	v_mbcnt_lo_u32_b32 v176, -1, 0
	v_mbcnt_hi_u32_b32 v176, -1, v176
	v_bfe_u32 v176, v176, 4, 1
	v_mul_u32_u24_e32 v176, 24, v176
	v_mov_b32_e32 v177, 0
	v_or_b32_e32 v34, 0x90, v132
	s_waitcnt lgkmcnt(0)
	v_ashrrev_i32_e32 v35, 31, v34
	v_lshlrev_b64 v[36:37], 10, v[34:35]
	v_lshlrev_b64 v[34:35], 6, v[34:35]
	v_or_b32_e32 v36, v36, v0
	v_lshl_add_u64 v[34:35], s[8:9], 0, v[34:35]
	v_readlane_b32 s8, v254, 60
	v_lshl_add_u64 v[42:43], v[36:37], 0, v[130:131]
	v_readlane_b32 s9, v254, 61
	s_nop 1
	v_lshl_add_u64 v[44:45], v[42:43], 2, s[8:9]
	global_load_dwordx4 v[38:41], v[44:45], off
	global_load_dwordx4 v[148:151], v[44:45], off offset:64
	global_load_dwordx4 v[152:155], v[44:45], off offset:128
	global_load_dwordx4 v[156:159], v[44:45], off offset:192
	v_lshl_add_u64 v[42:43], v[42:43], 1, s[6:7]
	s_waitcnt vmcnt(3)
	v_pk_add_f32 v[32:33], v[32:33], v[40:41]
	v_pk_add_f32 v[30:31], v[30:31], v[38:39]
	global_store_dwordx4 v[44:45], v[30:33], off
	v_pk_mul_f32 v[40:41], v[30:31], v[30:31]
	v_pk_mul_f32 v[38:39], v[32:33], v[32:33]
	v_cvt_pk_bf16_f32 v160, v30, v31
	v_cvt_pk_bf16_f32 v161, v32, v33
	s_nop 0
	s_nop 0
	v_add_f32_e32 v0, v40, v41
	v_add_f32_e32 v0, v38, v0
	v_add_f32_e32 v0, v39, v0
	s_waitcnt vmcnt(2)
	v_pk_add_f32 v[28:29], v[28:29], v[150:151]
	v_pk_add_f32 v[26:27], v[26:27], v[148:149]
	global_store_dwordx4 v[44:45], v[26:29], off offset:64
	v_pk_mul_f32 v[32:33], v[26:27], v[26:27]
	v_pk_mul_f32 v[30:31], v[28:29], v[28:29]
	v_cvt_pk_bf16_f32 v162, v26, v27
	v_cvt_pk_bf16_f32 v163, v28, v29
	v_lshl_add_u64 v[178:179], v[42:43], 0, v[176:177]
	s_nop 1
	v_permlane16_swap_b32_e32 v160, v162
	v_permlane16_swap_b32_e32 v161, v163
	global_store_dwordx4 v[178:179], v[160:163], off
	s_nop 0
	v_add_f32_e32 v32, v32, v33
	v_add_f32_e32 v30, v30, v32
	v_add_f32_e32 v30, v31, v30
	v_add_f32_e32 v0, v0, v30
	s_waitcnt vmcnt(2)
	v_pk_add_f32 v[24:25], v[24:25], v[154:155]
	v_pk_add_f32 v[22:23], v[22:23], v[152:153]
	global_store_dwordx4 v[44:45], v[22:25], off offset:128
	v_pk_mul_f32 v[28:29], v[22:23], v[22:23]
	v_pk_mul_f32 v[26:27], v[24:25], v[24:25]
	v_cvt_pk_bf16_f32 v164, v22, v23
	v_cvt_pk_bf16_f32 v165, v24, v25
	s_nop 0
	s_nop 0
	v_add_f32_e32 v28, v28, v29
	v_add_f32_e32 v26, v26, v28
	v_add_f32_e32 v26, v27, v26
	v_add_f32_e32 v0, v0, v26
	s_waitcnt vmcnt(1)
	v_pk_add_f32 v[20:21], v[20:21], v[158:159]
	v_pk_add_f32 v[18:19], v[18:19], v[156:157]
	global_store_dwordx4 v[44:45], v[18:21], off offset:192
	v_pk_mul_f32 v[24:25], v[18:19], v[18:19]
	v_pk_mul_f32 v[22:23], v[20:21], v[20:21]
	v_cvt_pk_bf16_f32 v166, v18, v19
	v_cvt_pk_bf16_f32 v167, v20, v21
	v_add_f32_e32 v24, v24, v25
	v_lshl_add_u64 v[178:179], v[42:43], 0, v[176:177]
	s_nop 1
	v_permlane16_swap_b32_e32 v164, v166
	v_permlane16_swap_b32_e32 v165, v167
	global_store_dwordx4 v[178:179], v[164:167], off offset:64
	v_mov_b32_e32 v18, v229
	v_add_f32_e32 v22, v22, v24
	v_add_f32_e32 v22, v23, v22
	v_lshlrev_b32_e32 v18, 2, v18
	v_add_f32_e32 v0, v0, v22
	v_xor_b32_e32 v18, 64, v18
	ds_bpermute_b32 v18, v18, v0
	s_waitcnt lgkmcnt(0)
	v_add_f32_e32 v0, v0, v18
	v_mov_b32_e32 v18, v229
	s_nop 0
	v_lshlrev_b32_e32 v18, 2, v18
	v_xor_b32_e32 v18, 0x80, v18
	ds_bpermute_b32 v18, v18, v0
	s_and_saveexec_b64 s[8:9], vcc
	s_cbranch_execz .LBB0_997
	v_ashrrev_i32_e32 v115, 31, v114
	v_lshl_add_u64 v[20:21], v[114:115], 2, v[34:35]
	s_waitcnt lgkmcnt(0)
	v_add_f32_e32 v0, v0, v18
	global_store_dword v[20:21], v0, off
.LBB0_997:
	s_or_b64 exec, exec, s[8:9]
	v_mbcnt_lo_u32_b32 v176, -1, 0
	v_mbcnt_hi_u32_b32 v176, -1, v176
	v_bfe_u32 v176, v176, 4, 1
	v_mul_u32_u24_e32 v176, 24, v176
	v_mov_b32_e32 v177, 0
	v_readlane_b32 s8, v254, 60
	v_lshl_add_u64 v[22:23], v[36:37], 0, v[116:117]
	v_readlane_b32 s9, v254, 61
	s_nop 1
	v_lshl_add_u64 v[24:25], v[22:23], 2, s[8:9]
	s_waitcnt lgkmcnt(0)
	global_load_dwordx4 v[18:21], v[24:25], off
	global_load_dwordx4 v[148:151], v[24:25], off offset:64
	global_load_dwordx4 v[152:155], v[24:25], off offset:128
	global_load_dwordx4 v[156:159], v[24:25], off offset:192
	v_lshl_add_u64 v[22:23], v[22:23], 1, s[6:7]
	s_waitcnt vmcnt(3)
	v_pk_add_f32 v[16:17], v[16:17], v[20:21]
	v_pk_add_f32 v[14:15], v[14:15], v[18:19]
	global_store_dwordx4 v[24:25], v[14:17], off
	v_pk_mul_f32 v[20:21], v[14:15], v[14:15]
	v_pk_mul_f32 v[18:19], v[16:17], v[16:17]
	v_cvt_pk_bf16_f32 v160, v14, v15
	v_cvt_pk_bf16_f32 v161, v16, v17
	s_nop 0
	s_nop 0
	v_add_f32_e32 v0, v20, v21
	v_add_f32_e32 v0, v18, v0
	v_add_f32_e32 v0, v19, v0
	s_waitcnt vmcnt(2)
	v_pk_add_f32 v[12:13], v[12:13], v[150:151]
	v_pk_add_f32 v[10:11], v[10:11], v[148:149]
	global_store_dwordx4 v[24:25], v[10:13], off offset:64
	v_pk_mul_f32 v[16:17], v[10:11], v[10:11]
	v_pk_mul_f32 v[14:15], v[12:13], v[12:13]
	v_cvt_pk_bf16_f32 v162, v10, v11
	v_cvt_pk_bf16_f32 v163, v12, v13
	v_lshl_add_u64 v[178:179], v[22:23], 0, v[176:177]
	s_nop 1
	v_permlane16_swap_b32_e32 v160, v162
	v_permlane16_swap_b32_e32 v161, v163
	global_store_dwordx4 v[178:179], v[160:163], off
	s_nop 0
	v_add_f32_e32 v16, v16, v17
	v_add_f32_e32 v14, v14, v16
	v_add_f32_e32 v14, v15, v14
	v_add_f32_e32 v0, v0, v14
	s_waitcnt vmcnt(2)
	v_pk_add_f32 v[8:9], v[8:9], v[154:155]
	v_pk_add_f32 v[6:7], v[6:7], v[152:153]
	global_store_dwordx4 v[24:25], v[6:9], off offset:128
	v_pk_mul_f32 v[12:13], v[6:7], v[6:7]
	v_pk_mul_f32 v[10:11], v[8:9], v[8:9]
	v_cvt_pk_bf16_f32 v164, v6, v7
	v_cvt_pk_bf16_f32 v165, v8, v9
	s_nop 0
	s_nop 0
	v_add_f32_e32 v12, v12, v13
	v_add_f32_e32 v10, v10, v12
	v_add_f32_e32 v10, v11, v10
	v_add_f32_e32 v0, v0, v10
	s_waitcnt vmcnt(1)
	v_pk_add_f32 v[4:5], v[4:5], v[158:159]
	v_pk_add_f32 v[2:3], v[2:3], v[156:157]
	global_store_dwordx4 v[24:25], v[2:5], off offset:192
	v_pk_mul_f32 v[8:9], v[2:3], v[2:3]
	v_pk_mul_f32 v[6:7], v[4:5], v[4:5]
	v_cvt_pk_bf16_f32 v166, v2, v3
	v_cvt_pk_bf16_f32 v167, v4, v5
	v_add_f32_e32 v8, v8, v9
	v_lshl_add_u64 v[178:179], v[22:23], 0, v[176:177]
	s_nop 1
	v_permlane16_swap_b32_e32 v164, v166
	v_permlane16_swap_b32_e32 v165, v167
	global_store_dwordx4 v[178:179], v[164:167], off offset:64
	v_mov_b32_e32 v2, v229
	v_add_f32_e32 v6, v6, v8
	v_add_f32_e32 v6, v7, v6
	v_lshlrev_b32_e32 v2, 2, v2
	v_add_f32_e32 v0, v0, v6
	v_xor_b32_e32 v2, 64, v2
	ds_bpermute_b32 v2, v2, v0
	s_waitcnt lgkmcnt(0)
	v_add_f32_e32 v0, v0, v2
	v_mov_b32_e32 v2, v229
	s_nop 0
	v_lshlrev_b32_e32 v2, 2, v2
	v_xor_b32_e32 v2, 0x80, v2
	ds_bpermute_b32 v2, v2, v0
	s_and_saveexec_b64 s[6:7], vcc
	s_cbranch_execz .LBB0_976
	v_ashrrev_i32_e32 v99, 31, v98
	v_lshl_add_u64 v[4:5], v[98:99], 2, v[34:35]
	s_waitcnt lgkmcnt(0)
	v_add_f32_e32 v0, v0, v2
	global_store_dword v[4:5], v0, off
	s_branch .LBB0_976
